# speedup vs baseline: 1.0446x; 1.0054x over previous
; #define WAIT_V(n) asm volatile("s_waitcnt vmcnt(" #n ")" ::: "memory")
; #define WAIT_L(n) asm volatile("s_waitcnt lgkmcnt(" #n ")" ::: "memory")
; #define BAR __builtin_amdgcn_s_barrier()
; #define SCHED __builtin_amdgcn_sched_barrier(0)
; #define STAGE(P, BASE, br, kt) do { const char* _g = (const char*)((BASE) + (size_t)(br) * GK + (kt) * BK); \
;     __builtin_amdgcn_global_load_lds((const unsigned*)(_g + voff0), (unsigned*)((char*)(P) + tx * 16), 16, 0, 0); \
;     __builtin_amdgcn_global_load_lds((const unsigned*)(_g + voff1), (unsigned*)((char*)(P) + tx * 16 + 8192), 16, 0, 0); } while (0)
; #define LDA(dst, b, h) _Pragma("unroll") for (int m = 0; m < 4; ++m) _Pragma("unroll") for (int k = 0; k < 2; ++k) \
;     dst[m][k] = *reinterpret_cast<const bf16x8*>((char*)shm + abase + (((b) * 2 + (h)) * 16384 + (m * 2 + k) * 1024))
; #define LDB(dst, b, h) _Pragma("unroll") for (int n = 0; n < 2; ++n) _Pragma("unroll") for (int k = 0; k < 2; ++k) \
;     dst[n][k] = *reinterpret_cast<const bf16x8*>((char*)shm + bbase + (((b) * 2 + (h)) * 16384 + (n * 2 + k) * 1024))
; template <bool SWAP>
; __device__ __forceinline__ void gemm_main(const u16* __restrict__ A, const u16* __restrict__ Bt, int brow, int bcol,
;                                           u16* shm, f32x4 (&acc)[2][2][4][2]) {
;     ...
;   for (int t = 0; t < nt - 2; t += 2) {
;     LDB(B0, 0, 0); SCHED; LDA(At, 0, 0); STAGE(SA(1, 1), A, brow + HALF, t + 1);
;     WAIT_L(8); BAR; WAIT_L(0); MMA(0, 0, At, B0); BAR; SCHED;
;     LDB(B1, 0, 1); STAGE(SB(0, 0), Bt, bcol, t + 2);
;     BAR; WAIT_L(0); MMA(0, 1, At, B1); BAR;
;     LDA(At, 0, 1); STAGE(SA(0, 0), A, brow, t + 2);
;     BAR; WAIT_L(0); MMA(1, 0, At, B0); BAR; SCHED;
;     STAGE(SB(0, 1), Bt, bcol + HALF, t + 2);
;     WAIT_V(6); BAR; MMA(1, 1, At, B1); BAR;
;     LDB(B0, 1, 0); SCHED; LDA(At, 1, 0); STAGE(SA(0, 1), A, brow + HALF, t + 2);
;     WAIT_L(8); BAR; WAIT_L(0); MMA(0, 0, At, B0); BAR; SCHED;
.LBB0_84:
	ds_read_b128 v[176:179], v128 offset:1024
	ds_read_b128 v[184:187], v128 offset:3072
	ds_read_b128 v[192:195], v128 offset:5120
	ds_read_b128 v[200:203], v128 offset:7168
	v_add_u32_e32 v211, 0, v146
	v_add_u32_e32 v153, 0xc000, v211
	s_add_u32 m0, s29, 0xc000
	s_nop 0
	s_add_u32 vcc_lo, s26, s6
	s_addc_u32 vcc_hi, s27, s7
	global_load_lds_dwordx4 v134, vcc
	v_add_u32_e32 v154, 0xe000, v211
	v_lshl_add_u64 v[224:225], s[26:27], 0, v[136:137]
	s_add_u32 m0, s29, 0xe000
	s_nop 0
	global_load_lds_dwordx4 v136, vcc
	s_waitcnt lgkmcnt(8)
	s_setprio 1
	s_barrier
	s_waitcnt lgkmcnt(0)
	v_mfma_f32_16x16x32_bf16 v[124:127], v[172:175], v[156:159], v[124:127]
	v_mfma_f32_16x16x32_bf16 v[120:123], v[172:175], v[164:167], v[120:123]
	v_mfma_f32_16x16x32_bf16 v[116:119], v[180:183], v[156:159], v[116:119]
	v_mfma_f32_16x16x32_bf16 v[112:115], v[180:183], v[164:167], v[112:115]
	v_mfma_f32_16x16x32_bf16 v[108:111], v[188:191], v[156:159], v[108:111]
	v_mfma_f32_16x16x32_bf16 v[104:107], v[188:191], v[164:167], v[104:107]
	v_mfma_f32_16x16x32_bf16 v[100:103], v[196:199], v[156:159], v[100:103]
	v_mfma_f32_16x16x32_bf16 v[96:99], v[196:199], v[164:167], v[96:99]
	v_mfma_f32_16x16x32_bf16 v[124:127], v[176:179], v[160:163], v[124:127]
	v_mfma_f32_16x16x32_bf16 v[120:123], v[176:179], v[168:171], v[120:123]
	v_mfma_f32_16x16x32_bf16 v[116:119], v[184:187], v[160:163], v[116:119]
	v_mfma_f32_16x16x32_bf16 v[112:115], v[184:187], v[168:171], v[112:115]
	v_mfma_f32_16x16x32_bf16 v[108:111], v[192:195], v[160:163], v[108:111]
	v_mfma_f32_16x16x32_bf16 v[104:107], v[192:195], v[168:171], v[104:107]
	v_mfma_f32_16x16x32_bf16 v[100:103], v[200:203], v[160:163], v[100:103]
	v_mfma_f32_16x16x32_bf16 v[96:99], v[200:203], v[168:171], v[96:99]
	s_barrier
	s_setprio 0
	ds_read_b128 v[204:207], v145 offset:16384
	ds_read_b128 v[212:215], v145 offset:17408
	ds_read_b128 v[216:219], v145 offset:18432
	ds_read_b128 v[220:223], v145 offset:19456
	v_lshl_add_u64 v[226:227], s[26:27], 0, v[130:131]
	s_add_u32 m0, s29, s44
	s_nop 0
	s_add_u32 vcc_lo, s26, s8
	s_addc_u32 vcc_hi, s27, s9
	global_load_lds_dwordx4 v130, vcc
	v_lshl_add_u64 v[228:229], s[26:27], 0, v[132:133]
	s_add_u32 m0, s29, s44
	s_add_u32 m0, m0, 0x2000
	s_nop 0
	global_load_lds_dwordx4 v132, vcc
	s_setprio 1
	s_barrier
	s_waitcnt lgkmcnt(0)
	v_mfma_f32_16x16x32_bf16 v[92:95], v[172:175], v[204:207], v[92:95]
	v_mfma_f32_16x16x32_bf16 v[88:91], v[172:175], v[216:219], v[88:91]
	v_mfma_f32_16x16x32_bf16 v[84:87], v[180:183], v[204:207], v[84:87]
	v_mfma_f32_16x16x32_bf16 v[80:83], v[180:183], v[216:219], v[80:83]
	v_mfma_f32_16x16x32_bf16 v[76:79], v[188:191], v[204:207], v[76:79]
	v_mfma_f32_16x16x32_bf16 v[72:75], v[188:191], v[216:219], v[72:75]
	v_mfma_f32_16x16x32_bf16 v[68:71], v[196:199], v[204:207], v[68:71]
	v_mfma_f32_16x16x32_bf16 v[64:67], v[196:199], v[216:219], v[64:67]
	v_mfma_f32_16x16x32_bf16 v[92:95], v[176:179], v[212:215], v[92:95]
	ds_read_b128 v[172:175], v128 offset:16384
	v_mfma_f32_16x16x32_bf16 v[88:91], v[176:179], v[220:223], v[88:91]
	v_mfma_f32_16x16x32_bf16 v[84:87], v[184:187], v[212:215], v[84:87]
	ds_read_b128 v[180:183], v128 offset:18432
	v_mfma_f32_16x16x32_bf16 v[80:83], v[184:187], v[220:223], v[80:83]
	v_mfma_f32_16x16x32_bf16 v[76:79], v[192:195], v[212:215], v[76:79]
	ds_read_b128 v[188:191], v128 offset:20480
	v_mfma_f32_16x16x32_bf16 v[72:75], v[192:195], v[220:223], v[72:75]
	v_mfma_f32_16x16x32_bf16 v[68:71], v[200:203], v[212:215], v[68:71]
	ds_read_b128 v[196:199], v128 offset:22528
	v_mfma_f32_16x16x32_bf16 v[64:67], v[200:203], v[220:223], v[64:67]
	s_barrier
	s_setprio 0
	ds_read_b128 v[176:179], v128 offset:17408
	ds_read_b128 v[184:187], v128 offset:19456
	ds_read_b128 v[192:195], v128 offset:21504
	ds_read_b128 v[200:203], v128 offset:23552
	s_add_u32 m0, s29, 0x0
	s_nop 0
	s_add_u32 vcc_lo, s26, s10
	s_addc_u32 vcc_hi, s27, s11
	global_load_lds_dwordx4 v134, vcc
	s_add_u32 m0, s29, 0x2000
	s_nop 0
	global_load_lds_dwordx4 v136, vcc
	s_waitcnt vmcnt(8)
	s_setprio 1
	s_barrier
	s_waitcnt lgkmcnt(0)
	v_mfma_f32_16x16x32_bf16 v[60:63], v[172:175], v[156:159], v[60:63]
	v_mfma_f32_16x16x32_bf16 v[56:59], v[172:175], v[164:167], v[56:59]
	v_mfma_f32_16x16x32_bf16 v[52:55], v[180:183], v[156:159], v[52:55]
	v_mfma_f32_16x16x32_bf16 v[48:51], v[180:183], v[164:167], v[48:51]
	v_mfma_f32_16x16x32_bf16 v[44:47], v[188:191], v[156:159], v[44:47]
	v_mfma_f32_16x16x32_bf16 v[40:43], v[188:191], v[164:167], v[40:43]
	v_mfma_f32_16x16x32_bf16 v[36:39], v[196:199], v[156:159], v[36:39]
	v_mfma_f32_16x16x32_bf16 v[32:35], v[196:199], v[164:167], v[32:35]
	v_mfma_f32_16x16x32_bf16 v[60:63], v[176:179], v[160:163], v[60:63]
	v_mfma_f32_16x16x32_bf16 v[56:59], v[176:179], v[168:171], v[56:59]
	v_mfma_f32_16x16x32_bf16 v[52:55], v[184:187], v[160:163], v[52:55]
	v_mfma_f32_16x16x32_bf16 v[48:51], v[184:187], v[168:171], v[48:51]
	v_mfma_f32_16x16x32_bf16 v[44:47], v[192:195], v[160:163], v[44:47]
	v_mfma_f32_16x16x32_bf16 v[40:43], v[192:195], v[168:171], v[40:43]
	v_mfma_f32_16x16x32_bf16 v[36:39], v[200:203], v[160:163], v[36:39]
	v_mfma_f32_16x16x32_bf16 v[32:35], v[200:203], v[168:171], v[32:35]
	s_barrier
	s_setprio 0
	ds_read_b128 v[156:159], v145 offset:32768
	ds_read_b128 v[160:163], v145 offset:33792
	ds_read_b128 v[164:167], v145 offset:34816
	ds_read_b128 v[168:171], v145 offset:35840
	s_add_u32 m0, s29, s45
	s_nop 0
	s_add_u32 vcc_lo, s26, s12
	s_addc_u32 vcc_hi, s27, s13
	global_load_lds_dwordx4 v130, vcc
	s_add_u32 m0, s29, s45
	s_add_u32 m0, m0, 0x2000
	s_nop 0
	global_load_lds_dwordx4 v132, vcc
	s_waitcnt vmcnt(6)
	s_setprio 1
	s_barrier
; #define WAIT_V(n) asm volatile("s_waitcnt vmcnt(" #n ")" ::: "memory")
; #define WAIT_L(n) asm volatile("s_waitcnt lgkmcnt(" #n ")" ::: "memory")
; #define BAR __builtin_amdgcn_s_barrier()
; #define SCHED __builtin_amdgcn_sched_barrier(0)
; #define STAGE(P, BASE, br, kt) do { const char* _g = (const char*)((BASE) + (size_t)(br) * GK + (kt) * BK); \
;     __builtin_amdgcn_global_load_lds((const unsigned*)(_g + voff0), (unsigned*)((char*)(P) + tx * 16), 16, 0, 0); \
;     __builtin_amdgcn_global_load_lds((const unsigned*)(_g + voff1), (unsigned*)((char*)(P) + tx * 16 + 8192), 16, 0, 0); } while (0)
; #define LDA(dst, b, h) _Pragma("unroll") for (int m = 0; m < 4; ++m) _Pragma("unroll") for (int k = 0; k < 2; ++k) \
;     dst[m][k] = *reinterpret_cast<const bf16x8*>((char*)shm + abase + (((b) * 2 + (h)) * 16384 + (m * 2 + k) * 1024))
; #define LDB(dst, b, h) _Pragma("unroll") for (int n = 0; n < 2; ++n) _Pragma("unroll") for (int k = 0; k < 2; ++k) \
;     dst[n][k] = *reinterpret_cast<const bf16x8*>((char*)shm + bbase + (((b) * 2 + (h)) * 16384 + (n * 2 + k) * 1024))
; template <bool SWAP>
; __device__ __forceinline__ void gemm_main(const u16* __restrict__ A, const u16* __restrict__ Bt, int brow, int bcol,
;                                           u16* shm, f32x4 (&acc)[2][2][4][2]) {
;     ...
;     WAIT_V(6); BAR; MMA(1, 1, At, B1); BAR;
;     LDB(B0, 1, 0); SCHED; LDA(At, 1, 0); STAGE(SA(0, 1), A, brow + HALF, t + 2);
;     WAIT_L(8); BAR; WAIT_L(0); MMA(0, 0, At, B0); BAR; SCHED;
;     LDB(B1, 1, 1); STAGE(SB(1, 0), Bt, bcol, t + 3);
;     BAR; WAIT_L(0); MMA(0, 1, At, B1); BAR;
;     LDA(At, 1, 1); STAGE(SA(1, 0), A, brow, t + 3);
;     BAR; WAIT_L(0); MMA(1, 0, At, B0); BAR; SCHED;
;     STAGE(SB(1, 1), Bt, bcol + HALF, t + 3);
;     WAIT_V(6); BAR; MMA(1, 1, At, B1); BAR;
	v_mfma_f32_16x16x32_bf16 v[28:31], v[172:175], v[204:207], v[28:31]
	v_mfma_f32_16x16x32_bf16 v[24:27], v[172:175], v[216:219], v[24:27]
	v_mfma_f32_16x16x32_bf16 v[20:23], v[180:183], v[204:207], v[20:23]
	v_mfma_f32_16x16x32_bf16 v[16:19], v[180:183], v[216:219], v[16:19]
	v_mfma_f32_16x16x32_bf16 v[12:15], v[188:191], v[204:207], v[12:15]
	v_mfma_f32_16x16x32_bf16 v[8:11], v[188:191], v[216:219], v[8:11]
	v_mfma_f32_16x16x32_bf16 v[4:7], v[196:199], v[204:207], v[4:7]
	v_mfma_f32_16x16x32_bf16 v[0:3], v[196:199], v[216:219], v[0:3]
	v_mfma_f32_16x16x32_bf16 v[28:31], v[176:179], v[212:215], v[28:31]
	ds_read_b128 v[172:175], v128 offset:32768
	v_mfma_f32_16x16x32_bf16 v[24:27], v[176:179], v[220:223], v[24:27]
	v_mfma_f32_16x16x32_bf16 v[20:23], v[184:187], v[212:215], v[20:23]
	ds_read_b128 v[180:183], v128 offset:34816
	v_mfma_f32_16x16x32_bf16 v[16:19], v[184:187], v[220:223], v[16:19]
	v_mfma_f32_16x16x32_bf16 v[12:15], v[192:195], v[212:215], v[12:15]
	ds_read_b128 v[188:191], v128 offset:36864
	v_mfma_f32_16x16x32_bf16 v[8:11], v[192:195], v[220:223], v[8:11]
	v_mfma_f32_16x16x32_bf16 v[4:7], v[200:203], v[212:215], v[4:7]
	ds_read_b128 v[196:199], v128 offset:38912
	v_mfma_f32_16x16x32_bf16 v[0:3], v[200:203], v[220:223], v[0:3]
	s_barrier
	s_setprio 0
	ds_read_b128 v[176:179], v128 offset:33792
	ds_read_b128 v[184:187], v128 offset:35840
	ds_read_b128 v[192:195], v128 offset:37888
	ds_read_b128 v[200:203], v128 offset:39936
	s_add_u32 m0, s29, 0x4000
	s_nop 0
	s_add_u32 vcc_lo, s26, s14
	s_addc_u32 vcc_hi, s27, s15
	global_load_lds_dwordx4 v134, vcc
	s_add_u32 m0, s29, 0x6000
	s_nop 0
	global_load_lds_dwordx4 v136, vcc
	s_waitcnt lgkmcnt(8)
	s_setprio 1
	s_barrier
	s_waitcnt lgkmcnt(0)
	v_mfma_f32_16x16x32_bf16 v[124:127], v[172:175], v[156:159], v[124:127]
	v_mfma_f32_16x16x32_bf16 v[120:123], v[172:175], v[164:167], v[120:123]
	v_mfma_f32_16x16x32_bf16 v[116:119], v[180:183], v[156:159], v[116:119]
	v_mfma_f32_16x16x32_bf16 v[112:115], v[180:183], v[164:167], v[112:115]
	v_mfma_f32_16x16x32_bf16 v[108:111], v[188:191], v[156:159], v[108:111]
	v_mfma_f32_16x16x32_bf16 v[104:107], v[188:191], v[164:167], v[104:107]
	v_mfma_f32_16x16x32_bf16 v[100:103], v[196:199], v[156:159], v[100:103]
	v_mfma_f32_16x16x32_bf16 v[96:99], v[196:199], v[164:167], v[96:99]
	v_mfma_f32_16x16x32_bf16 v[124:127], v[176:179], v[160:163], v[124:127]
	v_mfma_f32_16x16x32_bf16 v[120:123], v[176:179], v[168:171], v[120:123]
	v_mfma_f32_16x16x32_bf16 v[116:119], v[184:187], v[160:163], v[116:119]
	v_mfma_f32_16x16x32_bf16 v[112:115], v[184:187], v[168:171], v[112:115]
	v_mfma_f32_16x16x32_bf16 v[108:111], v[192:195], v[160:163], v[108:111]
	v_mfma_f32_16x16x32_bf16 v[104:107], v[192:195], v[168:171], v[104:107]
	v_mfma_f32_16x16x32_bf16 v[100:103], v[200:203], v[160:163], v[100:103]
	v_mfma_f32_16x16x32_bf16 v[96:99], v[200:203], v[168:171], v[96:99]
	s_barrier
	s_setprio 0
	ds_read_b128 v[204:207], v145 offset:49152
	ds_read_b128 v[212:215], v145 offset:50176
	ds_read_b128 v[216:219], v145 offset:51200
	ds_read_b128 v[220:223], v145 offset:52224
	s_add_u32 m0, s29, s52
	s_nop 0
	s_add_u32 vcc_lo, s26, s16
	s_addc_u32 vcc_hi, s27, s17
	global_load_lds_dwordx4 v130, vcc
	v_lshl_add_u64 v[230:231], v[228:229], 0, s[16:17]
	s_add_u32 m0, s29, s52
	s_add_u32 m0, m0, 0x2000
	s_nop 0
	global_load_lds_dwordx4 v132, vcc
	s_setprio 1
	s_barrier
	s_waitcnt lgkmcnt(0)
	v_mfma_f32_16x16x32_bf16 v[92:95], v[172:175], v[204:207], v[92:95]
	v_mfma_f32_16x16x32_bf16 v[88:91], v[172:175], v[216:219], v[88:91]
	v_mfma_f32_16x16x32_bf16 v[84:87], v[180:183], v[204:207], v[84:87]
	v_mfma_f32_16x16x32_bf16 v[80:83], v[180:183], v[216:219], v[80:83]
	v_mfma_f32_16x16x32_bf16 v[76:79], v[188:191], v[204:207], v[76:79]
	v_mfma_f32_16x16x32_bf16 v[72:75], v[188:191], v[216:219], v[72:75]
	v_mfma_f32_16x16x32_bf16 v[68:71], v[196:199], v[204:207], v[68:71]
	v_mfma_f32_16x16x32_bf16 v[64:67], v[196:199], v[216:219], v[64:67]
	v_mfma_f32_16x16x32_bf16 v[92:95], v[176:179], v[212:215], v[92:95]
	ds_read_b128 v[172:175], v128 offset:49152
	v_mfma_f32_16x16x32_bf16 v[88:91], v[176:179], v[220:223], v[88:91]
	v_mfma_f32_16x16x32_bf16 v[84:87], v[184:187], v[212:215], v[84:87]
	ds_read_b128 v[180:183], v128 offset:51200
	v_mfma_f32_16x16x32_bf16 v[80:83], v[184:187], v[220:223], v[80:83]
	v_mfma_f32_16x16x32_bf16 v[76:79], v[192:195], v[212:215], v[76:79]
	ds_read_b128 v[188:191], v128 offset:53248
	v_mfma_f32_16x16x32_bf16 v[72:75], v[192:195], v[220:223], v[72:75]
	v_mfma_f32_16x16x32_bf16 v[68:71], v[200:203], v[212:215], v[68:71]
	ds_read_b128 v[196:199], v128 offset:55296
	v_mfma_f32_16x16x32_bf16 v[64:67], v[200:203], v[220:223], v[64:67]
	s_barrier
	s_setprio 0
	ds_read_b128 v[176:179], v128 offset:50176
	ds_read_b128 v[184:187], v128 offset:52224
	ds_read_b128 v[192:195], v128 offset:54272
	ds_read_b128 v[200:203], v128 offset:56320
	s_add_u32 m0, s29, 0x8000
	s_nop 0
	s_add_u32 vcc_lo, s26, s18
	s_addc_u32 vcc_hi, s27, s19
	global_load_lds_dwordx4 v134, vcc
	v_lshl_add_u64 v[208:209], v[224:225], 0, s[18:19]
	s_add_u32 m0, s29, 0xa000
	s_nop 0
	global_load_lds_dwordx4 v136, vcc
	s_waitcnt vmcnt(8)
	s_setprio 1
	s_barrier
; #define WAIT_V(n) asm volatile("s_waitcnt vmcnt(" #n ")" ::: "memory")
; #define WAIT_L(n) asm volatile("s_waitcnt lgkmcnt(" #n ")" ::: "memory")
; #define BAR __builtin_amdgcn_s_barrier()
; #define SCHED __builtin_amdgcn_sched_barrier(0)
; #define STAGE(P, BASE, br, kt) do { const char* _g = (const char*)((BASE) + (size_t)(br) * GK + (kt) * BK); \
;     __builtin_amdgcn_global_load_lds((const unsigned*)(_g + voff0), (unsigned*)((char*)(P) + tx * 16), 16, 0, 0); \
;     __builtin_amdgcn_global_load_lds((const unsigned*)(_g + voff1), (unsigned*)((char*)(P) + tx * 16 + 8192), 16, 0, 0); } while (0)
; #define LDA(dst, b, h) _Pragma("unroll") for (int m = 0; m < 4; ++m) _Pragma("unroll") for (int k = 0; k < 2; ++k) \
;     dst[m][k] = *reinterpret_cast<const bf16x8*>((char*)shm + abase + (((b) * 2 + (h)) * 16384 + (m * 2 + k) * 1024))
; #define LDB(dst, b, h) _Pragma("unroll") for (int n = 0; n < 2; ++n) _Pragma("unroll") for (int k = 0; k < 2; ++k) \
;     dst[n][k] = *reinterpret_cast<const bf16x8*>((char*)shm + bbase + (((b) * 2 + (h)) * 16384 + (n * 2 + k) * 1024))
; template <bool SWAP>
; __device__ __forceinline__ void gemm_main(const u16* __restrict__ A, const u16* __restrict__ Bt, int brow, int bcol,
;                                           u16* shm, f32x4 (&acc)[2][2][4][2]) {
;     ...
;     LDA(At, 1, 1); STAGE(SA(1, 0), A, brow, t + 3);
;     BAR; WAIT_L(0); MMA(1, 0, At, B0); BAR; SCHED;
;     STAGE(SB(1, 1), Bt, bcol + HALF, t + 3);
;     WAIT_V(6); BAR; MMA(1, 1, At, B1); BAR;
;   }
;   { LDB(B0, 0, 0); LDA(At, 0, 0); STAGE(SA(1, 1), A, brow + HALF, nt - 1);
;     BAR; WAIT_L(0); MMA(0, 0, At, B0); BAR;
;     LDB(B1, 0, 1); BAR; WAIT_L(0); MMA(0, 1, At, B1); BAR;
;     LDA(At, 0, 1); WAIT_V(4); BAR; WAIT_L(0); MMA(1, 0, At, B0); MMA(1, 1, At, B1); BAR; }
;   { LDB(B0, 1, 0); LDA(At, 1, 0); WAIT_V(2); BAR; WAIT_L(0); MMA(0, 0, At, B0); BAR;
	s_waitcnt lgkmcnt(0)
	v_mfma_f32_16x16x32_bf16 v[60:63], v[172:175], v[156:159], v[60:63]
	v_mfma_f32_16x16x32_bf16 v[56:59], v[172:175], v[164:167], v[56:59]
	v_mfma_f32_16x16x32_bf16 v[52:55], v[180:183], v[156:159], v[52:55]
	v_mfma_f32_16x16x32_bf16 v[48:51], v[180:183], v[164:167], v[48:51]
	v_mfma_f32_16x16x32_bf16 v[44:47], v[188:191], v[156:159], v[44:47]
	v_mfma_f32_16x16x32_bf16 v[40:43], v[188:191], v[164:167], v[40:43]
	v_mfma_f32_16x16x32_bf16 v[36:39], v[196:199], v[156:159], v[36:39]
	v_mfma_f32_16x16x32_bf16 v[32:35], v[196:199], v[164:167], v[32:35]
	v_mfma_f32_16x16x32_bf16 v[60:63], v[176:179], v[160:163], v[60:63]
	v_mfma_f32_16x16x32_bf16 v[56:59], v[176:179], v[168:171], v[56:59]
	v_mfma_f32_16x16x32_bf16 v[52:55], v[184:187], v[160:163], v[52:55]
	v_mfma_f32_16x16x32_bf16 v[48:51], v[184:187], v[168:171], v[48:51]
	v_mfma_f32_16x16x32_bf16 v[44:47], v[192:195], v[160:163], v[44:47]
	v_mfma_f32_16x16x32_bf16 v[40:43], v[192:195], v[168:171], v[40:43]
	v_mfma_f32_16x16x32_bf16 v[36:39], v[200:203], v[160:163], v[36:39]
	v_mfma_f32_16x16x32_bf16 v[32:35], v[200:203], v[168:171], v[32:35]
	s_barrier
	s_setprio 0
	ds_read_b128 v[156:159], v145
	ds_read_b128 v[160:163], v145 offset:1024
	ds_read_b128 v[164:167], v145 offset:2048
	ds_read_b128 v[168:171], v145 offset:3072
	s_add_u32 m0, s29, s53
	s_nop 0
	s_add_u32 vcc_lo, s26, s20
	s_addc_u32 vcc_hi, s27, s21
	global_load_lds_dwordx4 v130, vcc
	v_lshl_add_u64 v[254:255], v[228:229], 0, s[20:21]
	s_add_u32 m0, s29, s53
	s_add_u32 m0, m0, 0x2000
	s_nop 0
	global_load_lds_dwordx4 v132, vcc
	s_waitcnt vmcnt(6)
	s_setprio 1
	s_barrier
	v_mfma_f32_16x16x32_bf16 v[28:31], v[172:175], v[204:207], v[28:31]
	v_mfma_f32_16x16x32_bf16 v[24:27], v[172:175], v[216:219], v[24:27]
	v_mfma_f32_16x16x32_bf16 v[20:23], v[180:183], v[204:207], v[20:23]
	v_mfma_f32_16x16x32_bf16 v[16:19], v[180:183], v[216:219], v[16:19]
	v_mfma_f32_16x16x32_bf16 v[12:15], v[188:191], v[204:207], v[12:15]
	v_mfma_f32_16x16x32_bf16 v[8:11], v[188:191], v[216:219], v[8:11]
	v_mfma_f32_16x16x32_bf16 v[4:7], v[196:199], v[204:207], v[4:7]
	v_mfma_f32_16x16x32_bf16 v[0:3], v[196:199], v[216:219], v[0:3]
	v_mfma_f32_16x16x32_bf16 v[28:31], v[176:179], v[212:215], v[28:31]
	ds_read_b128 v[172:175], v128
	v_mfma_f32_16x16x32_bf16 v[24:27], v[176:179], v[220:223], v[24:27]
	v_mfma_f32_16x16x32_bf16 v[20:23], v[184:187], v[212:215], v[20:23]
	ds_read_b128 v[180:183], v128 offset:2048
	v_mfma_f32_16x16x32_bf16 v[16:19], v[184:187], v[220:223], v[16:19]
	v_mfma_f32_16x16x32_bf16 v[12:15], v[192:195], v[212:215], v[12:15]
	ds_read_b128 v[188:191], v128 offset:4096
	v_mfma_f32_16x16x32_bf16 v[8:11], v[192:195], v[220:223], v[8:11]
	v_mfma_f32_16x16x32_bf16 v[4:7], v[200:203], v[212:215], v[4:7]
	ds_read_b128 v[196:199], v128 offset:6144
	v_mfma_f32_16x16x32_bf16 v[0:3], v[200:203], v[220:223], v[0:3]
	s_add_i32 s28, s28, 2
	s_add_u32 s26, s26, 0x100
	s_addc_u32 s27, s27, 0
	s_cmp_lt_u32 s28, 28
	s_barrier
	s_setprio 0
	s_cbranch_scc1 .LBB0_84
	v_lshlrev_b32_e32 v130, 3, v147
	v_lshlrev_b32_e32 v131, 5, v147
	v_and_b32_e32 v130, 0xffff0, v130
	v_and_b32_e32 v131, 32, v131
	v_add_u32_e32 v131, v131, v149
	v_add_lshl_u32 v130, v148, v130, 12
	s_add_u32 s4, s37, s4
	v_lshl_add_u32 v155, v131, 1, v130
	v_lshlrev_b32_e32 v130, 3, v150
	v_lshlrev_b32_e32 v131, 5, v150
	s_addc_u32 s27, s38, 0
	v_and_b32_e32 v130, 0xffff0, v130
	v_and_b32_e32 v131, 32, v131
	s_add_u32 s26, s4, 0x80f80
	v_readfirstlane_b32 s4, v153
	v_add_u32_e32 v131, v131, v152
	v_add_lshl_u32 v130, v151, v130, 12
	s_addc_u32 s27, s27, 0
	s_mov_b32 m0, s4
	v_readfirstlane_b32 s4, v154
	v_lshl_add_u32 v150, v131, 1, v130
	ds_read_b128 v[130:133], v145
	ds_read_b128 v[134:137], v145 offset:1024
	ds_read_b128 v[146:149], v145 offset:2048
	ds_read_b128 v[156:159], v145 offset:3072
	ds_read_b128 v[160:163], v128
	ds_read_b128 v[164:167], v128 offset:1024
	ds_read_b128 v[168:171], v128 offset:2048
	ds_read_b128 v[172:175], v128 offset:3072
	ds_read_b128 v[176:179], v128 offset:4096
	ds_read_b128 v[180:183], v128 offset:5120
	ds_read_b128 v[184:187], v128 offset:6144
	ds_read_b128 v[188:191], v128 offset:7168
	global_load_lds_dwordx4 v155, s[26:27]
	s_mov_b32 m0, s4
	s_nop 0
	global_load_lds_dwordx4 v150, s[26:27]
	s_barrier
	s_waitcnt lgkmcnt(0)
	s_setprio 1
	s_waitcnt lgkmcnt(0)
	v_mfma_f32_16x16x32_bf16 v[124:127], v[160:163], v[130:133], v[124:127]
	v_mfma_f32_16x16x32_bf16 v[116:119], v[168:171], v[130:133], v[116:119]
	v_mfma_f32_16x16x32_bf16 v[108:111], v[176:179], v[130:133], v[108:111]
	v_mfma_f32_16x16x32_bf16 v[100:103], v[184:187], v[130:133], v[100:103]
	v_mfma_f32_16x16x32_bf16 v[96:99], v[184:187], v[146:149], v[96:99]
	v_mfma_f32_16x16x32_bf16 v[124:127], v[164:167], v[134:137], v[124:127]
	v_mfma_f32_16x16x32_bf16 v[120:123], v[160:163], v[146:149], v[120:123]
	v_mfma_f32_16x16x32_bf16 v[116:119], v[172:175], v[134:137], v[116:119]
	v_mfma_f32_16x16x32_bf16 v[112:115], v[168:171], v[146:149], v[112:115]
	v_mfma_f32_16x16x32_bf16 v[108:111], v[180:183], v[134:137], v[108:111]
	v_mfma_f32_16x16x32_bf16 v[104:107], v[176:179], v[146:149], v[104:107]
	v_mfma_f32_16x16x32_bf16 v[100:103], v[188:191], v[134:137], v[100:103]
	v_mfma_f32_16x16x32_bf16 v[96:99], v[188:191], v[156:159], v[96:99]
	v_mfma_f32_16x16x32_bf16 v[150:153], v[164:167], v[156:159], v[120:123]
	v_mfma_f32_16x16x32_bf16 v[192:195], v[172:175], v[156:159], v[112:115]
	v_mfma_f32_16x16x32_bf16 v[196:199], v[180:183], v[156:159], v[104:107]
	s_setprio 0
	s_barrier
	s_nop 0
	ds_read_b128 v[104:107], v145 offset:16384
	ds_read_b128 v[112:115], v145 offset:17408
	ds_read_b128 v[120:123], v145 offset:18432
	ds_read_b128 v[200:203], v145 offset:19456
	s_barrier
; #define WAIT_V(n) asm volatile("s_waitcnt vmcnt(" #n ")" ::: "memory")
; #define WAIT_L(n) asm volatile("s_waitcnt lgkmcnt(" #n ")" ::: "memory")
; #define BAR __builtin_amdgcn_s_barrier()
; #define LDA(dst, b, h) _Pragma("unroll") for (int m = 0; m < 4; ++m) _Pragma("unroll") for (int k = 0; k < 2; ++k) \
;     dst[m][k] = *reinterpret_cast<const bf16x8*>((char*)shm + abase + (((b) * 2 + (h)) * 16384 + (m * 2 + k) * 1024))
; #define LDB(dst, b, h) _Pragma("unroll") for (int n = 0; n < 2; ++n) _Pragma("unroll") for (int k = 0; k < 2; ++k) \
;     dst[n][k] = *reinterpret_cast<const bf16x8*>((char*)shm + bbase + (((b) * 2 + (h)) * 16384 + (n * 2 + k) * 1024))
; template <bool SWAP>
; __device__ __forceinline__ void gemm_main(const u16* __restrict__ A, const u16* __restrict__ Bt, int brow, int bcol,
;                                           u16* shm, f32x4 (&acc)[2][2][4][2]) {
;     ...
;     LDB(B1, 0, 1); BAR; WAIT_L(0); MMA(0, 1, At, B1); BAR;
;     LDA(At, 0, 1); WAIT_V(4); BAR; WAIT_L(0); MMA(1, 0, At, B0); MMA(1, 1, At, B1); BAR; }
;   { LDB(B0, 1, 0); LDA(At, 1, 0); WAIT_V(2); BAR; WAIT_L(0); MMA(0, 0, At, B0); BAR;
	s_waitcnt lgkmcnt(0)
	s_setprio 1
	s_waitcnt lgkmcnt(0)
	v_mfma_f32_16x16x32_bf16 v[84:87], v[168:171], v[104:107], v[84:87]
	v_mfma_f32_16x16x32_bf16 v[76:79], v[176:179], v[104:107], v[76:79]
	v_mfma_f32_16x16x32_bf16 v[68:71], v[184:187], v[104:107], v[68:71]
	v_mfma_f32_16x16x32_bf16 v[92:95], v[160:163], v[104:107], v[92:95]
	v_mfma_f32_16x16x32_bf16 v[88:91], v[160:163], v[120:123], v[88:91]
	v_mfma_f32_16x16x32_bf16 v[84:87], v[172:175], v[112:115], v[84:87]
	v_mfma_f32_16x16x32_bf16 v[80:83], v[168:171], v[120:123], v[80:83]
	v_mfma_f32_16x16x32_bf16 v[76:79], v[180:183], v[112:115], v[76:79]
	v_mfma_f32_16x16x32_bf16 v[72:75], v[176:179], v[120:123], v[72:75]
	v_mfma_f32_16x16x32_bf16 v[68:71], v[188:191], v[112:115], v[68:71]
	v_mfma_f32_16x16x32_bf16 v[64:67], v[184:187], v[120:123], v[64:67]
	v_mfma_f32_16x16x32_bf16 v[204:207], v[164:167], v[112:115], v[92:95]
	v_mfma_f32_16x16x32_bf16 v[160:163], v[164:167], v[200:203], v[88:91]
	v_mfma_f32_16x16x32_bf16 v[164:167], v[172:175], v[200:203], v[80:83]
	v_mfma_f32_16x16x32_bf16 v[168:171], v[180:183], v[200:203], v[72:75]
	v_mfma_f32_16x16x32_bf16 v[172:175], v[188:191], v[200:203], v[64:67]
	s_setprio 0
	s_barrier
	s_nop 0
	ds_read_b128 v[64:67], v128 offset:16384
	ds_read_b128 v[72:75], v128 offset:17408
	ds_read_b128 v[80:83], v128 offset:18432
	ds_read_b128 v[88:91], v128 offset:19456
	ds_read_b128 v[92:95], v128 offset:20480
	ds_read_b128 v[176:179], v128 offset:21504
	ds_read_b128 v[180:183], v128 offset:22528
	ds_read_b128 v[184:187], v128 offset:23552
	s_waitcnt vmcnt(4)
	s_barrier
	s_waitcnt lgkmcnt(0)
	s_setprio 1
	s_waitcnt lgkmcnt(0)
	v_mfma_f32_16x16x32_bf16 v[60:63], v[64:67], v[130:133], v[60:63]
	v_mfma_f32_16x16x32_bf16 v[52:55], v[80:83], v[130:133], v[52:55]
	v_mfma_f32_16x16x32_bf16 v[44:47], v[92:95], v[130:133], v[44:47]
	v_mfma_f32_16x16x32_bf16 v[36:39], v[180:183], v[130:133], v[36:39]
	v_mfma_f32_16x16x32_bf16 v[60:63], v[72:75], v[134:137], v[60:63]
	v_mfma_f32_16x16x32_bf16 v[56:59], v[64:67], v[146:149], v[56:59]
	v_mfma_f32_16x16x32_bf16 v[52:55], v[88:91], v[134:137], v[52:55]
	v_mfma_f32_16x16x32_bf16 v[48:51], v[80:83], v[146:149], v[48:51]
	v_mfma_f32_16x16x32_bf16 v[44:47], v[176:179], v[134:137], v[44:47]
	v_mfma_f32_16x16x32_bf16 v[40:43], v[92:95], v[146:149], v[40:43]
	v_mfma_f32_16x16x32_bf16 v[36:39], v[184:187], v[134:137], v[36:39]
	v_mfma_f32_16x16x32_bf16 v[32:35], v[180:183], v[146:149], v[32:35]
	v_mfma_f32_16x16x32_bf16 v[188:191], v[72:75], v[156:159], v[56:59]
	v_mfma_f32_16x16x32_bf16 v[212:215], v[88:91], v[156:159], v[48:51]
	v_mfma_f32_16x16x32_bf16 v[216:219], v[176:179], v[156:159], v[40:43]
	v_mfma_f32_16x16x32_bf16 v[130:133], v[184:187], v[156:159], v[32:35]
	s_setprio 0
	s_setprio 1
	v_mfma_f32_16x16x32_bf16 v[28:31], v[64:67], v[104:107], v[28:31]
	v_mfma_f32_16x16x32_bf16 v[20:23], v[80:83], v[104:107], v[20:23]
	v_mfma_f32_16x16x32_bf16 v[12:15], v[92:95], v[104:107], v[12:15]
	v_mfma_f32_16x16x32_bf16 v[4:7], v[180:183], v[104:107], v[4:7]
	v_mfma_f32_16x16x32_bf16 v[28:31], v[72:75], v[112:115], v[28:31]
	v_mfma_f32_16x16x32_bf16 v[24:27], v[64:67], v[120:123], v[24:27]
	v_mfma_f32_16x16x32_bf16 v[20:23], v[88:91], v[112:115], v[20:23]
	v_mfma_f32_16x16x32_bf16 v[16:19], v[80:83], v[120:123], v[16:19]
	v_mfma_f32_16x16x32_bf16 v[12:15], v[176:179], v[112:115], v[12:15]
	v_mfma_f32_16x16x32_bf16 v[8:11], v[92:95], v[120:123], v[8:11]
	v_mfma_f32_16x16x32_bf16 v[4:7], v[184:187], v[112:115], v[4:7]
	v_mfma_f32_16x16x32_bf16 v[0:3], v[180:183], v[120:123], v[0:3]
	v_mfma_f32_16x16x32_bf16 v[134:137], v[72:75], v[200:203], v[24:27]
	v_mfma_f32_16x16x32_bf16 v[146:149], v[88:91], v[200:203], v[16:19]
	v_mfma_f32_16x16x32_bf16 v[154:157], v[176:179], v[200:203], v[8:11]
	v_mfma_f32_16x16x32_bf16 v[176:179], v[184:187], v[200:203], v[0:3]
	s_setprio 0
	s_barrier
	s_nop 1
	ds_read_b128 v[0:3], v145 offset:32768
	ds_read_b128 v[8:11], v145 offset:33792
	ds_read_b128 v[16:19], v145 offset:34816
	ds_read_b128 v[24:27], v145 offset:35840
	ds_read_b128 v[32:35], v128 offset:32768
	ds_read_b128 v[40:43], v128 offset:33792
	ds_read_b128 v[48:51], v128 offset:34816
	ds_read_b128 v[56:59], v128 offset:35840
	ds_read_b128 v[64:67], v128 offset:36864
	ds_read_b128 v[180:183], v128 offset:37888
	ds_read_b128 v[184:187], v128 offset:38912
	ds_read_b128 v[200:203], v128 offset:39936
	s_waitcnt vmcnt(2)
	s_barrier
; #define WAIT_V(n) asm volatile("s_waitcnt vmcnt(" #n ")" ::: "memory")
; #define WAIT_L(n) asm volatile("s_waitcnt lgkmcnt(" #n ")" ::: "memory")
; #define BAR __builtin_amdgcn_s_barrier()
; #define LDA(dst, b, h) _Pragma("unroll") for (int m = 0; m < 4; ++m) _Pragma("unroll") for (int k = 0; k < 2; ++k) \
;     dst[m][k] = *reinterpret_cast<const bf16x8*>((char*)shm + abase + (((b) * 2 + (h)) * 16384 + (m * 2 + k) * 1024))
; #define LDB(dst, b, h) _Pragma("unroll") for (int n = 0; n < 2; ++n) _Pragma("unroll") for (int k = 0; k < 2; ++k) \
;     dst[n][k] = *reinterpret_cast<const bf16x8*>((char*)shm + bbase + (((b) * 2 + (h)) * 16384 + (n * 2 + k) * 1024))
; template <bool SWAP>
; __device__ __forceinline__ void gemm_main(const u16* __restrict__ A, const u16* __restrict__ Bt, int brow, int bcol,
;                                           u16* shm, f32x4 (&acc)[2][2][4][2]) {
;     ...
;   { LDB(B0, 1, 0); LDA(At, 1, 0); WAIT_V(2); BAR; WAIT_L(0); MMA(0, 0, At, B0); BAR;
;     LDB(B1, 1, 1); WAIT_V(0); BAR; WAIT_L(0); MMA(0, 1, At, B1); BAR;
;     LDA(At, 1, 1); BAR; WAIT_L(0); MMA(1, 0, At, B0); MMA(1, 1, At, B1); BAR; }
;   if (wr == 0) BAR;
	s_waitcnt lgkmcnt(0)
	s_setprio 1
	s_waitcnt lgkmcnt(0)
	v_mfma_f32_16x16x32_bf16 v[72:75], v[32:35], v[0:3], v[124:127]
	v_mfma_f32_16x16x32_bf16 v[120:123], v[40:43], v[8:11], v[72:75]
	v_mfma_f32_16x16x32_bf16 v[72:75], v[32:35], v[16:19], v[150:153]
	v_mfma_f32_16x16x32_bf16 v[112:115], v[40:43], v[24:27], v[72:75]
	v_mfma_f32_16x16x32_bf16 v[72:75], v[48:51], v[0:3], v[116:119]
	v_mfma_f32_16x16x32_bf16 v[124:127], v[56:59], v[8:11], v[72:75]
	v_mfma_f32_16x16x32_bf16 v[72:75], v[48:51], v[16:19], v[192:195]
	v_mfma_f32_16x16x32_bf16 v[116:119], v[56:59], v[24:27], v[72:75]
	v_mfma_f32_16x16x32_bf16 v[72:75], v[64:67], v[0:3], v[108:111]
	v_mfma_f32_16x16x32_bf16 v[104:107], v[180:183], v[8:11], v[72:75]
	v_mfma_f32_16x16x32_bf16 v[72:75], v[64:67], v[16:19], v[196:199]
	v_mfma_f32_16x16x32_bf16 v[92:95], v[180:183], v[24:27], v[72:75]
	v_mfma_f32_16x16x32_bf16 v[72:75], v[184:187], v[0:3], v[100:103]
	v_mfma_f32_16x16x32_bf16 v[108:111], v[200:203], v[8:11], v[72:75]
	v_mfma_f32_16x16x32_bf16 v[72:75], v[184:187], v[16:19], v[96:99]
	v_mfma_f32_16x16x32_bf16 v[100:103], v[200:203], v[24:27], v[72:75]
	s_setprio 0
	s_barrier
	ds_read_b128 v[150:153], v145 offset:49152
	ds_read_b128 v[192:195], v145 offset:50176
	ds_read_b128 v[196:199], v145 offset:51200
	ds_read_b128 v[220:223], v145 offset:52224
	s_waitcnt vmcnt(0)
	s_barrier
	s_waitcnt lgkmcnt(0)
	s_setprio 1
	s_waitcnt lgkmcnt(0)
	v_mfma_f32_16x16x32_bf16 v[72:75], v[32:35], v[150:153], v[204:207]
	v_mfma_f32_16x16x32_bf16 v[32:35], v[32:35], v[196:199], v[160:163]
	v_mfma_f32_16x16x32_bf16 v[80:83], v[40:43], v[220:223], v[32:35]
	v_mfma_f32_16x16x32_bf16 v[32:35], v[48:51], v[150:153], v[84:87]
	v_mfma_f32_16x16x32_bf16 v[96:99], v[56:59], v[192:195], v[32:35]
	v_mfma_f32_16x16x32_bf16 v[32:35], v[48:51], v[196:199], v[164:167]
	v_mfma_f32_16x16x32_bf16 v[84:87], v[56:59], v[220:223], v[32:35]
	v_mfma_f32_16x16x32_bf16 v[32:35], v[64:67], v[150:153], v[76:79]
	v_mfma_f32_16x16x32_bf16 v[88:91], v[40:43], v[192:195], v[72:75]
	v_mfma_f32_16x16x32_bf16 v[72:75], v[180:183], v[192:195], v[32:35]
	v_mfma_f32_16x16x32_bf16 v[32:35], v[64:67], v[196:199], v[168:171]
	v_mfma_f32_16x16x32_bf16 v[64:67], v[180:183], v[220:223], v[32:35]
	v_mfma_f32_16x16x32_bf16 v[32:35], v[184:187], v[150:153], v[68:71]
	v_mfma_f32_16x16x32_bf16 v[76:79], v[200:203], v[192:195], v[32:35]
	v_mfma_f32_16x16x32_bf16 v[32:35], v[184:187], v[196:199], v[172:175]
	v_mfma_f32_16x16x32_bf16 v[68:71], v[200:203], v[220:223], v[32:35]
	s_setprio 0
	s_barrier
	ds_read_b128 v[158:161], v128 offset:49152
	ds_read_b128 v[162:165], v128 offset:50176
	ds_read_b128 v[166:169], v128 offset:51200
	ds_read_b128 v[170:173], v128 offset:52224
	ds_read_b128 v[180:183], v128 offset:53248
	ds_read_b128 v[184:187], v128 offset:54272
	ds_read_b128 v[200:203], v128 offset:55296
	ds_read_b128 v[204:207], v128 offset:56320
	s_barrier
	s_waitcnt lgkmcnt(0)
	s_setprio 1
	s_waitcnt lgkmcnt(0)
	v_mfma_f32_16x16x32_bf16 v[32:35], v[158:161], v[0:3], v[60:63]
	v_mfma_f32_16x16x32_bf16 v[56:59], v[162:165], v[8:11], v[32:35]
	v_mfma_f32_16x16x32_bf16 v[32:35], v[158:161], v[16:19], v[188:191]
	v_mfma_f32_16x16x32_bf16 v[48:51], v[162:165], v[24:27], v[32:35]
	v_mfma_f32_16x16x32_bf16 v[32:35], v[166:169], v[0:3], v[52:55]
	v_mfma_f32_16x16x32_bf16 v[60:63], v[170:173], v[8:11], v[32:35]
	v_mfma_f32_16x16x32_bf16 v[32:35], v[166:169], v[16:19], v[212:215]
	v_mfma_f32_16x16x32_bf16 v[52:55], v[170:173], v[24:27], v[32:35]
	v_mfma_f32_16x16x32_bf16 v[32:35], v[180:183], v[0:3], v[44:47]
	v_mfma_f32_16x16x32_bf16 v[0:3], v[200:203], v[0:3], v[36:39]
	v_mfma_f32_16x16x32_bf16 v[40:43], v[184:187], v[8:11], v[32:35]
	v_mfma_f32_16x16x32_bf16 v[32:35], v[180:183], v[16:19], v[216:219]
	v_mfma_f32_16x16x32_bf16 v[44:47], v[204:207], v[8:11], v[0:3]
	v_mfma_f32_16x16x32_bf16 v[0:3], v[200:203], v[16:19], v[130:133]
	v_mfma_f32_16x16x32_bf16 v[32:35], v[184:187], v[24:27], v[32:35]
	v_mfma_f32_16x16x32_bf16 v[36:39], v[204:207], v[24:27], v[0:3]
	s_setprio 0
	s_setprio 1
	v_mfma_f32_16x16x32_bf16 v[0:3], v[158:161], v[150:153], v[28:31]
	v_mfma_f32_16x16x32_bf16 v[24:27], v[162:165], v[192:195], v[0:3]
	v_mfma_f32_16x16x32_bf16 v[0:3], v[158:161], v[196:199], v[134:137]
	v_mfma_f32_16x16x32_bf16 v[16:19], v[162:165], v[220:223], v[0:3]
	v_mfma_f32_16x16x32_bf16 v[0:3], v[166:169], v[150:153], v[20:23]
	v_mfma_f32_16x16x32_bf16 v[28:31], v[170:173], v[192:195], v[0:3]
	v_mfma_f32_16x16x32_bf16 v[0:3], v[166:169], v[196:199], v[146:149]
	v_mfma_f32_16x16x32_bf16 v[20:23], v[170:173], v[220:223], v[0:3]
	v_mfma_f32_16x16x32_bf16 v[0:3], v[180:183], v[150:153], v[12:15]
	v_mfma_f32_16x16x32_bf16 v[4:7], v[200:203], v[150:153], v[4:7]
	v_mfma_f32_16x16x32_bf16 v[8:11], v[184:187], v[192:195], v[0:3]
	v_mfma_f32_16x16x32_bf16 v[0:3], v[180:183], v[196:199], v[154:157]
	v_mfma_f32_16x16x32_bf16 v[12:15], v[204:207], v[192:195], v[4:7]
	v_mfma_f32_16x16x32_bf16 v[4:7], v[200:203], v[196:199], v[176:179]
	v_mfma_f32_16x16x32_bf16 v[0:3], v[184:187], v[220:223], v[0:3]
	v_mfma_f32_16x16x32_bf16 v[4:7], v[204:207], v[220:223], v[4:7]
	s_setprio 0
	v_cmp_gt_u32_e32 vcc, s55, v144
	s_barrier
	s_and_saveexec_b64 s[26:27], vcc
	s_cbranch_execz .LBB0_87
	s_barrier

; #define WAIT_V(n) asm volatile("s_waitcnt vmcnt(" #n ")" ::: "memory")
; #define WAIT_L(n) asm volatile("s_waitcnt lgkmcnt(" #n ")" ::: "memory")
; #define BAR __builtin_amdgcn_s_barrier()
; #define SCHED __builtin_amdgcn_sched_barrier(0)
; #define STAGE(P, BASE, br, kt) do { const char* _g = (const char*)((BASE) + (size_t)(br) * GK + (kt) * BK); \
;     __builtin_amdgcn_global_load_lds((const unsigned*)(_g + voff0), (unsigned*)((char*)(P) + tx * 16), 16, 0, 0); \
;     __builtin_amdgcn_global_load_lds((const unsigned*)(_g + voff1), (unsigned*)((char*)(P) + tx * 16 + 8192), 16, 0, 0); } while (0)
; #define LDA(dst, b, h) _Pragma("unroll") for (int m = 0; m < 4; ++m) _Pragma("unroll") for (int k = 0; k < 2; ++k) \
;     dst[m][k] = *reinterpret_cast<const bf16x8*>((char*)shm + abase + (((b) * 2 + (h)) * 16384 + (m * 2 + k) * 1024))
; #define LDB(dst, b, h) _Pragma("unroll") for (int n = 0; n < 2; ++n) _Pragma("unroll") for (int k = 0; k < 2; ++k) \
;     dst[n][k] = *reinterpret_cast<const bf16x8*>((char*)shm + bbase + (((b) * 2 + (h)) * 16384 + (n * 2 + k) * 1024))
; template <bool SWAP>
; __device__ __forceinline__ void gemm_main(const u16* __restrict__ A, const u16* __restrict__ Bt, int brow, int bcol,
;                                           u16* shm, f32x4 (&acc)[2][2][4][2]) {
;     ...
;   for (int t = 0; t < nt - 2; t += 2) {
;     LDB(B0, 0, 0); SCHED; LDA(At, 0, 0); STAGE(SA(1, 1), A, brow + HALF, t + 1);
;     WAIT_L(8); BAR; WAIT_L(0); MMA(0, 0, At, B0); BAR; SCHED;
;     LDB(B1, 0, 1); STAGE(SB(0, 0), Bt, bcol, t + 2);
;     BAR; WAIT_L(0); MMA(0, 1, At, B1); BAR;
;     LDA(At, 0, 1); STAGE(SA(0, 0), A, brow, t + 2);
;     BAR; WAIT_L(0); MMA(1, 0, At, B0); BAR; SCHED;
;     STAGE(SB(0, 1), Bt, bcol + HALF, t + 2);
;     WAIT_V(6); BAR; MMA(1, 1, At, B1); BAR;
;     LDB(B0, 1, 0); SCHED; LDA(At, 1, 0); STAGE(SA(0, 1), A, brow + HALF, t + 2);
;     WAIT_L(8); BAR; WAIT_L(0); MMA(0, 0, At, B0); BAR; SCHED;
.LBB0_94:
	ds_read_b128 v[176:179], v145 offset:1024
	ds_read_b128 v[184:187], v145 offset:3072
	ds_read_b128 v[192:195], v145 offset:5120
	ds_read_b128 v[200:203], v145 offset:7168
	v_add_u32_e32 v128, 0, v147
	v_add_u32_e32 v154, 0xc000, v128
	v_add_u32_e32 v155, 0xe000, v128
	s_add_u32 m0, s25, 0xc000
	v_lshl_add_u64 v[224:225], s[28:29], 0, v[132:133]
	s_add_u32 vcc_lo, s28, s6
	s_addc_u32 vcc_hi, s29, s7
	global_load_lds_dwordx4 v136, vcc
	s_add_u32 m0, s25, 0xe000
	s_nop 0
	global_load_lds_dwordx4 v132, vcc
	s_waitcnt lgkmcnt(8)
	s_setprio 1
	s_barrier
	s_waitcnt lgkmcnt(0)
	v_mfma_f32_16x16x32_bf16 v[124:127], v[156:159], v[172:175], v[124:127]
	v_mfma_f32_16x16x32_bf16 v[120:123], v[164:167], v[172:175], v[120:123]
	v_mfma_f32_16x16x32_bf16 v[116:119], v[156:159], v[180:183], v[116:119]
	v_mfma_f32_16x16x32_bf16 v[112:115], v[164:167], v[180:183], v[112:115]
	v_mfma_f32_16x16x32_bf16 v[108:111], v[156:159], v[188:191], v[108:111]
	v_mfma_f32_16x16x32_bf16 v[104:107], v[164:167], v[188:191], v[104:107]
	v_mfma_f32_16x16x32_bf16 v[100:103], v[156:159], v[196:199], v[100:103]
	v_mfma_f32_16x16x32_bf16 v[96:99], v[164:167], v[196:199], v[96:99]
	v_mfma_f32_16x16x32_bf16 v[124:127], v[160:163], v[176:179], v[124:127]
	v_mfma_f32_16x16x32_bf16 v[120:123], v[168:171], v[176:179], v[120:123]
	v_mfma_f32_16x16x32_bf16 v[116:119], v[160:163], v[184:187], v[116:119]
	v_mfma_f32_16x16x32_bf16 v[112:115], v[168:171], v[184:187], v[112:115]
	v_mfma_f32_16x16x32_bf16 v[108:111], v[160:163], v[192:195], v[108:111]
	v_mfma_f32_16x16x32_bf16 v[104:107], v[168:171], v[192:195], v[104:107]
	v_mfma_f32_16x16x32_bf16 v[100:103], v[160:163], v[200:203], v[100:103]
	v_mfma_f32_16x16x32_bf16 v[96:99], v[168:171], v[200:203], v[96:99]
	s_barrier
	s_setprio 0
	ds_read_b128 v[204:207], v146 offset:16384
	ds_read_b128 v[212:215], v146 offset:17408
	ds_read_b128 v[216:219], v146 offset:18432
	ds_read_b128 v[220:223], v146 offset:19456
	v_lshl_add_u64 v[226:227], s[28:29], 0, v[134:135]
	s_add_u32 m0, s25, s44
	s_nop 0
	s_add_u32 vcc_lo, s28, s8
	s_addc_u32 vcc_hi, s29, s9
	global_load_lds_dwordx4 v134, vcc
	v_lshl_add_u64 v[228:229], s[28:29], 0, v[130:131]
	s_add_u32 m0, s25, s44
	s_add_u32 m0, m0, 0x2000
	s_nop 0
	global_load_lds_dwordx4 v130, vcc
	s_setprio 1
	s_barrier
	s_waitcnt lgkmcnt(0)
	v_mfma_f32_16x16x32_bf16 v[92:95], v[204:207], v[172:175], v[92:95]
	v_mfma_f32_16x16x32_bf16 v[88:91], v[216:219], v[172:175], v[88:91]
	v_mfma_f32_16x16x32_bf16 v[84:87], v[204:207], v[180:183], v[84:87]
	v_mfma_f32_16x16x32_bf16 v[80:83], v[216:219], v[180:183], v[80:83]
	v_mfma_f32_16x16x32_bf16 v[76:79], v[204:207], v[188:191], v[76:79]
	v_mfma_f32_16x16x32_bf16 v[72:75], v[216:219], v[188:191], v[72:75]
	v_mfma_f32_16x16x32_bf16 v[68:71], v[204:207], v[196:199], v[68:71]
	v_mfma_f32_16x16x32_bf16 v[64:67], v[216:219], v[196:199], v[64:67]
	v_mfma_f32_16x16x32_bf16 v[92:95], v[212:215], v[176:179], v[92:95]
	ds_read_b128 v[172:175], v145 offset:16384
	v_mfma_f32_16x16x32_bf16 v[88:91], v[220:223], v[176:179], v[88:91]
	v_mfma_f32_16x16x32_bf16 v[84:87], v[212:215], v[184:187], v[84:87]
	ds_read_b128 v[180:183], v145 offset:18432
	v_mfma_f32_16x16x32_bf16 v[80:83], v[220:223], v[184:187], v[80:83]
	v_mfma_f32_16x16x32_bf16 v[76:79], v[212:215], v[192:195], v[76:79]
	ds_read_b128 v[188:191], v145 offset:20480
	v_mfma_f32_16x16x32_bf16 v[72:75], v[220:223], v[192:195], v[72:75]
	v_mfma_f32_16x16x32_bf16 v[68:71], v[212:215], v[200:203], v[68:71]
	ds_read_b128 v[196:199], v145 offset:22528
	v_mfma_f32_16x16x32_bf16 v[64:67], v[220:223], v[200:203], v[64:67]
	s_barrier
	s_setprio 0
	ds_read_b128 v[176:179], v145 offset:17408
	ds_read_b128 v[184:187], v145 offset:19456
	ds_read_b128 v[192:195], v145 offset:21504
	ds_read_b128 v[200:203], v145 offset:23552
	s_add_u32 m0, s25, 0x0
	s_nop 0
	s_add_u32 vcc_lo, s28, s10
	s_addc_u32 vcc_hi, s29, s11
	global_load_lds_dwordx4 v136, vcc
	s_add_u32 m0, s25, 0x2000
	s_nop 0
	global_load_lds_dwordx4 v132, vcc
	s_waitcnt vmcnt(8)
	s_setprio 1
	s_barrier
	s_waitcnt lgkmcnt(0)
	v_mfma_f32_16x16x32_bf16 v[60:63], v[156:159], v[172:175], v[60:63]
	v_mfma_f32_16x16x32_bf16 v[56:59], v[164:167], v[172:175], v[56:59]
	v_mfma_f32_16x16x32_bf16 v[52:55], v[156:159], v[180:183], v[52:55]
	v_mfma_f32_16x16x32_bf16 v[48:51], v[164:167], v[180:183], v[48:51]
	v_mfma_f32_16x16x32_bf16 v[44:47], v[156:159], v[188:191], v[44:47]
	v_mfma_f32_16x16x32_bf16 v[40:43], v[164:167], v[188:191], v[40:43]
	v_mfma_f32_16x16x32_bf16 v[36:39], v[156:159], v[196:199], v[36:39]
	v_mfma_f32_16x16x32_bf16 v[32:35], v[164:167], v[196:199], v[32:35]
	v_mfma_f32_16x16x32_bf16 v[60:63], v[160:163], v[176:179], v[60:63]
	v_mfma_f32_16x16x32_bf16 v[56:59], v[168:171], v[176:179], v[56:59]
	v_mfma_f32_16x16x32_bf16 v[52:55], v[160:163], v[184:187], v[52:55]
	v_mfma_f32_16x16x32_bf16 v[48:51], v[168:171], v[184:187], v[48:51]
	v_mfma_f32_16x16x32_bf16 v[44:47], v[160:163], v[192:195], v[44:47]
	v_mfma_f32_16x16x32_bf16 v[40:43], v[168:171], v[192:195], v[40:43]
	v_mfma_f32_16x16x32_bf16 v[36:39], v[160:163], v[200:203], v[36:39]
	v_mfma_f32_16x16x32_bf16 v[32:35], v[168:171], v[200:203], v[32:35]
	s_barrier
	s_setprio 0
	ds_read_b128 v[156:159], v146 offset:32768
	ds_read_b128 v[160:163], v146 offset:33792
	ds_read_b128 v[164:167], v146 offset:34816
	ds_read_b128 v[168:171], v146 offset:35840
	s_add_u32 m0, s25, s45
	s_nop 0
	s_add_u32 vcc_lo, s28, s12
	s_addc_u32 vcc_hi, s29, s13
	global_load_lds_dwordx4 v134, vcc
	s_add_u32 m0, s25, s45
	s_add_u32 m0, m0, 0x2000
	s_nop 0
	global_load_lds_dwordx4 v130, vcc
	s_waitcnt vmcnt(6)
	s_setprio 1
	s_barrier
; #define WAIT_V(n) asm volatile("s_waitcnt vmcnt(" #n ")" ::: "memory")
; #define WAIT_L(n) asm volatile("s_waitcnt lgkmcnt(" #n ")" ::: "memory")
; #define BAR __builtin_amdgcn_s_barrier()
; #define SCHED __builtin_amdgcn_sched_barrier(0)
; #define STAGE(P, BASE, br, kt) do { const char* _g = (const char*)((BASE) + (size_t)(br) * GK + (kt) * BK); \
;     __builtin_amdgcn_global_load_lds((const unsigned*)(_g + voff0), (unsigned*)((char*)(P) + tx * 16), 16, 0, 0); \
;     __builtin_amdgcn_global_load_lds((const unsigned*)(_g + voff1), (unsigned*)((char*)(P) + tx * 16 + 8192), 16, 0, 0); } while (0)
; #define LDA(dst, b, h) _Pragma("unroll") for (int m = 0; m < 4; ++m) _Pragma("unroll") for (int k = 0; k < 2; ++k) \
;     dst[m][k] = *reinterpret_cast<const bf16x8*>((char*)shm + abase + (((b) * 2 + (h)) * 16384 + (m * 2 + k) * 1024))
; #define LDB(dst, b, h) _Pragma("unroll") for (int n = 0; n < 2; ++n) _Pragma("unroll") for (int k = 0; k < 2; ++k) \
;     dst[n][k] = *reinterpret_cast<const bf16x8*>((char*)shm + bbase + (((b) * 2 + (h)) * 16384 + (n * 2 + k) * 1024))
; template <bool SWAP>
; __device__ __forceinline__ void gemm_main(const u16* __restrict__ A, const u16* __restrict__ Bt, int brow, int bcol,
;                                           u16* shm, f32x4 (&acc)[2][2][4][2]) {
;     ...
;     WAIT_V(6); BAR; MMA(1, 1, At, B1); BAR;
;     LDB(B0, 1, 0); SCHED; LDA(At, 1, 0); STAGE(SA(0, 1), A, brow + HALF, t + 2);
;     WAIT_L(8); BAR; WAIT_L(0); MMA(0, 0, At, B0); BAR; SCHED;
;     LDB(B1, 1, 1); STAGE(SB(1, 0), Bt, bcol, t + 3);
;     BAR; WAIT_L(0); MMA(0, 1, At, B1); BAR;
;     LDA(At, 1, 1); STAGE(SA(1, 0), A, brow, t + 3);
;     BAR; WAIT_L(0); MMA(1, 0, At, B0); BAR; SCHED;
;     STAGE(SB(1, 1), Bt, bcol + HALF, t + 3);
;     WAIT_V(6); BAR; MMA(1, 1, At, B1); BAR;
	v_mfma_f32_16x16x32_bf16 v[28:31], v[204:207], v[172:175], v[28:31]
	v_mfma_f32_16x16x32_bf16 v[24:27], v[216:219], v[172:175], v[24:27]
	v_mfma_f32_16x16x32_bf16 v[20:23], v[204:207], v[180:183], v[20:23]
	v_mfma_f32_16x16x32_bf16 v[16:19], v[216:219], v[180:183], v[16:19]
	v_mfma_f32_16x16x32_bf16 v[12:15], v[204:207], v[188:191], v[12:15]
	v_mfma_f32_16x16x32_bf16 v[8:11], v[216:219], v[188:191], v[8:11]
	v_mfma_f32_16x16x32_bf16 v[4:7], v[204:207], v[196:199], v[4:7]
	v_mfma_f32_16x16x32_bf16 v[0:3], v[216:219], v[196:199], v[0:3]
	v_mfma_f32_16x16x32_bf16 v[28:31], v[212:215], v[176:179], v[28:31]
	ds_read_b128 v[172:175], v145 offset:32768
	v_mfma_f32_16x16x32_bf16 v[24:27], v[220:223], v[176:179], v[24:27]
	v_mfma_f32_16x16x32_bf16 v[20:23], v[212:215], v[184:187], v[20:23]
	ds_read_b128 v[180:183], v145 offset:34816
	v_mfma_f32_16x16x32_bf16 v[16:19], v[220:223], v[184:187], v[16:19]
	v_mfma_f32_16x16x32_bf16 v[12:15], v[212:215], v[192:195], v[12:15]
	ds_read_b128 v[188:191], v145 offset:36864
	v_mfma_f32_16x16x32_bf16 v[8:11], v[220:223], v[192:195], v[8:11]
	v_mfma_f32_16x16x32_bf16 v[4:7], v[212:215], v[200:203], v[4:7]
	ds_read_b128 v[196:199], v145 offset:38912
	v_mfma_f32_16x16x32_bf16 v[0:3], v[220:223], v[200:203], v[0:3]
	s_barrier
	s_setprio 0
	ds_read_b128 v[176:179], v145 offset:33792
	ds_read_b128 v[184:187], v145 offset:35840
	ds_read_b128 v[192:195], v145 offset:37888
	ds_read_b128 v[200:203], v145 offset:39936
	s_add_u32 m0, s25, 0x4000
	s_nop 0
	s_add_u32 vcc_lo, s28, s14
	s_addc_u32 vcc_hi, s29, s15
	global_load_lds_dwordx4 v136, vcc
	s_add_u32 m0, s25, 0x6000
	s_nop 0
	global_load_lds_dwordx4 v132, vcc
	s_waitcnt lgkmcnt(8)
	s_setprio 1
	s_barrier
	s_waitcnt lgkmcnt(0)
	v_mfma_f32_16x16x32_bf16 v[124:127], v[156:159], v[172:175], v[124:127]
	v_mfma_f32_16x16x32_bf16 v[120:123], v[164:167], v[172:175], v[120:123]
	v_mfma_f32_16x16x32_bf16 v[116:119], v[156:159], v[180:183], v[116:119]
	v_mfma_f32_16x16x32_bf16 v[112:115], v[164:167], v[180:183], v[112:115]
	v_mfma_f32_16x16x32_bf16 v[108:111], v[156:159], v[188:191], v[108:111]
	v_mfma_f32_16x16x32_bf16 v[104:107], v[164:167], v[188:191], v[104:107]
	v_mfma_f32_16x16x32_bf16 v[100:103], v[156:159], v[196:199], v[100:103]
	v_mfma_f32_16x16x32_bf16 v[96:99], v[164:167], v[196:199], v[96:99]
	v_mfma_f32_16x16x32_bf16 v[124:127], v[160:163], v[176:179], v[124:127]
	v_mfma_f32_16x16x32_bf16 v[120:123], v[168:171], v[176:179], v[120:123]
	v_mfma_f32_16x16x32_bf16 v[116:119], v[160:163], v[184:187], v[116:119]
	v_mfma_f32_16x16x32_bf16 v[112:115], v[168:171], v[184:187], v[112:115]
	v_mfma_f32_16x16x32_bf16 v[108:111], v[160:163], v[192:195], v[108:111]
	v_mfma_f32_16x16x32_bf16 v[104:107], v[168:171], v[192:195], v[104:107]
	v_mfma_f32_16x16x32_bf16 v[100:103], v[160:163], v[200:203], v[100:103]
	v_mfma_f32_16x16x32_bf16 v[96:99], v[168:171], v[200:203], v[96:99]
	s_barrier
	s_setprio 0
	ds_read_b128 v[204:207], v146 offset:49152
	ds_read_b128 v[212:215], v146 offset:50176
	ds_read_b128 v[216:219], v146 offset:51200
	ds_read_b128 v[220:223], v146 offset:52224
	s_add_u32 m0, s25, s52
	s_nop 0
	s_add_u32 vcc_lo, s28, s16
	s_addc_u32 vcc_hi, s29, s17
	global_load_lds_dwordx4 v134, vcc
	v_lshl_add_u64 v[230:231], v[228:229], 0, s[16:17]
	s_add_u32 m0, s25, s52
	s_add_u32 m0, m0, 0x2000
	s_nop 0
	global_load_lds_dwordx4 v130, vcc
	s_setprio 1
	s_barrier
	s_waitcnt lgkmcnt(0)
	v_mfma_f32_16x16x32_bf16 v[92:95], v[204:207], v[172:175], v[92:95]
	v_mfma_f32_16x16x32_bf16 v[88:91], v[216:219], v[172:175], v[88:91]
	v_mfma_f32_16x16x32_bf16 v[84:87], v[204:207], v[180:183], v[84:87]
	v_mfma_f32_16x16x32_bf16 v[80:83], v[216:219], v[180:183], v[80:83]
	v_mfma_f32_16x16x32_bf16 v[76:79], v[204:207], v[188:191], v[76:79]
	v_mfma_f32_16x16x32_bf16 v[72:75], v[216:219], v[188:191], v[72:75]
	v_mfma_f32_16x16x32_bf16 v[68:71], v[204:207], v[196:199], v[68:71]
	v_mfma_f32_16x16x32_bf16 v[64:67], v[216:219], v[196:199], v[64:67]
	v_mfma_f32_16x16x32_bf16 v[92:95], v[212:215], v[176:179], v[92:95]
	ds_read_b128 v[172:175], v145 offset:49152
	v_mfma_f32_16x16x32_bf16 v[88:91], v[220:223], v[176:179], v[88:91]
	v_mfma_f32_16x16x32_bf16 v[84:87], v[212:215], v[184:187], v[84:87]
	ds_read_b128 v[180:183], v145 offset:51200
	v_mfma_f32_16x16x32_bf16 v[80:83], v[220:223], v[184:187], v[80:83]
	v_mfma_f32_16x16x32_bf16 v[76:79], v[212:215], v[192:195], v[76:79]
	ds_read_b128 v[188:191], v145 offset:53248
	v_mfma_f32_16x16x32_bf16 v[72:75], v[220:223], v[192:195], v[72:75]
	v_mfma_f32_16x16x32_bf16 v[68:71], v[212:215], v[200:203], v[68:71]
	ds_read_b128 v[196:199], v145 offset:55296
	v_mfma_f32_16x16x32_bf16 v[64:67], v[220:223], v[200:203], v[64:67]
	s_barrier
	s_setprio 0
	ds_read_b128 v[176:179], v145 offset:50176
	ds_read_b128 v[184:187], v145 offset:52224
	ds_read_b128 v[192:195], v145 offset:54272
	ds_read_b128 v[200:203], v145 offset:56320
	s_add_u32 m0, s25, 0x8000
	s_nop 0
	s_add_u32 vcc_lo, s28, s18
	s_addc_u32 vcc_hi, s29, s19
	global_load_lds_dwordx4 v136, vcc
	v_lshl_add_u64 v[208:209], v[224:225], 0, s[18:19]
	s_add_u32 m0, s25, 0xa000
	s_nop 0
	global_load_lds_dwordx4 v132, vcc
	s_waitcnt vmcnt(8)
	s_setprio 1
	s_barrier
; #define WAIT_V(n) asm volatile("s_waitcnt vmcnt(" #n ")" ::: "memory")
; #define WAIT_L(n) asm volatile("s_waitcnt lgkmcnt(" #n ")" ::: "memory")
; #define BAR __builtin_amdgcn_s_barrier()
; #define SCHED __builtin_amdgcn_sched_barrier(0)
; #define STAGE(P, BASE, br, kt) do { const char* _g = (const char*)((BASE) + (size_t)(br) * GK + (kt) * BK); \
;     __builtin_amdgcn_global_load_lds((const unsigned*)(_g + voff0), (unsigned*)((char*)(P) + tx * 16), 16, 0, 0); \
;     __builtin_amdgcn_global_load_lds((const unsigned*)(_g + voff1), (unsigned*)((char*)(P) + tx * 16 + 8192), 16, 0, 0); } while (0)
; #define LDA(dst, b, h) _Pragma("unroll") for (int m = 0; m < 4; ++m) _Pragma("unroll") for (int k = 0; k < 2; ++k) \
;     dst[m][k] = *reinterpret_cast<const bf16x8*>((char*)shm + abase + (((b) * 2 + (h)) * 16384 + (m * 2 + k) * 1024))
; #define LDB(dst, b, h) _Pragma("unroll") for (int n = 0; n < 2; ++n) _Pragma("unroll") for (int k = 0; k < 2; ++k) \
;     dst[n][k] = *reinterpret_cast<const bf16x8*>((char*)shm + bbase + (((b) * 2 + (h)) * 16384 + (n * 2 + k) * 1024))
; template <bool SWAP>
; __device__ __forceinline__ void gemm_main(const u16* __restrict__ A, const u16* __restrict__ Bt, int brow, int bcol,
;                                           u16* shm, f32x4 (&acc)[2][2][4][2]) {
;     ...
;     LDA(At, 1, 1); STAGE(SA(1, 0), A, brow, t + 3);
;     BAR; WAIT_L(0); MMA(1, 0, At, B0); BAR; SCHED;
;     STAGE(SB(1, 1), Bt, bcol + HALF, t + 3);
;     WAIT_V(6); BAR; MMA(1, 1, At, B1); BAR;
;   }
;   { LDB(B0, 0, 0); LDA(At, 0, 0); STAGE(SA(1, 1), A, brow + HALF, nt - 1);
;     BAR; WAIT_L(0); MMA(0, 0, At, B0); BAR;
;     LDB(B1, 0, 1); BAR; WAIT_L(0); MMA(0, 1, At, B1); BAR;
;     LDA(At, 0, 1); WAIT_V(4); BAR; WAIT_L(0); MMA(1, 0, At, B0); MMA(1, 1, At, B1); BAR; }
;   { LDB(B0, 1, 0); LDA(At, 1, 0); WAIT_V(2); BAR; WAIT_L(0); MMA(0, 0, At, B0); BAR;
	s_waitcnt lgkmcnt(0)
	v_mfma_f32_16x16x32_bf16 v[60:63], v[156:159], v[172:175], v[60:63]
	v_mfma_f32_16x16x32_bf16 v[56:59], v[164:167], v[172:175], v[56:59]
	v_mfma_f32_16x16x32_bf16 v[52:55], v[156:159], v[180:183], v[52:55]
	v_mfma_f32_16x16x32_bf16 v[48:51], v[164:167], v[180:183], v[48:51]
	v_mfma_f32_16x16x32_bf16 v[44:47], v[156:159], v[188:191], v[44:47]
	v_mfma_f32_16x16x32_bf16 v[40:43], v[164:167], v[188:191], v[40:43]
	v_mfma_f32_16x16x32_bf16 v[36:39], v[156:159], v[196:199], v[36:39]
	v_mfma_f32_16x16x32_bf16 v[32:35], v[164:167], v[196:199], v[32:35]
	v_mfma_f32_16x16x32_bf16 v[60:63], v[160:163], v[176:179], v[60:63]
	v_mfma_f32_16x16x32_bf16 v[56:59], v[168:171], v[176:179], v[56:59]
	v_mfma_f32_16x16x32_bf16 v[52:55], v[160:163], v[184:187], v[52:55]
	v_mfma_f32_16x16x32_bf16 v[48:51], v[168:171], v[184:187], v[48:51]
	v_mfma_f32_16x16x32_bf16 v[44:47], v[160:163], v[192:195], v[44:47]
	v_mfma_f32_16x16x32_bf16 v[40:43], v[168:171], v[192:195], v[40:43]
	v_mfma_f32_16x16x32_bf16 v[36:39], v[160:163], v[200:203], v[36:39]
	v_mfma_f32_16x16x32_bf16 v[32:35], v[168:171], v[200:203], v[32:35]
	s_barrier
	s_setprio 0
	ds_read_b128 v[156:159], v146
	ds_read_b128 v[160:163], v146 offset:1024
	ds_read_b128 v[164:167], v146 offset:2048
	ds_read_b128 v[168:171], v146 offset:3072
	s_add_u32 m0, s25, s53
	s_nop 0
	s_add_u32 vcc_lo, s28, s20
	s_addc_u32 vcc_hi, s29, s21
	global_load_lds_dwordx4 v134, vcc
	v_lshl_add_u64 v[254:255], v[228:229], 0, s[20:21]
	s_add_u32 m0, s25, s53
	s_add_u32 m0, m0, 0x2000
	s_nop 0
	global_load_lds_dwordx4 v130, vcc
	s_waitcnt vmcnt(6)
	s_setprio 1
	s_barrier
	v_mfma_f32_16x16x32_bf16 v[28:31], v[204:207], v[172:175], v[28:31]
	v_mfma_f32_16x16x32_bf16 v[24:27], v[216:219], v[172:175], v[24:27]
	v_mfma_f32_16x16x32_bf16 v[20:23], v[204:207], v[180:183], v[20:23]
	v_mfma_f32_16x16x32_bf16 v[16:19], v[216:219], v[180:183], v[16:19]
	v_mfma_f32_16x16x32_bf16 v[12:15], v[204:207], v[188:191], v[12:15]
	v_mfma_f32_16x16x32_bf16 v[8:11], v[216:219], v[188:191], v[8:11]
	v_mfma_f32_16x16x32_bf16 v[4:7], v[204:207], v[196:199], v[4:7]
	v_mfma_f32_16x16x32_bf16 v[0:3], v[216:219], v[196:199], v[0:3]
	v_mfma_f32_16x16x32_bf16 v[28:31], v[212:215], v[176:179], v[28:31]
	ds_read_b128 v[172:175], v145
	v_mfma_f32_16x16x32_bf16 v[24:27], v[220:223], v[176:179], v[24:27]
	v_mfma_f32_16x16x32_bf16 v[20:23], v[212:215], v[184:187], v[20:23]
	ds_read_b128 v[180:183], v145 offset:2048
	v_mfma_f32_16x16x32_bf16 v[16:19], v[220:223], v[184:187], v[16:19]
	v_mfma_f32_16x16x32_bf16 v[12:15], v[212:215], v[192:195], v[12:15]
	ds_read_b128 v[188:191], v145 offset:4096
	v_mfma_f32_16x16x32_bf16 v[8:11], v[220:223], v[192:195], v[8:11]
	v_mfma_f32_16x16x32_bf16 v[4:7], v[212:215], v[200:203], v[4:7]
	ds_read_b128 v[196:199], v145 offset:6144
	v_mfma_f32_16x16x32_bf16 v[0:3], v[220:223], v[200:203], v[0:3]
	s_add_i32 s4, s4, 2
	s_add_u32 s28, s28, 0x100
	s_addc_u32 s29, s29, 0
	s_cmp_lt_u32 s4, 28
	s_barrier
	s_setprio 0
	s_cbranch_scc1 .LBB0_94
	v_lshlrev_b32_e32 v128, 3, v148
	v_lshlrev_b32_e32 v130, 5, v148
	v_and_b32_e32 v128, 0xffff0, v128
	v_and_b32_e32 v130, 32, v130
	s_or_b32 s28, s26, 0x80
	v_add_u32_e32 v130, v130, v150
	v_add_lshl_u32 v128, v149, v128, 12
	s_ashr_i32 s29, s28, 31
	v_lshl_add_u32 v128, v130, 1, v128
	v_lshlrev_b32_e32 v130, 3, v151
	v_lshlrev_b32_e32 v131, 5, v151
	s_lshl_b64 s[28:29], s[28:29], 12
	v_and_b32_e32 v130, 0xffff0, v130
	v_and_b32_e32 v131, 32, v131
	s_add_u32 s28, s37, s28
	v_add_u32_e32 v131, v131, v153
	v_add_lshl_u32 v130, v152, v130, 12
	s_addc_u32 s29, s38, s29
	v_lshl_add_u32 v152, v131, 1, v130
	v_mov_b32_e32 v153, v129
	v_lshl_add_u64 v[192:193], s[28:29], 0, v[128:129]
	v_readfirstlane_b32 s4, v154
	v_lshl_add_u64 v[192:193], v[192:193], 0, s[22:23]
	s_mov_b32 m0, s4
	v_lshl_add_u64 v[152:153], s[28:29], 0, v[152:153]
	v_readfirstlane_b32 s4, v155
	ds_read_b128 v[130:133], v146
	ds_read_b128 v[134:137], v146 offset:1024
	ds_read_b128 v[148:151], v146 offset:2048
	ds_read_b128 v[156:159], v146 offset:3072
	ds_read_b128 v[160:163], v145
	ds_read_b128 v[164:167], v145 offset:1024
	ds_read_b128 v[168:171], v145 offset:2048
	ds_read_b128 v[172:175], v145 offset:3072
	ds_read_b128 v[176:179], v145 offset:4096
	ds_read_b128 v[180:183], v145 offset:5120
	ds_read_b128 v[184:187], v145 offset:6144
	ds_read_b128 v[188:191], v145 offset:7168
	global_load_lds_dwordx4 v[192:193], off
	v_lshl_add_u64 v[152:153], v[152:153], 0, s[22:23]
	s_mov_b32 m0, s4
	s_nop 0
	global_load_lds_dwordx4 v[152:153], off
	s_barrier
	s_waitcnt lgkmcnt(0)
	s_setprio 1
	s_waitcnt lgkmcnt(0)
	v_mfma_f32_16x16x32_bf16 v[124:127], v[130:133], v[160:163], v[124:127]
	v_mfma_f32_16x16x32_bf16 v[116:119], v[130:133], v[168:171], v[116:119]
	v_mfma_f32_16x16x32_bf16 v[108:111], v[130:133], v[176:179], v[108:111]
	v_mfma_f32_16x16x32_bf16 v[100:103], v[130:133], v[184:187], v[100:103]
	v_mfma_f32_16x16x32_bf16 v[124:127], v[134:137], v[164:167], v[124:127]
	v_mfma_f32_16x16x32_bf16 v[120:123], v[148:151], v[160:163], v[120:123]
	v_mfma_f32_16x16x32_bf16 v[116:119], v[134:137], v[172:175], v[116:119]
	v_mfma_f32_16x16x32_bf16 v[112:115], v[148:151], v[168:171], v[112:115]
	v_mfma_f32_16x16x32_bf16 v[108:111], v[134:137], v[180:183], v[108:111]
	v_mfma_f32_16x16x32_bf16 v[104:107], v[148:151], v[176:179], v[104:107]
	v_mfma_f32_16x16x32_bf16 v[100:103], v[134:137], v[188:191], v[100:103]
	v_mfma_f32_16x16x32_bf16 v[96:99], v[148:151], v[184:187], v[96:99]
	v_mfma_f32_16x16x32_bf16 v[152:155], v[156:159], v[164:167], v[120:123]
	v_mfma_f32_16x16x32_bf16 v[192:195], v[156:159], v[172:175], v[112:115]
	v_mfma_f32_16x16x32_bf16 v[196:199], v[156:159], v[180:183], v[104:107]
	v_mfma_f32_16x16x32_bf16 v[200:203], v[156:159], v[188:191], v[96:99]
	s_setprio 0
	s_barrier
; #define WAIT_V(n) asm volatile("s_waitcnt vmcnt(" #n ")" ::: "memory")
; #define WAIT_L(n) asm volatile("s_waitcnt lgkmcnt(" #n ")" ::: "memory")
; #define BAR __builtin_amdgcn_s_barrier()
; #define LDA(dst, b, h) _Pragma("unroll") for (int m = 0; m < 4; ++m) _Pragma("unroll") for (int k = 0; k < 2; ++k) \
;     dst[m][k] = *reinterpret_cast<const bf16x8*>((char*)shm + abase + (((b) * 2 + (h)) * 16384 + (m * 2 + k) * 1024))
; #define LDB(dst, b, h) _Pragma("unroll") for (int n = 0; n < 2; ++n) _Pragma("unroll") for (int k = 0; k < 2; ++k) \
;     dst[n][k] = *reinterpret_cast<const bf16x8*>((char*)shm + bbase + (((b) * 2 + (h)) * 16384 + (n * 2 + k) * 1024))
; template <bool SWAP>
; __device__ __forceinline__ void gemm_main(const u16* __restrict__ A, const u16* __restrict__ Bt, int brow, int bcol,
;                                           u16* shm, f32x4 (&acc)[2][2][4][2]) {
;     ...
;     LDB(B1, 0, 1); BAR; WAIT_L(0); MMA(0, 1, At, B1); BAR;
;     LDA(At, 0, 1); WAIT_V(4); BAR; WAIT_L(0); MMA(1, 0, At, B0); MMA(1, 1, At, B1); BAR; }
;   { LDB(B0, 1, 0); LDA(At, 1, 0); WAIT_V(2); BAR; WAIT_L(0); MMA(0, 0, At, B0); BAR;
	s_nop 1
	ds_read_b128 v[96:99], v146 offset:16384
	ds_read_b128 v[104:107], v146 offset:17408
	ds_read_b128 v[112:115], v146 offset:18432
	ds_read_b128 v[120:123], v146 offset:19456
	s_barrier
	s_waitcnt lgkmcnt(0)
	s_setprio 1
	s_waitcnt lgkmcnt(0)
	v_mfma_f32_16x16x32_bf16 v[92:95], v[96:99], v[160:163], v[92:95]
	v_mfma_f32_16x16x32_bf16 v[84:87], v[96:99], v[168:171], v[84:87]
	v_mfma_f32_16x16x32_bf16 v[76:79], v[96:99], v[176:179], v[76:79]
	v_mfma_f32_16x16x32_bf16 v[68:71], v[96:99], v[184:187], v[68:71]
	v_mfma_f32_16x16x32_bf16 v[92:95], v[104:107], v[164:167], v[92:95]
	v_mfma_f32_16x16x32_bf16 v[88:91], v[112:115], v[160:163], v[88:91]
	v_mfma_f32_16x16x32_bf16 v[84:87], v[104:107], v[172:175], v[84:87]
	v_mfma_f32_16x16x32_bf16 v[80:83], v[112:115], v[168:171], v[80:83]
	v_mfma_f32_16x16x32_bf16 v[76:79], v[104:107], v[180:183], v[76:79]
	v_mfma_f32_16x16x32_bf16 v[72:75], v[112:115], v[176:179], v[72:75]
	v_mfma_f32_16x16x32_bf16 v[68:71], v[104:107], v[188:191], v[68:71]
	v_mfma_f32_16x16x32_bf16 v[64:67], v[112:115], v[184:187], v[64:67]
	v_mfma_f32_16x16x32_bf16 v[160:163], v[120:123], v[164:167], v[88:91]
	v_mfma_f32_16x16x32_bf16 v[164:167], v[120:123], v[172:175], v[80:83]
	v_mfma_f32_16x16x32_bf16 v[168:171], v[120:123], v[180:183], v[72:75]
	v_mfma_f32_16x16x32_bf16 v[172:175], v[120:123], v[188:191], v[64:67]
	s_setprio 0
	s_barrier
	s_nop 1
	ds_read_b128 v[64:67], v145 offset:16384
	ds_read_b128 v[72:75], v145 offset:17408
	ds_read_b128 v[80:83], v145 offset:18432
	ds_read_b128 v[88:91], v145 offset:19456
	ds_read_b128 v[176:179], v145 offset:20480
	ds_read_b128 v[180:183], v145 offset:21504
	ds_read_b128 v[184:187], v145 offset:22528
	ds_read_b128 v[188:191], v145 offset:23552
	s_waitcnt vmcnt(4)
	s_barrier
	s_waitcnt lgkmcnt(0)
	s_setprio 1
	s_waitcnt lgkmcnt(0)
	v_mfma_f32_16x16x32_bf16 v[60:63], v[130:133], v[64:67], v[60:63]
	v_mfma_f32_16x16x32_bf16 v[52:55], v[130:133], v[80:83], v[52:55]
	v_mfma_f32_16x16x32_bf16 v[44:47], v[130:133], v[176:179], v[44:47]
	v_mfma_f32_16x16x32_bf16 v[36:39], v[130:133], v[184:187], v[36:39]
	v_mfma_f32_16x16x32_bf16 v[60:63], v[134:137], v[72:75], v[60:63]
	v_mfma_f32_16x16x32_bf16 v[56:59], v[148:151], v[64:67], v[56:59]
	v_mfma_f32_16x16x32_bf16 v[52:55], v[134:137], v[88:91], v[52:55]
	v_mfma_f32_16x16x32_bf16 v[48:51], v[148:151], v[80:83], v[48:51]
	v_mfma_f32_16x16x32_bf16 v[44:47], v[134:137], v[180:183], v[44:47]
	v_mfma_f32_16x16x32_bf16 v[40:43], v[148:151], v[176:179], v[40:43]
	v_mfma_f32_16x16x32_bf16 v[36:39], v[134:137], v[188:191], v[36:39]
	v_mfma_f32_16x16x32_bf16 v[32:35], v[148:151], v[184:187], v[32:35]
	v_mfma_f32_16x16x32_bf16 v[204:207], v[156:159], v[72:75], v[56:59]
	v_mfma_f32_16x16x32_bf16 v[212:215], v[156:159], v[88:91], v[48:51]
	v_mfma_f32_16x16x32_bf16 v[216:219], v[156:159], v[180:183], v[40:43]
	v_mfma_f32_16x16x32_bf16 v[130:133], v[156:159], v[188:191], v[32:35]
	s_setprio 0
	s_setprio 1
	v_mfma_f32_16x16x32_bf16 v[28:31], v[96:99], v[64:67], v[28:31]
	v_mfma_f32_16x16x32_bf16 v[20:23], v[96:99], v[80:83], v[20:23]
	v_mfma_f32_16x16x32_bf16 v[12:15], v[96:99], v[176:179], v[12:15]
	v_mfma_f32_16x16x32_bf16 v[4:7], v[96:99], v[184:187], v[4:7]
	v_mfma_f32_16x16x32_bf16 v[28:31], v[104:107], v[72:75], v[28:31]
	v_mfma_f32_16x16x32_bf16 v[24:27], v[112:115], v[64:67], v[24:27]
	v_mfma_f32_16x16x32_bf16 v[20:23], v[104:107], v[88:91], v[20:23]
	v_mfma_f32_16x16x32_bf16 v[16:19], v[112:115], v[80:83], v[16:19]
	v_mfma_f32_16x16x32_bf16 v[12:15], v[104:107], v[180:183], v[12:15]
	v_mfma_f32_16x16x32_bf16 v[8:11], v[112:115], v[176:179], v[8:11]
	v_mfma_f32_16x16x32_bf16 v[4:7], v[104:107], v[188:191], v[4:7]
	v_mfma_f32_16x16x32_bf16 v[0:3], v[112:115], v[184:187], v[0:3]
	v_mfma_f32_16x16x32_bf16 v[134:137], v[120:123], v[72:75], v[24:27]
	v_mfma_f32_16x16x32_bf16 v[148:151], v[120:123], v[88:91], v[16:19]
	v_mfma_f32_16x16x32_bf16 v[156:159], v[120:123], v[180:183], v[8:11]
	v_mfma_f32_16x16x32_bf16 v[176:179], v[120:123], v[188:191], v[0:3]
	s_setprio 0
	s_barrier
	s_nop 1
	ds_read_b128 v[0:3], v146 offset:32768
	ds_read_b128 v[8:11], v146 offset:33792
	ds_read_b128 v[16:19], v146 offset:34816
	ds_read_b128 v[24:27], v146 offset:35840
	ds_read_b128 v[32:35], v145 offset:32768
	ds_read_b128 v[40:43], v145 offset:33792
	ds_read_b128 v[48:51], v145 offset:34816
	ds_read_b128 v[56:59], v145 offset:35840
	ds_read_b128 v[64:67], v145 offset:36864
	ds_read_b128 v[180:183], v145 offset:37888
	ds_read_b128 v[184:187], v145 offset:38912
	ds_read_b128 v[188:191], v145 offset:39936
	s_waitcnt vmcnt(2)
	s_barrier
; #define WAIT_V(n) asm volatile("s_waitcnt vmcnt(" #n ")" ::: "memory")
; #define WAIT_L(n) asm volatile("s_waitcnt lgkmcnt(" #n ")" ::: "memory")
; #define BAR __builtin_amdgcn_s_barrier()
; #define LDA(dst, b, h) _Pragma("unroll") for (int m = 0; m < 4; ++m) _Pragma("unroll") for (int k = 0; k < 2; ++k) \
;     dst[m][k] = *reinterpret_cast<const bf16x8*>((char*)shm + abase + (((b) * 2 + (h)) * 16384 + (m * 2 + k) * 1024))
; #define LDB(dst, b, h) _Pragma("unroll") for (int n = 0; n < 2; ++n) _Pragma("unroll") for (int k = 0; k < 2; ++k) \
;     dst[n][k] = *reinterpret_cast<const bf16x8*>((char*)shm + bbase + (((b) * 2 + (h)) * 16384 + (n * 2 + k) * 1024))
; template <bool SWAP>
; __device__ __forceinline__ void gemm_main(const u16* __restrict__ A, const u16* __restrict__ Bt, int brow, int bcol,
;                                           u16* shm, f32x4 (&acc)[2][2][4][2]) {
;     ...
;   { LDB(B0, 1, 0); LDA(At, 1, 0); WAIT_V(2); BAR; WAIT_L(0); MMA(0, 0, At, B0); BAR;
;     LDB(B1, 1, 1); WAIT_V(0); BAR; WAIT_L(0); MMA(0, 1, At, B1); BAR;
;     LDA(At, 1, 1); BAR; WAIT_L(0); MMA(1, 0, At, B0); MMA(1, 1, At, B1); BAR; }
;   if (wr == 0) BAR;
	s_waitcnt lgkmcnt(0)
	s_setprio 1
	s_waitcnt lgkmcnt(0)
	v_mfma_f32_16x16x32_bf16 v[72:75], v[0:3], v[32:35], v[124:127]
	v_mfma_f32_16x16x32_bf16 v[120:123], v[8:11], v[40:43], v[72:75]
	v_mfma_f32_16x16x32_bf16 v[72:75], v[16:19], v[32:35], v[152:155]
	v_mfma_f32_16x16x32_bf16 v[124:127], v[24:27], v[40:43], v[72:75]
	v_mfma_f32_16x16x32_bf16 v[72:75], v[0:3], v[48:51], v[116:119]
	v_mfma_f32_16x16x32_bf16 v[112:115], v[8:11], v[56:59], v[72:75]
	v_mfma_f32_16x16x32_bf16 v[72:75], v[16:19], v[48:51], v[192:195]
	v_mfma_f32_16x16x32_bf16 v[116:119], v[24:27], v[56:59], v[72:75]
	v_mfma_f32_16x16x32_bf16 v[72:75], v[0:3], v[64:67], v[108:111]
	v_mfma_f32_16x16x32_bf16 v[104:107], v[8:11], v[180:183], v[72:75]
	v_mfma_f32_16x16x32_bf16 v[72:75], v[16:19], v[64:67], v[196:199]
	v_mfma_f32_16x16x32_bf16 v[108:111], v[24:27], v[180:183], v[72:75]
	v_mfma_f32_16x16x32_bf16 v[72:75], v[0:3], v[184:187], v[100:103]
	v_mfma_f32_16x16x32_bf16 v[96:99], v[8:11], v[188:191], v[72:75]
	v_mfma_f32_16x16x32_bf16 v[72:75], v[16:19], v[184:187], v[200:203]
	v_mfma_f32_16x16x32_bf16 v[100:103], v[24:27], v[188:191], v[72:75]
	s_setprio 0
	s_barrier
	ds_read_b128 v[152:155], v146 offset:49152
	ds_read_b128 v[192:195], v146 offset:50176
	ds_read_b128 v[196:199], v146 offset:51200
	ds_read_b128 v[200:203], v146 offset:52224
	s_waitcnt vmcnt(0)
	s_barrier
	s_waitcnt lgkmcnt(0)
	s_setprio 1
	s_waitcnt lgkmcnt(0)
	v_mfma_f32_16x16x32_bf16 v[72:75], v[152:155], v[32:35], v[92:95]
	v_mfma_f32_16x16x32_bf16 v[32:35], v[196:199], v[32:35], v[160:163]
	v_mfma_f32_16x16x32_bf16 v[92:95], v[200:203], v[40:43], v[32:35]
	v_mfma_f32_16x16x32_bf16 v[32:35], v[152:155], v[48:51], v[84:87]
	v_mfma_f32_16x16x32_bf16 v[80:83], v[192:195], v[56:59], v[32:35]
	v_mfma_f32_16x16x32_bf16 v[32:35], v[196:199], v[48:51], v[164:167]
	v_mfma_f32_16x16x32_bf16 v[84:87], v[200:203], v[56:59], v[32:35]
	v_mfma_f32_16x16x32_bf16 v[32:35], v[152:155], v[64:67], v[76:79]
	v_mfma_f32_16x16x32_bf16 v[88:91], v[192:195], v[40:43], v[72:75]
	v_mfma_f32_16x16x32_bf16 v[72:75], v[192:195], v[180:183], v[32:35]
	v_mfma_f32_16x16x32_bf16 v[32:35], v[196:199], v[64:67], v[168:171]
	v_mfma_f32_16x16x32_bf16 v[76:79], v[200:203], v[180:183], v[32:35]
	v_mfma_f32_16x16x32_bf16 v[32:35], v[152:155], v[184:187], v[68:71]
	v_mfma_f32_16x16x32_bf16 v[64:67], v[192:195], v[188:191], v[32:35]
	v_mfma_f32_16x16x32_bf16 v[32:35], v[196:199], v[184:187], v[172:175]
	v_mfma_f32_16x16x32_bf16 v[68:71], v[200:203], v[188:191], v[32:35]
	s_setprio 0
	s_barrier
	ds_read_b128 v[160:163], v145 offset:49152
	ds_read_b128 v[164:167], v145 offset:50176
	ds_read_b128 v[168:171], v145 offset:51200
	ds_read_b128 v[172:175], v145 offset:52224
	ds_read_b128 v[180:183], v145 offset:53248
	ds_read_b128 v[184:187], v145 offset:54272
	ds_read_b128 v[188:191], v145 offset:55296
	ds_read_b128 v[220:223], v145 offset:56320
	s_barrier
	s_waitcnt lgkmcnt(0)
	s_setprio 1
	s_waitcnt lgkmcnt(0)
	v_mfma_f32_16x16x32_bf16 v[32:35], v[0:3], v[160:163], v[60:63]
	v_mfma_f32_16x16x32_bf16 v[56:59], v[8:11], v[164:167], v[32:35]
	v_mfma_f32_16x16x32_bf16 v[32:35], v[16:19], v[160:163], v[204:207]
	v_mfma_f32_16x16x32_bf16 v[60:63], v[24:27], v[164:167], v[32:35]
	v_mfma_f32_16x16x32_bf16 v[32:35], v[0:3], v[168:171], v[52:55]
	v_mfma_f32_16x16x32_bf16 v[48:51], v[8:11], v[172:175], v[32:35]
	v_mfma_f32_16x16x32_bf16 v[32:35], v[16:19], v[168:171], v[212:215]
	v_mfma_f32_16x16x32_bf16 v[52:55], v[24:27], v[172:175], v[32:35]
	v_mfma_f32_16x16x32_bf16 v[32:35], v[0:3], v[180:183], v[44:47]
	v_mfma_f32_16x16x32_bf16 v[40:43], v[8:11], v[184:187], v[32:35]
	v_mfma_f32_16x16x32_bf16 v[32:35], v[16:19], v[180:183], v[216:219]
	v_mfma_f32_16x16x32_bf16 v[0:3], v[0:3], v[188:191], v[36:39]
	v_mfma_f32_16x16x32_bf16 v[44:47], v[24:27], v[184:187], v[32:35]
	v_mfma_f32_16x16x32_bf16 v[32:35], v[8:11], v[220:223], v[0:3]
	v_mfma_f32_16x16x32_bf16 v[0:3], v[16:19], v[188:191], v[130:133]
	v_mfma_f32_16x16x32_bf16 v[36:39], v[24:27], v[220:223], v[0:3]
	s_setprio 0
	s_setprio 1
	v_mfma_f32_16x16x32_bf16 v[0:3], v[152:155], v[160:163], v[28:31]
	v_mfma_f32_16x16x32_bf16 v[24:27], v[192:195], v[164:167], v[0:3]
	v_mfma_f32_16x16x32_bf16 v[0:3], v[196:199], v[160:163], v[134:137]
	v_mfma_f32_16x16x32_bf16 v[28:31], v[200:203], v[164:167], v[0:3]
	v_mfma_f32_16x16x32_bf16 v[0:3], v[152:155], v[168:171], v[20:23]
	v_mfma_f32_16x16x32_bf16 v[16:19], v[192:195], v[172:175], v[0:3]
	v_mfma_f32_16x16x32_bf16 v[0:3], v[196:199], v[168:171], v[148:151]
	v_mfma_f32_16x16x32_bf16 v[20:23], v[200:203], v[172:175], v[0:3]
	v_mfma_f32_16x16x32_bf16 v[0:3], v[152:155], v[180:183], v[12:15]
	v_mfma_f32_16x16x32_bf16 v[8:11], v[192:195], v[184:187], v[0:3]
	v_mfma_f32_16x16x32_bf16 v[0:3], v[196:199], v[180:183], v[156:159]
	v_mfma_f32_16x16x32_bf16 v[12:15], v[200:203], v[184:187], v[0:3]
	v_mfma_f32_16x16x32_bf16 v[0:3], v[152:155], v[188:191], v[4:7]
	v_mfma_f32_16x16x32_bf16 v[4:7], v[196:199], v[188:191], v[176:179]
	v_mfma_f32_16x16x32_bf16 v[0:3], v[192:195], v[220:223], v[0:3]
	v_mfma_f32_16x16x32_bf16 v[4:7], v[200:203], v[220:223], v[4:7]
	s_setprio 0
	v_cmp_gt_u32_e32 vcc, s55, v144
	s_barrier
	s_and_saveexec_b64 s[28:29], vcc
	s_cbranch_execz .LBB0_97
	s_barrier

; #define WAIT_V(n) asm volatile("s_waitcnt vmcnt(" #n ")" ::: "memory")
; #define WAIT_L(n) asm volatile("s_waitcnt lgkmcnt(" #n ")" ::: "memory")
; #define BAR __builtin_amdgcn_s_barrier()
; #define SCHED __builtin_amdgcn_sched_barrier(0)
; #define STAGE(P, BASE, br, kt) do { const char* _g = (const char*)((BASE) + (size_t)(br) * GK + (kt) * BK); \
;     __builtin_amdgcn_global_load_lds((const unsigned*)(_g + voff0), (unsigned*)((char*)(P) + tx * 16), 16, 0, 0); \
;     __builtin_amdgcn_global_load_lds((const unsigned*)(_g + voff1), (unsigned*)((char*)(P) + tx * 16 + 8192), 16, 0, 0); } while (0)
; #define LDA(dst, b, h) _Pragma("unroll") for (int m = 0; m < 4; ++m) _Pragma("unroll") for (int k = 0; k < 2; ++k) \
;     dst[m][k] = *reinterpret_cast<const bf16x8*>((char*)shm + abase + (((b) * 2 + (h)) * 16384 + (m * 2 + k) * 1024))
; #define LDB(dst, b, h) _Pragma("unroll") for (int n = 0; n < 2; ++n) _Pragma("unroll") for (int k = 0; k < 2; ++k) \
;     dst[n][k] = *reinterpret_cast<const bf16x8*>((char*)shm + bbase + (((b) * 2 + (h)) * 16384 + (n * 2 + k) * 1024))
; template <bool SWAP>
; __device__ __forceinline__ void gemm_main(const u16* __restrict__ A, const u16* __restrict__ Bt, int brow, int bcol,
;                                           u16* shm, f32x4 (&acc)[2][2][4][2]) {
;     ...
;   for (int t = 0; t < nt - 2; t += 2) {
;     LDB(B0, 0, 0); SCHED; LDA(At, 0, 0); STAGE(SA(1, 1), A, brow + HALF, t + 1);
;     WAIT_L(8); BAR; WAIT_L(0); MMA(0, 0, At, B0); BAR; SCHED;
;     LDB(B1, 0, 1); STAGE(SB(0, 0), Bt, bcol, t + 2);
;     BAR; WAIT_L(0); MMA(0, 1, At, B1); BAR;
;     LDA(At, 0, 1); STAGE(SA(0, 0), A, brow, t + 2);
;     BAR; WAIT_L(0); MMA(1, 0, At, B0); BAR; SCHED;
;     STAGE(SB(0, 1), Bt, bcol + HALF, t + 2);
;     WAIT_V(6); BAR; MMA(1, 1, At, B1); BAR;
.LBB0_114:
	ds_read_b128 v[182:185], v137 offset:1024
	ds_read_b128 v[194:197], v137 offset:3072
	ds_read_b128 v[202:205], v137 offset:5120
	ds_read_b128 v[222:225], v137 offset:7168
	v_add_u32_e32 v192, 0, v153
	v_add_u32_e32 v160, 0xc000, v192
	v_add_u32_e32 v161, 0xe000, v192
	s_add_u32 m0, s4, 0xc000
	v_lshl_add_u64 v[242:243], s[0:1], 0, v[134:135]
	s_add_u32 vcc_lo, s0, s82
	s_addc_u32 vcc_hi, s1, s83
	global_load_lds_dwordx4 v132, vcc
	s_add_u32 m0, s4, 0xe000
	s_nop 0
	global_load_lds_dwordx4 v134, vcc
	s_waitcnt lgkmcnt(8)
	s_setprio 1
	s_barrier
	s_waitcnt lgkmcnt(0)
	v_mfma_f32_16x16x32_bf16 v[124:127], v[178:181], v[162:165], v[124:127]
	v_mfma_f32_16x16x32_bf16 v[120:123], v[178:181], v[170:173], v[120:123]
	v_mfma_f32_16x16x32_bf16 v[116:119], v[186:189], v[162:165], v[116:119]
	v_mfma_f32_16x16x32_bf16 v[112:115], v[186:189], v[170:173], v[112:115]
	v_mfma_f32_16x16x32_bf16 v[108:111], v[198:201], v[162:165], v[108:111]
	v_mfma_f32_16x16x32_bf16 v[104:107], v[198:201], v[170:173], v[104:107]
	v_mfma_f32_16x16x32_bf16 v[100:103], v[206:209], v[162:165], v[100:103]
	v_mfma_f32_16x16x32_bf16 v[96:99], v[206:209], v[170:173], v[96:99]
	v_mfma_f32_16x16x32_bf16 v[124:127], v[182:185], v[166:169], v[124:127]
	v_mfma_f32_16x16x32_bf16 v[120:123], v[182:185], v[174:177], v[120:123]
	v_mfma_f32_16x16x32_bf16 v[116:119], v[194:197], v[166:169], v[116:119]
	v_mfma_f32_16x16x32_bf16 v[112:115], v[194:197], v[174:177], v[112:115]
	v_mfma_f32_16x16x32_bf16 v[108:111], v[202:205], v[166:169], v[108:111]
	v_mfma_f32_16x16x32_bf16 v[104:107], v[202:205], v[174:177], v[104:107]
	v_mfma_f32_16x16x32_bf16 v[100:103], v[222:225], v[166:169], v[100:103]
	v_mfma_f32_16x16x32_bf16 v[96:99], v[222:225], v[174:177], v[96:99]
	s_barrier
	s_setprio 0
	ds_read_b128 v[226:229], v152 offset:16384
	ds_read_b128 v[230:233], v152 offset:17408
	ds_read_b128 v[234:237], v152 offset:18432
	ds_read_b128 v[238:241], v152 offset:19456
	v_lshl_add_u64 v[244:245], s[0:1], 0, v[128:129]
	s_add_u32 m0, s4, s28
	s_nop 0
	s_add_u32 vcc_lo, s0, s74
	s_addc_u32 vcc_hi, s1, s75
	global_load_lds_dwordx4 v128, vcc
	v_lshl_add_u64 v[246:247], s[0:1], 0, v[130:131]
	s_add_u32 m0, s4, s28
	s_add_u32 m0, m0, 0x2000
	s_nop 0
	global_load_lds_dwordx4 v130, vcc
	s_setprio 1
	s_barrier
	s_waitcnt lgkmcnt(0)
	v_mfma_f32_16x16x32_bf16 v[92:95], v[178:181], v[226:229], v[92:95]
	v_mfma_f32_16x16x32_bf16 v[88:91], v[178:181], v[234:237], v[88:91]
	v_mfma_f32_16x16x32_bf16 v[84:87], v[186:189], v[226:229], v[84:87]
	v_mfma_f32_16x16x32_bf16 v[80:83], v[186:189], v[234:237], v[80:83]
	v_mfma_f32_16x16x32_bf16 v[76:79], v[198:201], v[226:229], v[76:79]
	v_mfma_f32_16x16x32_bf16 v[72:75], v[198:201], v[234:237], v[72:75]
	v_mfma_f32_16x16x32_bf16 v[68:71], v[206:209], v[226:229], v[68:71]
	v_mfma_f32_16x16x32_bf16 v[64:67], v[206:209], v[234:237], v[64:67]
	v_mfma_f32_16x16x32_bf16 v[92:95], v[182:185], v[230:233], v[92:95]
	ds_read_b128 v[178:181], v137 offset:16384
	v_mfma_f32_16x16x32_bf16 v[88:91], v[182:185], v[238:241], v[88:91]
	v_mfma_f32_16x16x32_bf16 v[84:87], v[194:197], v[230:233], v[84:87]
	ds_read_b128 v[186:189], v137 offset:18432
	v_mfma_f32_16x16x32_bf16 v[80:83], v[194:197], v[238:241], v[80:83]
	v_mfma_f32_16x16x32_bf16 v[76:79], v[202:205], v[230:233], v[76:79]
	ds_read_b128 v[198:201], v137 offset:20480
	v_mfma_f32_16x16x32_bf16 v[72:75], v[202:205], v[238:241], v[72:75]
	v_mfma_f32_16x16x32_bf16 v[68:71], v[222:225], v[230:233], v[68:71]
	ds_read_b128 v[206:209], v137 offset:22528
	v_mfma_f32_16x16x32_bf16 v[64:67], v[222:225], v[238:241], v[64:67]
	s_barrier
	s_setprio 0
	ds_read_b128 v[182:185], v137 offset:17408
	ds_read_b128 v[194:197], v137 offset:19456
	ds_read_b128 v[202:205], v137 offset:21504
	ds_read_b128 v[222:225], v137 offset:23552
	s_add_u32 m0, s4, 0x0
	s_nop 0
	s_add_u32 vcc_lo, s0, s76
	s_addc_u32 vcc_hi, s1, s77
	global_load_lds_dwordx4 v132, vcc
	s_add_u32 m0, s4, 0x2000
	s_nop 0
	global_load_lds_dwordx4 v134, vcc
	s_waitcnt vmcnt(8)
	s_setprio 1
	s_barrier
	s_waitcnt lgkmcnt(0)
	v_mfma_f32_16x16x32_bf16 v[60:63], v[178:181], v[162:165], v[60:63]
	v_mfma_f32_16x16x32_bf16 v[56:59], v[178:181], v[170:173], v[56:59]
	v_mfma_f32_16x16x32_bf16 v[52:55], v[186:189], v[162:165], v[52:55]
	v_mfma_f32_16x16x32_bf16 v[48:51], v[186:189], v[170:173], v[48:51]
	v_mfma_f32_16x16x32_bf16 v[44:47], v[198:201], v[162:165], v[44:47]
	v_mfma_f32_16x16x32_bf16 v[40:43], v[198:201], v[170:173], v[40:43]
	v_mfma_f32_16x16x32_bf16 v[36:39], v[206:209], v[162:165], v[36:39]
	v_mfma_f32_16x16x32_bf16 v[32:35], v[206:209], v[170:173], v[32:35]
	v_mfma_f32_16x16x32_bf16 v[60:63], v[182:185], v[166:169], v[60:63]
	v_mfma_f32_16x16x32_bf16 v[56:59], v[182:185], v[174:177], v[56:59]
	v_mfma_f32_16x16x32_bf16 v[52:55], v[194:197], v[166:169], v[52:55]
	v_mfma_f32_16x16x32_bf16 v[48:51], v[194:197], v[174:177], v[48:51]
	v_mfma_f32_16x16x32_bf16 v[44:47], v[202:205], v[166:169], v[44:47]
	v_mfma_f32_16x16x32_bf16 v[40:43], v[202:205], v[174:177], v[40:43]
	v_mfma_f32_16x16x32_bf16 v[36:39], v[222:225], v[166:169], v[36:39]
	v_mfma_f32_16x16x32_bf16 v[32:35], v[222:225], v[174:177], v[32:35]
	s_barrier
	s_setprio 0
	ds_read_b128 v[162:165], v152 offset:32768
	ds_read_b128 v[166:169], v152 offset:33792
	ds_read_b128 v[170:173], v152 offset:34816
	ds_read_b128 v[174:177], v152 offset:35840
	s_add_u32 m0, s4, s29
	s_nop 0
	s_add_u32 vcc_lo, s0, s70
	s_addc_u32 vcc_hi, s1, s71
	global_load_lds_dwordx4 v128, vcc
	s_add_u32 m0, s4, s29
	s_add_u32 m0, m0, 0x2000
	s_nop 0
	global_load_lds_dwordx4 v130, vcc
	s_waitcnt vmcnt(6)
	s_setprio 1
	s_barrier
; #define WAIT_V(n) asm volatile("s_waitcnt vmcnt(" #n ")" ::: "memory")
; #define WAIT_L(n) asm volatile("s_waitcnt lgkmcnt(" #n ")" ::: "memory")
; #define BAR __builtin_amdgcn_s_barrier()
; #define SCHED __builtin_amdgcn_sched_barrier(0)
; #define STAGE(P, BASE, br, kt) do { const char* _g = (const char*)((BASE) + (size_t)(br) * GK + (kt) * BK); \
;     __builtin_amdgcn_global_load_lds((const unsigned*)(_g + voff0), (unsigned*)((char*)(P) + tx * 16), 16, 0, 0); \
;     __builtin_amdgcn_global_load_lds((const unsigned*)(_g + voff1), (unsigned*)((char*)(P) + tx * 16 + 8192), 16, 0, 0); } while (0)
; #define LDA(dst, b, h) _Pragma("unroll") for (int m = 0; m < 4; ++m) _Pragma("unroll") for (int k = 0; k < 2; ++k) \
;     dst[m][k] = *reinterpret_cast<const bf16x8*>((char*)shm + abase + (((b) * 2 + (h)) * 16384 + (m * 2 + k) * 1024))
; #define LDB(dst, b, h) _Pragma("unroll") for (int n = 0; n < 2; ++n) _Pragma("unroll") for (int k = 0; k < 2; ++k) \
;     dst[n][k] = *reinterpret_cast<const bf16x8*>((char*)shm + bbase + (((b) * 2 + (h)) * 16384 + (n * 2 + k) * 1024))
; template <bool SWAP>
; __device__ __forceinline__ void gemm_main(const u16* __restrict__ A, const u16* __restrict__ Bt, int brow, int bcol,
;                                           u16* shm, f32x4 (&acc)[2][2][4][2]) {
;     ...
;     WAIT_V(6); BAR; MMA(1, 1, At, B1); BAR;
;     LDB(B0, 1, 0); SCHED; LDA(At, 1, 0); STAGE(SA(0, 1), A, brow + HALF, t + 2);
;     WAIT_L(8); BAR; WAIT_L(0); MMA(0, 0, At, B0); BAR; SCHED;
;     LDB(B1, 1, 1); STAGE(SB(1, 0), Bt, bcol, t + 3);
;     BAR; WAIT_L(0); MMA(0, 1, At, B1); BAR;
;     LDA(At, 1, 1); STAGE(SA(1, 0), A, brow, t + 3);
	v_mfma_f32_16x16x32_bf16 v[28:31], v[178:181], v[226:229], v[28:31]
	v_mfma_f32_16x16x32_bf16 v[24:27], v[178:181], v[234:237], v[24:27]
	v_mfma_f32_16x16x32_bf16 v[20:23], v[186:189], v[226:229], v[20:23]
	v_mfma_f32_16x16x32_bf16 v[16:19], v[186:189], v[234:237], v[16:19]
	v_mfma_f32_16x16x32_bf16 v[12:15], v[198:201], v[226:229], v[12:15]
	v_mfma_f32_16x16x32_bf16 v[8:11], v[198:201], v[234:237], v[8:11]
	v_mfma_f32_16x16x32_bf16 v[4:7], v[206:209], v[226:229], v[4:7]
	v_mfma_f32_16x16x32_bf16 v[0:3], v[206:209], v[234:237], v[0:3]
	v_mfma_f32_16x16x32_bf16 v[28:31], v[182:185], v[230:233], v[28:31]
	ds_read_b128 v[178:181], v137 offset:32768
	v_mfma_f32_16x16x32_bf16 v[24:27], v[182:185], v[238:241], v[24:27]
	v_mfma_f32_16x16x32_bf16 v[20:23], v[194:197], v[230:233], v[20:23]
	ds_read_b128 v[186:189], v137 offset:34816
	v_mfma_f32_16x16x32_bf16 v[16:19], v[194:197], v[238:241], v[16:19]
	v_mfma_f32_16x16x32_bf16 v[12:15], v[202:205], v[230:233], v[12:15]
	ds_read_b128 v[198:201], v137 offset:36864
	v_mfma_f32_16x16x32_bf16 v[8:11], v[202:205], v[238:241], v[8:11]
	v_mfma_f32_16x16x32_bf16 v[4:7], v[222:225], v[230:233], v[4:7]
	ds_read_b128 v[206:209], v137 offset:38912
	v_mfma_f32_16x16x32_bf16 v[0:3], v[222:225], v[238:241], v[0:3]
	s_barrier
	s_setprio 0
	ds_read_b128 v[182:185], v137 offset:33792
	ds_read_b128 v[194:197], v137 offset:35840
	ds_read_b128 v[202:205], v137 offset:37888
	ds_read_b128 v[222:225], v137 offset:39936
	s_add_u32 m0, s4, 0x4000
	s_nop 0
	s_add_u32 vcc_lo, s0, s96
	s_addc_u32 vcc_hi, s1, s97
	global_load_lds_dwordx4 v132, vcc
	s_add_u32 m0, s4, 0x6000
	s_nop 0
	global_load_lds_dwordx4 v134, vcc
	s_waitcnt lgkmcnt(8)
	s_setprio 1
	s_barrier
	s_waitcnt lgkmcnt(0)
	v_mfma_f32_16x16x32_bf16 v[124:127], v[178:181], v[162:165], v[124:127]
	v_mfma_f32_16x16x32_bf16 v[120:123], v[178:181], v[170:173], v[120:123]
	v_mfma_f32_16x16x32_bf16 v[116:119], v[186:189], v[162:165], v[116:119]
	v_mfma_f32_16x16x32_bf16 v[112:115], v[186:189], v[170:173], v[112:115]
	v_mfma_f32_16x16x32_bf16 v[108:111], v[198:201], v[162:165], v[108:111]
	v_mfma_f32_16x16x32_bf16 v[104:107], v[198:201], v[170:173], v[104:107]
	v_mfma_f32_16x16x32_bf16 v[100:103], v[206:209], v[162:165], v[100:103]
	v_mfma_f32_16x16x32_bf16 v[96:99], v[206:209], v[170:173], v[96:99]
	v_mfma_f32_16x16x32_bf16 v[124:127], v[182:185], v[166:169], v[124:127]
	v_mfma_f32_16x16x32_bf16 v[120:123], v[182:185], v[174:177], v[120:123]
	v_mfma_f32_16x16x32_bf16 v[116:119], v[194:197], v[166:169], v[116:119]
	v_mfma_f32_16x16x32_bf16 v[112:115], v[194:197], v[174:177], v[112:115]
	v_mfma_f32_16x16x32_bf16 v[108:111], v[202:205], v[166:169], v[108:111]
	v_mfma_f32_16x16x32_bf16 v[104:107], v[202:205], v[174:177], v[104:107]
	v_mfma_f32_16x16x32_bf16 v[100:103], v[222:225], v[166:169], v[100:103]
	v_mfma_f32_16x16x32_bf16 v[96:99], v[222:225], v[174:177], v[96:99]
	s_barrier
	s_setprio 0
	ds_read_b128 v[226:229], v152 offset:49152
	ds_read_b128 v[230:233], v152 offset:50176
	ds_read_b128 v[234:237], v152 offset:51200
	ds_read_b128 v[238:241], v152 offset:52224
	v_add_u32_e32 v250, s30, v153
	v_add_u32_e32 v250, 0x2000, v250
	s_add_u32 m0, s4, s30
	s_nop 0
	s_add_u32 vcc_lo, s0, s34
	s_addc_u32 vcc_hi, s1, s35
	global_load_lds_dwordx4 v128, vcc
	v_lshl_add_u64 v[248:249], v[246:247], 0, s[34:35]
	s_add_u32 m0, s4, s30
	s_add_u32 m0, m0, 0x2000
	s_nop 0
	global_load_lds_dwordx4 v130, vcc
	s_setprio 1
	s_barrier
	s_waitcnt lgkmcnt(0)
	v_mfma_f32_16x16x32_bf16 v[92:95], v[178:181], v[226:229], v[92:95]
	v_mfma_f32_16x16x32_bf16 v[88:91], v[178:181], v[234:237], v[88:91]
	v_mfma_f32_16x16x32_bf16 v[84:87], v[186:189], v[226:229], v[84:87]
	v_mfma_f32_16x16x32_bf16 v[80:83], v[186:189], v[234:237], v[80:83]
	v_mfma_f32_16x16x32_bf16 v[76:79], v[198:201], v[226:229], v[76:79]
	v_mfma_f32_16x16x32_bf16 v[72:75], v[198:201], v[234:237], v[72:75]
	v_mfma_f32_16x16x32_bf16 v[68:71], v[206:209], v[226:229], v[68:71]
	v_mfma_f32_16x16x32_bf16 v[64:67], v[206:209], v[234:237], v[64:67]
	v_mfma_f32_16x16x32_bf16 v[92:95], v[182:185], v[230:233], v[92:95]
	ds_read_b128 v[178:181], v137 offset:49152
	v_mfma_f32_16x16x32_bf16 v[88:91], v[182:185], v[238:241], v[88:91]
	v_mfma_f32_16x16x32_bf16 v[84:87], v[194:197], v[230:233], v[84:87]
	ds_read_b128 v[186:189], v137 offset:51200
	v_mfma_f32_16x16x32_bf16 v[80:83], v[194:197], v[238:241], v[80:83]
	v_mfma_f32_16x16x32_bf16 v[76:79], v[202:205], v[230:233], v[76:79]
	ds_read_b128 v[198:201], v137 offset:53248
	v_mfma_f32_16x16x32_bf16 v[72:75], v[202:205], v[238:241], v[72:75]
	v_mfma_f32_16x16x32_bf16 v[68:71], v[222:225], v[230:233], v[68:71]
	ds_read_b128 v[206:209], v137 offset:55296
	v_mfma_f32_16x16x32_bf16 v[64:67], v[222:225], v[238:241], v[64:67]
	s_barrier
	s_setprio 0
	ds_read_b128 v[182:185], v137 offset:50176
	ds_read_b128 v[194:197], v137 offset:52224
	ds_read_b128 v[202:205], v137 offset:54272
	ds_read_b128 v[222:225], v137 offset:56320
	v_add_u32_e32 v248, 0x8000, v192
	s_add_u32 m0, s4, 0x8000
	s_nop 0
	s_add_u32 vcc_lo, s0, s36
	s_addc_u32 vcc_hi, s1, s37
	global_load_lds_dwordx4 v132, vcc
	s_add_u32 m0, s4, 0xa000
	s_nop 0
	global_load_lds_dwordx4 v134, vcc
	s_waitcnt vmcnt(8)
	s_setprio 1
	s_barrier
; #define WAIT_V(n) asm volatile("s_waitcnt vmcnt(" #n ")" ::: "memory")
; #define WAIT_L(n) asm volatile("s_waitcnt lgkmcnt(" #n ")" ::: "memory")
; #define BAR __builtin_amdgcn_s_barrier()
; #define SCHED __builtin_amdgcn_sched_barrier(0)
; #define STAGE(P, BASE, br, kt) do { const char* _g = (const char*)((BASE) + (size_t)(br) * GK + (kt) * BK); \
;     __builtin_amdgcn_global_load_lds((const unsigned*)(_g + voff0), (unsigned*)((char*)(P) + tx * 16), 16, 0, 0); \
;     __builtin_amdgcn_global_load_lds((const unsigned*)(_g + voff1), (unsigned*)((char*)(P) + tx * 16 + 8192), 16, 0, 0); } while (0)
; #define LDA(dst, b, h) _Pragma("unroll") for (int m = 0; m < 4; ++m) _Pragma("unroll") for (int k = 0; k < 2; ++k) \
;     dst[m][k] = *reinterpret_cast<const bf16x8*>((char*)shm + abase + (((b) * 2 + (h)) * 16384 + (m * 2 + k) * 1024))
; #define LDB(dst, b, h) _Pragma("unroll") for (int n = 0; n < 2; ++n) _Pragma("unroll") for (int k = 0; k < 2; ++k) \
;     dst[n][k] = *reinterpret_cast<const bf16x8*>((char*)shm + bbase + (((b) * 2 + (h)) * 16384 + (n * 2 + k) * 1024))
; template <bool SWAP>
; __device__ __forceinline__ void gemm_main(const u16* __restrict__ A, const u16* __restrict__ Bt, int brow, int bcol,
;                                           u16* shm, f32x4 (&acc)[2][2][4][2]) {
;     ...
;     BAR; WAIT_L(0); MMA(1, 0, At, B0); BAR; SCHED;
;     STAGE(SB(1, 1), Bt, bcol + HALF, t + 3);
;     WAIT_V(6); BAR; MMA(1, 1, At, B1); BAR;
;   }
;   { LDB(B0, 0, 0); LDA(At, 0, 0); STAGE(SA(1, 1), A, brow + HALF, nt - 1);
;     BAR; WAIT_L(0); MMA(0, 0, At, B0); BAR;
	s_waitcnt lgkmcnt(0)
	v_mfma_f32_16x16x32_bf16 v[60:63], v[178:181], v[162:165], v[60:63]
	v_mfma_f32_16x16x32_bf16 v[56:59], v[178:181], v[170:173], v[56:59]
	v_mfma_f32_16x16x32_bf16 v[52:55], v[186:189], v[162:165], v[52:55]
	v_mfma_f32_16x16x32_bf16 v[48:51], v[186:189], v[170:173], v[48:51]
	v_mfma_f32_16x16x32_bf16 v[44:47], v[198:201], v[162:165], v[44:47]
	v_mfma_f32_16x16x32_bf16 v[40:43], v[198:201], v[170:173], v[40:43]
	v_mfma_f32_16x16x32_bf16 v[36:39], v[206:209], v[162:165], v[36:39]
	v_mfma_f32_16x16x32_bf16 v[32:35], v[206:209], v[170:173], v[32:35]
	v_mfma_f32_16x16x32_bf16 v[60:63], v[182:185], v[166:169], v[60:63]
	v_mfma_f32_16x16x32_bf16 v[56:59], v[182:185], v[174:177], v[56:59]
	v_mfma_f32_16x16x32_bf16 v[52:55], v[194:197], v[166:169], v[52:55]
	v_mfma_f32_16x16x32_bf16 v[48:51], v[194:197], v[174:177], v[48:51]
	v_mfma_f32_16x16x32_bf16 v[44:47], v[202:205], v[166:169], v[44:47]
	v_mfma_f32_16x16x32_bf16 v[40:43], v[202:205], v[174:177], v[40:43]
	v_mfma_f32_16x16x32_bf16 v[36:39], v[222:225], v[166:169], v[36:39]
	v_mfma_f32_16x16x32_bf16 v[32:35], v[222:225], v[174:177], v[32:35]
	s_barrier
	s_setprio 0
	ds_read_b128 v[162:165], v152
	ds_read_b128 v[166:169], v152 offset:1024
	ds_read_b128 v[170:173], v152 offset:2048
	ds_read_b128 v[174:177], v152 offset:3072
	s_add_u32 m0, s4, s31
	s_nop 0
	s_add_u32 vcc_lo, s0, s64
	s_addc_u32 vcc_hi, s1, s65
	global_load_lds_dwordx4 v128, vcc
	v_lshl_add_u64 v[254:255], v[246:247], 0, s[64:65]
	s_add_u32 m0, s4, s31
	s_add_u32 m0, m0, 0x2000
	s_nop 0
	global_load_lds_dwordx4 v130, vcc
	s_waitcnt vmcnt(6)
	s_setprio 1
	s_barrier
	v_mfma_f32_16x16x32_bf16 v[28:31], v[178:181], v[226:229], v[28:31]
	v_mfma_f32_16x16x32_bf16 v[24:27], v[178:181], v[234:237], v[24:27]
	v_mfma_f32_16x16x32_bf16 v[20:23], v[186:189], v[226:229], v[20:23]
	v_mfma_f32_16x16x32_bf16 v[16:19], v[186:189], v[234:237], v[16:19]
	v_mfma_f32_16x16x32_bf16 v[12:15], v[198:201], v[226:229], v[12:15]
	v_mfma_f32_16x16x32_bf16 v[8:11], v[198:201], v[234:237], v[8:11]
	v_mfma_f32_16x16x32_bf16 v[4:7], v[206:209], v[226:229], v[4:7]
	v_mfma_f32_16x16x32_bf16 v[0:3], v[206:209], v[234:237], v[0:3]
	v_mfma_f32_16x16x32_bf16 v[28:31], v[182:185], v[230:233], v[28:31]
	ds_read_b128 v[178:181], v137
	v_mfma_f32_16x16x32_bf16 v[24:27], v[182:185], v[238:241], v[24:27]
	v_mfma_f32_16x16x32_bf16 v[20:23], v[194:197], v[230:233], v[20:23]
	ds_read_b128 v[186:189], v137 offset:2048
	v_mfma_f32_16x16x32_bf16 v[16:19], v[194:197], v[238:241], v[16:19]
	v_mfma_f32_16x16x32_bf16 v[12:15], v[202:205], v[230:233], v[12:15]
	ds_read_b128 v[198:201], v137 offset:4096
	v_mfma_f32_16x16x32_bf16 v[8:11], v[202:205], v[238:241], v[8:11]
	v_mfma_f32_16x16x32_bf16 v[4:7], v[222:225], v[230:233], v[4:7]
	ds_read_b128 v[206:209], v137 offset:6144
	v_mfma_f32_16x16x32_bf16 v[0:3], v[222:225], v[238:241], v[0:3]
	s_add_i32 s3, s3, 2
	s_add_u32 s0, s0, 0x100
	s_addc_u32 s1, s1, 0
	s_cmp_lt_u32 s3, 28
	s_barrier
	s_setprio 0
	s_cbranch_scc1 .LBB0_114
	v_lshlrev_b32_e32 v128, 3, v154
	v_lshlrev_b32_e32 v129, 5, v154
	v_and_b32_e32 v128, 0xffff0, v128
	v_and_b32_e32 v129, 32, v129
	s_or_b32 s0, s24, 0x80
	v_add_u32_e32 v129, v129, v156
	v_add_lshl_u32 v128, v155, v128, 12
	s_ashr_i32 s1, s0, 31
	v_lshl_add_u32 v192, v129, 1, v128
	v_lshlrev_b32_e32 v128, 3, v157
	v_lshlrev_b32_e32 v129, 5, v157
	s_mov_b32 s22, s0
	s_lshl_b64 s[0:1], s[0:1], 12
	v_readlane_b32 s4, v253, 35
	v_and_b32_e32 v128, 0xffff0, v128
	v_and_b32_e32 v129, 32, v129
	v_readlane_b32 s5, v253, 36
	s_add_u32 s0, s4, s0
	v_add_u32_e32 v129, v129, v159
	v_add_lshl_u32 v128, v158, v128, 12
	s_addc_u32 s1, s5, s1
	v_lshl_add_u32 v158, v129, 1, v128
	v_mov_b32_e32 v159, v193
	v_lshl_add_u64 v[190:191], s[0:1], 0, v[192:193]
	s_mov_b64 s[4:5], 0xf80
	v_readfirstlane_b32 s3, v160
	v_lshl_add_u64 v[190:191], v[190:191], 0, s[4:5]
	s_mov_b32 m0, s3
	v_lshl_add_u64 v[158:159], s[0:1], 0, v[158:159]
	v_readfirstlane_b32 s0, v161
	ds_read_b128 v[128:131], v152
	ds_read_b128 v[132:135], v152 offset:1024
	ds_read_b128 v[154:157], v152 offset:2048
	ds_read_b128 v[162:165], v152 offset:3072
	ds_read_b128 v[166:169], v137
	ds_read_b128 v[170:173], v137 offset:1024
	ds_read_b128 v[174:177], v137 offset:2048
	ds_read_b128 v[178:181], v137 offset:3072
	ds_read_b128 v[182:185], v137 offset:4096
	ds_read_b128 v[186:189], v137 offset:5120
	ds_read_b128 v[194:197], v137 offset:6144
	ds_read_b128 v[198:201], v137 offset:7168
	global_load_lds_dwordx4 v[190:191], off
	v_lshl_add_u64 v[158:159], v[158:159], 0, s[4:5]
	s_mov_b32 m0, s0
	s_nop 0
	global_load_lds_dwordx4 v[158:159], off
	s_barrier
	s_waitcnt lgkmcnt(0)
	s_setprio 1
	s_waitcnt lgkmcnt(0)
	v_mfma_f32_16x16x32_bf16 v[124:127], v[166:169], v[128:131], v[124:127]
	v_mfma_f32_16x16x32_bf16 v[120:123], v[166:169], v[154:157], v[120:123]
	v_mfma_f32_16x16x32_bf16 v[116:119], v[174:177], v[128:131], v[116:119]
	v_mfma_f32_16x16x32_bf16 v[112:115], v[174:177], v[154:157], v[112:115]
	v_mfma_f32_16x16x32_bf16 v[108:111], v[182:185], v[128:131], v[108:111]
	v_mfma_f32_16x16x32_bf16 v[104:107], v[182:185], v[154:157], v[104:107]
	v_mfma_f32_16x16x32_bf16 v[100:103], v[194:197], v[128:131], v[100:103]
	v_mfma_f32_16x16x32_bf16 v[96:99], v[194:197], v[154:157], v[96:99]
	v_mfma_f32_16x16x32_bf16 v[124:127], v[170:173], v[132:135], v[124:127]
	v_mfma_f32_16x16x32_bf16 v[120:123], v[170:173], v[162:165], v[120:123]
	v_mfma_f32_16x16x32_bf16 v[116:119], v[178:181], v[132:135], v[116:119]
	v_mfma_f32_16x16x32_bf16 v[112:115], v[178:181], v[162:165], v[112:115]
	v_mfma_f32_16x16x32_bf16 v[108:111], v[186:189], v[132:135], v[108:111]
	v_mfma_f32_16x16x32_bf16 v[104:107], v[186:189], v[162:165], v[104:107]
	v_mfma_f32_16x16x32_bf16 v[100:103], v[198:201], v[132:135], v[100:103]
	v_mfma_f32_16x16x32_bf16 v[96:99], v[198:201], v[162:165], v[96:99]
	s_setprio 0
	s_barrier
; #define WAIT_V(n) asm volatile("s_waitcnt vmcnt(" #n ")" ::: "memory")
; #define WAIT_L(n) asm volatile("s_waitcnt lgkmcnt(" #n ")" ::: "memory")
; #define BAR __builtin_amdgcn_s_barrier()
; #define LDA(dst, b, h) _Pragma("unroll") for (int m = 0; m < 4; ++m) _Pragma("unroll") for (int k = 0; k < 2; ++k) \
;     dst[m][k] = *reinterpret_cast<const bf16x8*>((char*)shm + abase + (((b) * 2 + (h)) * 16384 + (m * 2 + k) * 1024))
; #define LDB(dst, b, h) _Pragma("unroll") for (int n = 0; n < 2; ++n) _Pragma("unroll") for (int k = 0; k < 2; ++k) \
;     dst[n][k] = *reinterpret_cast<const bf16x8*>((char*)shm + bbase + (((b) * 2 + (h)) * 16384 + (n * 2 + k) * 1024))
; template <bool SWAP>
; __device__ __forceinline__ void gemm_main(const u16* __restrict__ A, const u16* __restrict__ Bt, int brow, int bcol,
;                                           u16* shm, f32x4 (&acc)[2][2][4][2]) {
;     ...
;     LDB(B1, 0, 1); BAR; WAIT_L(0); MMA(0, 1, At, B1); BAR;
;     LDA(At, 0, 1); WAIT_V(4); BAR; WAIT_L(0); MMA(1, 0, At, B0); MMA(1, 1, At, B1); BAR; }
;   { LDB(B0, 1, 0); LDA(At, 1, 0); WAIT_V(2); BAR; WAIT_L(0); MMA(0, 0, At, B0); BAR;
	ds_read_b128 v[158:161], v152 offset:16384
	ds_read_b128 v[202:205], v152 offset:17408
	ds_read_b128 v[206:209], v152 offset:18432
	ds_read_b128 v[222:225], v152 offset:19456
	s_barrier
	s_waitcnt lgkmcnt(0)
	s_setprio 1
	s_waitcnt lgkmcnt(0)
	v_mfma_f32_16x16x32_bf16 v[92:95], v[166:169], v[158:161], v[92:95]
	v_mfma_f32_16x16x32_bf16 v[88:91], v[166:169], v[206:209], v[88:91]
	v_mfma_f32_16x16x32_bf16 v[84:87], v[174:177], v[158:161], v[84:87]
	v_mfma_f32_16x16x32_bf16 v[80:83], v[174:177], v[206:209], v[80:83]
	v_mfma_f32_16x16x32_bf16 v[76:79], v[182:185], v[158:161], v[76:79]
	v_mfma_f32_16x16x32_bf16 v[72:75], v[182:185], v[206:209], v[72:75]
	v_mfma_f32_16x16x32_bf16 v[68:71], v[194:197], v[158:161], v[68:71]
	v_mfma_f32_16x16x32_bf16 v[64:67], v[194:197], v[206:209], v[64:67]
	v_mfma_f32_16x16x32_bf16 v[92:95], v[170:173], v[202:205], v[92:95]
	v_mfma_f32_16x16x32_bf16 v[88:91], v[170:173], v[222:225], v[88:91]
	v_mfma_f32_16x16x32_bf16 v[84:87], v[178:181], v[202:205], v[84:87]
	v_mfma_f32_16x16x32_bf16 v[80:83], v[178:181], v[222:225], v[80:83]
	v_mfma_f32_16x16x32_bf16 v[76:79], v[186:189], v[202:205], v[76:79]
	v_mfma_f32_16x16x32_bf16 v[72:75], v[186:189], v[222:225], v[72:75]
	v_mfma_f32_16x16x32_bf16 v[68:71], v[198:201], v[202:205], v[68:71]
	v_mfma_f32_16x16x32_bf16 v[64:67], v[198:201], v[222:225], v[64:67]
	s_setprio 0
	s_barrier
	ds_read_b128 v[166:169], v137 offset:16384
	ds_read_b128 v[170:173], v137 offset:17408
	ds_read_b128 v[174:177], v137 offset:18432
	ds_read_b128 v[178:181], v137 offset:19456
	ds_read_b128 v[182:185], v137 offset:20480
	ds_read_b128 v[186:189], v137 offset:21504
	ds_read_b128 v[194:197], v137 offset:22528
	ds_read_b128 v[198:201], v137 offset:23552
	s_waitcnt vmcnt(4)
	s_barrier
	s_waitcnt lgkmcnt(0)
	s_setprio 1
	s_waitcnt lgkmcnt(0)
	v_mfma_f32_16x16x32_bf16 v[60:63], v[166:169], v[128:131], v[60:63]
	v_mfma_f32_16x16x32_bf16 v[56:59], v[166:169], v[154:157], v[56:59]
	v_mfma_f32_16x16x32_bf16 v[52:55], v[174:177], v[128:131], v[52:55]
	v_mfma_f32_16x16x32_bf16 v[48:51], v[174:177], v[154:157], v[48:51]
	v_mfma_f32_16x16x32_bf16 v[44:47], v[182:185], v[128:131], v[44:47]
	v_mfma_f32_16x16x32_bf16 v[40:43], v[182:185], v[154:157], v[40:43]
	v_mfma_f32_16x16x32_bf16 v[36:39], v[194:197], v[128:131], v[36:39]
	v_mfma_f32_16x16x32_bf16 v[32:35], v[194:197], v[154:157], v[32:35]
	v_mfma_f32_16x16x32_bf16 v[60:63], v[170:173], v[132:135], v[60:63]
	v_mfma_f32_16x16x32_bf16 v[56:59], v[170:173], v[162:165], v[56:59]
	v_mfma_f32_16x16x32_bf16 v[52:55], v[178:181], v[132:135], v[52:55]
	v_mfma_f32_16x16x32_bf16 v[48:51], v[178:181], v[162:165], v[48:51]
	v_mfma_f32_16x16x32_bf16 v[44:47], v[186:189], v[132:135], v[44:47]
	v_mfma_f32_16x16x32_bf16 v[40:43], v[186:189], v[162:165], v[40:43]
	v_mfma_f32_16x16x32_bf16 v[36:39], v[198:201], v[132:135], v[36:39]
	v_mfma_f32_16x16x32_bf16 v[32:35], v[198:201], v[162:165], v[32:35]
	s_setprio 0
	s_setprio 1
	v_mfma_f32_16x16x32_bf16 v[28:31], v[166:169], v[158:161], v[28:31]
	v_mfma_f32_16x16x32_bf16 v[24:27], v[166:169], v[206:209], v[24:27]
	v_mfma_f32_16x16x32_bf16 v[20:23], v[174:177], v[158:161], v[20:23]
	v_mfma_f32_16x16x32_bf16 v[16:19], v[174:177], v[206:209], v[16:19]
	v_mfma_f32_16x16x32_bf16 v[12:15], v[182:185], v[158:161], v[12:15]
	v_mfma_f32_16x16x32_bf16 v[8:11], v[182:185], v[206:209], v[8:11]
	v_mfma_f32_16x16x32_bf16 v[4:7], v[194:197], v[158:161], v[4:7]
	v_mfma_f32_16x16x32_bf16 v[0:3], v[194:197], v[206:209], v[0:3]
	v_mfma_f32_16x16x32_bf16 v[28:31], v[170:173], v[202:205], v[28:31]
	v_mfma_f32_16x16x32_bf16 v[24:27], v[170:173], v[222:225], v[24:27]
	v_mfma_f32_16x16x32_bf16 v[20:23], v[178:181], v[202:205], v[20:23]
	v_mfma_f32_16x16x32_bf16 v[16:19], v[178:181], v[222:225], v[16:19]
	v_mfma_f32_16x16x32_bf16 v[12:15], v[186:189], v[202:205], v[12:15]
	v_mfma_f32_16x16x32_bf16 v[8:11], v[186:189], v[222:225], v[8:11]
	v_mfma_f32_16x16x32_bf16 v[4:7], v[198:201], v[202:205], v[4:7]
	v_mfma_f32_16x16x32_bf16 v[0:3], v[198:201], v[222:225], v[0:3]
	s_setprio 0
	s_barrier
	ds_read_b128 v[128:131], v152 offset:32768
	ds_read_b128 v[132:135], v152 offset:33792
	ds_read_b128 v[154:157], v152 offset:34816
	ds_read_b128 v[158:161], v152 offset:35840
	ds_read_b128 v[162:165], v137 offset:32768
	ds_read_b128 v[166:169], v137 offset:33792
	ds_read_b128 v[170:173], v137 offset:34816
	ds_read_b128 v[174:177], v137 offset:35840
	ds_read_b128 v[178:181], v137 offset:36864
	ds_read_b128 v[182:185], v137 offset:37888
	ds_read_b128 v[186:189], v137 offset:38912
	ds_read_b128 v[194:197], v137 offset:39936
	s_waitcnt vmcnt(2)
	s_barrier
; #define WAIT_V(n) asm volatile("s_waitcnt vmcnt(" #n ")" ::: "memory")
; #define WAIT_L(n) asm volatile("s_waitcnt lgkmcnt(" #n ")" ::: "memory")
; #define BAR __builtin_amdgcn_s_barrier()
; #define LDA(dst, b, h) _Pragma("unroll") for (int m = 0; m < 4; ++m) _Pragma("unroll") for (int k = 0; k < 2; ++k) \
;     dst[m][k] = *reinterpret_cast<const bf16x8*>((char*)shm + abase + (((b) * 2 + (h)) * 16384 + (m * 2 + k) * 1024))
; #define LDB(dst, b, h) _Pragma("unroll") for (int n = 0; n < 2; ++n) _Pragma("unroll") for (int k = 0; k < 2; ++k) \
;     dst[n][k] = *reinterpret_cast<const bf16x8*>((char*)shm + bbase + (((b) * 2 + (h)) * 16384 + (n * 2 + k) * 1024))
; template <bool SWAP>
; __device__ __forceinline__ void gemm_main(const u16* __restrict__ A, const u16* __restrict__ Bt, int brow, int bcol,
;                                           u16* shm, f32x4 (&acc)[2][2][4][2]) {
;     ...
;   { LDB(B0, 1, 0); LDA(At, 1, 0); WAIT_V(2); BAR; WAIT_L(0); MMA(0, 0, At, B0); BAR;
;     LDB(B1, 1, 1); WAIT_V(0); BAR; WAIT_L(0); MMA(0, 1, At, B1); BAR;
;     LDA(At, 1, 1); BAR; WAIT_L(0); MMA(1, 0, At, B0); MMA(1, 1, At, B1); BAR; }
;   if (wr == 0) BAR;
; __device__ __forceinline__ void phase_inproj1(const Params& p, char* smem) {
;     ...
;       if (nt < 16) {
	s_waitcnt lgkmcnt(0)
	s_setprio 1
	s_waitcnt lgkmcnt(0)
	v_mfma_f32_16x16x32_bf16 v[124:127], v[162:165], v[128:131], v[124:127]
	v_mfma_f32_16x16x32_bf16 v[120:123], v[162:165], v[154:157], v[120:123]
	v_mfma_f32_16x16x32_bf16 v[116:119], v[170:173], v[128:131], v[116:119]
	v_mfma_f32_16x16x32_bf16 v[112:115], v[170:173], v[154:157], v[112:115]
	v_mfma_f32_16x16x32_bf16 v[108:111], v[178:181], v[128:131], v[108:111]
	v_mfma_f32_16x16x32_bf16 v[104:107], v[178:181], v[154:157], v[104:107]
	v_mfma_f32_16x16x32_bf16 v[100:103], v[186:189], v[128:131], v[100:103]
	v_mfma_f32_16x16x32_bf16 v[96:99], v[186:189], v[154:157], v[96:99]
	v_mfma_f32_16x16x32_bf16 v[124:127], v[166:169], v[132:135], v[124:127]
	v_mfma_f32_16x16x32_bf16 v[120:123], v[166:169], v[158:161], v[120:123]
	v_mfma_f32_16x16x32_bf16 v[116:119], v[174:177], v[132:135], v[116:119]
	v_mfma_f32_16x16x32_bf16 v[112:115], v[174:177], v[158:161], v[112:115]
	v_mfma_f32_16x16x32_bf16 v[108:111], v[182:185], v[132:135], v[108:111]
	v_mfma_f32_16x16x32_bf16 v[104:107], v[182:185], v[158:161], v[104:107]
	v_mfma_f32_16x16x32_bf16 v[100:103], v[194:197], v[132:135], v[100:103]
	v_mfma_f32_16x16x32_bf16 v[96:99], v[194:197], v[158:161], v[96:99]
	s_setprio 0
	s_barrier
	ds_read_b128 v[198:201], v152 offset:49152
	ds_read_b128 v[202:205], v152 offset:50176
	ds_read_b128 v[206:209], v152 offset:51200
	ds_read_b128 v[222:225], v152 offset:52224
	s_waitcnt vmcnt(0)
	s_barrier
	s_waitcnt lgkmcnt(0)
	s_setprio 1
	s_waitcnt lgkmcnt(0)
	v_mfma_f32_16x16x32_bf16 v[92:95], v[162:165], v[198:201], v[92:95]
	v_mfma_f32_16x16x32_bf16 v[88:91], v[162:165], v[206:209], v[88:91]
	v_mfma_f32_16x16x32_bf16 v[84:87], v[170:173], v[198:201], v[84:87]
	v_mfma_f32_16x16x32_bf16 v[80:83], v[170:173], v[206:209], v[80:83]
	v_mfma_f32_16x16x32_bf16 v[76:79], v[178:181], v[198:201], v[76:79]
	v_mfma_f32_16x16x32_bf16 v[72:75], v[178:181], v[206:209], v[72:75]
	v_mfma_f32_16x16x32_bf16 v[68:71], v[186:189], v[198:201], v[68:71]
	v_mfma_f32_16x16x32_bf16 v[64:67], v[186:189], v[206:209], v[64:67]
	v_mfma_f32_16x16x32_bf16 v[92:95], v[166:169], v[202:205], v[92:95]
	v_mfma_f32_16x16x32_bf16 v[88:91], v[166:169], v[222:225], v[88:91]
	v_mfma_f32_16x16x32_bf16 v[84:87], v[174:177], v[202:205], v[84:87]
	v_mfma_f32_16x16x32_bf16 v[80:83], v[174:177], v[222:225], v[80:83]
	v_mfma_f32_16x16x32_bf16 v[76:79], v[182:185], v[202:205], v[76:79]
	v_mfma_f32_16x16x32_bf16 v[72:75], v[182:185], v[222:225], v[72:75]
	v_mfma_f32_16x16x32_bf16 v[68:71], v[194:197], v[202:205], v[68:71]
	v_mfma_f32_16x16x32_bf16 v[64:67], v[194:197], v[222:225], v[64:67]
	s_setprio 0
	s_barrier
	ds_read_b128 v[162:165], v137 offset:49152
	ds_read_b128 v[166:169], v137 offset:50176
	ds_read_b128 v[170:173], v137 offset:51200
	ds_read_b128 v[174:177], v137 offset:52224
	ds_read_b128 v[178:181], v137 offset:53248
	ds_read_b128 v[182:185], v137 offset:54272
	ds_read_b128 v[186:189], v137 offset:55296
	ds_read_b128 v[194:197], v137 offset:56320
	s_barrier
	s_waitcnt lgkmcnt(0)
	s_setprio 1
	s_waitcnt lgkmcnt(0)
	v_mfma_f32_16x16x32_bf16 v[60:63], v[162:165], v[128:131], v[60:63]
	v_mfma_f32_16x16x32_bf16 v[56:59], v[162:165], v[154:157], v[56:59]
	v_mfma_f32_16x16x32_bf16 v[52:55], v[170:173], v[128:131], v[52:55]
	v_mfma_f32_16x16x32_bf16 v[48:51], v[170:173], v[154:157], v[48:51]
	v_mfma_f32_16x16x32_bf16 v[44:47], v[178:181], v[128:131], v[44:47]
	v_mfma_f32_16x16x32_bf16 v[40:43], v[178:181], v[154:157], v[40:43]
	v_mfma_f32_16x16x32_bf16 v[36:39], v[186:189], v[128:131], v[36:39]
	v_mfma_f32_16x16x32_bf16 v[32:35], v[186:189], v[154:157], v[32:35]
	v_mfma_f32_16x16x32_bf16 v[60:63], v[166:169], v[132:135], v[60:63]
	v_mfma_f32_16x16x32_bf16 v[56:59], v[166:169], v[158:161], v[56:59]
	v_mfma_f32_16x16x32_bf16 v[52:55], v[174:177], v[132:135], v[52:55]
	v_mfma_f32_16x16x32_bf16 v[48:51], v[174:177], v[158:161], v[48:51]
	v_mfma_f32_16x16x32_bf16 v[44:47], v[182:185], v[132:135], v[44:47]
	v_mfma_f32_16x16x32_bf16 v[40:43], v[182:185], v[158:161], v[40:43]
	v_mfma_f32_16x16x32_bf16 v[36:39], v[194:197], v[132:135], v[36:39]
	v_mfma_f32_16x16x32_bf16 v[32:35], v[194:197], v[158:161], v[32:35]
	s_setprio 0
	s_setprio 1
	v_mfma_f32_16x16x32_bf16 v[28:31], v[162:165], v[198:201], v[28:31]
	v_mfma_f32_16x16x32_bf16 v[24:27], v[162:165], v[206:209], v[24:27]
	v_mfma_f32_16x16x32_bf16 v[20:23], v[170:173], v[198:201], v[20:23]
	v_mfma_f32_16x16x32_bf16 v[16:19], v[170:173], v[206:209], v[16:19]
	v_mfma_f32_16x16x32_bf16 v[12:15], v[178:181], v[198:201], v[12:15]
	v_mfma_f32_16x16x32_bf16 v[8:11], v[178:181], v[206:209], v[8:11]
	v_mfma_f32_16x16x32_bf16 v[4:7], v[186:189], v[198:201], v[4:7]
	v_mfma_f32_16x16x32_bf16 v[0:3], v[186:189], v[206:209], v[0:3]
	v_mfma_f32_16x16x32_bf16 v[28:31], v[166:169], v[202:205], v[28:31]
	v_mfma_f32_16x16x32_bf16 v[24:27], v[166:169], v[222:225], v[24:27]
	v_mfma_f32_16x16x32_bf16 v[20:23], v[174:177], v[202:205], v[20:23]
	v_mfma_f32_16x16x32_bf16 v[16:19], v[174:177], v[222:225], v[16:19]
	v_mfma_f32_16x16x32_bf16 v[12:15], v[182:185], v[202:205], v[12:15]
	v_mfma_f32_16x16x32_bf16 v[8:11], v[182:185], v[222:225], v[8:11]
	v_mfma_f32_16x16x32_bf16 v[4:7], v[194:197], v[202:205], v[4:7]
	v_mfma_f32_16x16x32_bf16 v[0:3], v[194:197], v[222:225], v[0:3]
	s_setprio 0
	s_movk_i32 s0, 0x100
	v_cmp_gt_u32_e32 vcc, s0, v136
	s_barrier
	s_and_saveexec_b64 s[0:1], vcc
	s_cbranch_execz .LBB0_118
	s_barrier
	s_or_b64 exec, exec, s[0:1]
	s_cmp_gt_u32 s2, 15
	s_mov_b64 s[0:1], -1
	s_cbranch_scc1 .LBB0_119

; #define WAIT_V(n) asm volatile("s_waitcnt vmcnt(" #n ")" ::: "memory")
; #define WAIT_L(n) asm volatile("s_waitcnt lgkmcnt(" #n ")" ::: "memory")
; #define BAR __builtin_amdgcn_s_barrier()
; #define SCHED __builtin_amdgcn_sched_barrier(0)
; #define STAGE(P, BASE, br, kt) do { const char* _g = (const char*)((BASE) + (size_t)(br) * GK + (kt) * BK); \
;     __builtin_amdgcn_global_load_lds((const unsigned*)(_g + voff0), (unsigned*)((char*)(P) + tx * 16), 16, 0, 0); \
;     __builtin_amdgcn_global_load_lds((const unsigned*)(_g + voff1), (unsigned*)((char*)(P) + tx * 16 + 8192), 16, 0, 0); } while (0)
; #define LDA(dst, b, h) _Pragma("unroll") for (int m = 0; m < 4; ++m) _Pragma("unroll") for (int k = 0; k < 2; ++k) \
;     dst[m][k] = *reinterpret_cast<const bf16x8*>((char*)shm + abase + (((b) * 2 + (h)) * 16384 + (m * 2 + k) * 1024))
; #define LDB(dst, b, h) _Pragma("unroll") for (int n = 0; n < 2; ++n) _Pragma("unroll") for (int k = 0; k < 2; ++k) \
;     dst[n][k] = *reinterpret_cast<const bf16x8*>((char*)shm + bbase + (((b) * 2 + (h)) * 16384 + (n * 2 + k) * 1024))
; template <bool SWAP>
; __device__ __forceinline__ void gemm_main(const u16* __restrict__ A, const u16* __restrict__ Bt, int brow, int bcol,
;                                           u16* shm, f32x4 (&acc)[2][2][4][2]) {
;     ...
;     LDB(B0, 0, 0); SCHED; LDA(At, 0, 0); STAGE(SA(1, 1), A, brow + HALF, t + 1);
;     WAIT_L(8); BAR; WAIT_L(0); MMA(0, 0, At, B0); BAR; SCHED;
;     LDB(B1, 0, 1); STAGE(SB(0, 0), Bt, bcol, t + 2);
;     BAR; WAIT_L(0); MMA(0, 1, At, B1); BAR;
;     LDA(At, 0, 1); STAGE(SA(0, 0), A, brow, t + 2);
;     BAR; WAIT_L(0); MMA(1, 0, At, B0); BAR; SCHED;
;     STAGE(SB(0, 1), Bt, bcol + HALF, t + 2);
;     WAIT_V(6); BAR; MMA(1, 1, At, B1); BAR;
;     LDB(B0, 1, 0); SCHED; LDA(At, 1, 0); STAGE(SA(0, 1), A, brow + HALF, t + 2);
.LBB0_200:
	ds_read_b128 v[182:185], v137 offset:1024
	ds_read_b128 v[194:197], v137 offset:3072
	ds_read_b128 v[202:205], v137 offset:5120
	ds_read_b128 v[222:225], v137 offset:7168
	v_add_u32_e32 v192, 0, v153
	v_add_u32_e32 v160, 0xc000, v192
	v_add_u32_e32 v161, 0xe000, v192
	s_add_u32 m0, s3, 0xc000
	v_lshl_add_u64 v[242:243], s[0:1], 0, v[134:135]
	s_add_u32 vcc_lo, s0, s82
	s_addc_u32 vcc_hi, s1, s83
	global_load_lds_dwordx4 v132, vcc
	s_add_u32 m0, s3, 0xe000
	s_nop 0
	global_load_lds_dwordx4 v134, vcc
	s_waitcnt lgkmcnt(8)
	s_setprio 1
	s_barrier
	s_waitcnt lgkmcnt(0)
	v_mfma_f32_16x16x32_bf16 v[124:127], v[162:165], v[178:181], v[124:127]
	v_mfma_f32_16x16x32_bf16 v[120:123], v[170:173], v[178:181], v[120:123]
	v_mfma_f32_16x16x32_bf16 v[116:119], v[162:165], v[186:189], v[116:119]
	v_mfma_f32_16x16x32_bf16 v[112:115], v[170:173], v[186:189], v[112:115]
	v_mfma_f32_16x16x32_bf16 v[108:111], v[162:165], v[198:201], v[108:111]
	v_mfma_f32_16x16x32_bf16 v[104:107], v[170:173], v[198:201], v[104:107]
	v_mfma_f32_16x16x32_bf16 v[100:103], v[162:165], v[206:209], v[100:103]
	v_mfma_f32_16x16x32_bf16 v[96:99], v[170:173], v[206:209], v[96:99]
	v_mfma_f32_16x16x32_bf16 v[124:127], v[166:169], v[182:185], v[124:127]
	v_mfma_f32_16x16x32_bf16 v[120:123], v[174:177], v[182:185], v[120:123]
	v_mfma_f32_16x16x32_bf16 v[116:119], v[166:169], v[194:197], v[116:119]
	v_mfma_f32_16x16x32_bf16 v[112:115], v[174:177], v[194:197], v[112:115]
	v_mfma_f32_16x16x32_bf16 v[108:111], v[166:169], v[202:205], v[108:111]
	v_mfma_f32_16x16x32_bf16 v[104:107], v[174:177], v[202:205], v[104:107]
	v_mfma_f32_16x16x32_bf16 v[100:103], v[166:169], v[222:225], v[100:103]
	v_mfma_f32_16x16x32_bf16 v[96:99], v[174:177], v[222:225], v[96:99]
	s_barrier
	s_setprio 0
	ds_read_b128 v[226:229], v152 offset:16384
	ds_read_b128 v[230:233], v152 offset:17408
	ds_read_b128 v[234:237], v152 offset:18432
	ds_read_b128 v[238:241], v152 offset:19456
	v_lshl_add_u64 v[244:245], s[0:1], 0, v[128:129]
	s_add_u32 m0, s3, s28
	s_nop 0
	s_add_u32 vcc_lo, s0, s74
	s_addc_u32 vcc_hi, s1, s75
	global_load_lds_dwordx4 v128, vcc
	v_lshl_add_u64 v[246:247], s[0:1], 0, v[130:131]
	s_add_u32 m0, s3, s28
	s_add_u32 m0, m0, 0x2000
	s_nop 0
	global_load_lds_dwordx4 v130, vcc
	s_setprio 1
	s_barrier
	s_waitcnt lgkmcnt(0)
	v_mfma_f32_16x16x32_bf16 v[92:95], v[226:229], v[178:181], v[92:95]
	v_mfma_f32_16x16x32_bf16 v[88:91], v[234:237], v[178:181], v[88:91]
	v_mfma_f32_16x16x32_bf16 v[84:87], v[226:229], v[186:189], v[84:87]
	v_mfma_f32_16x16x32_bf16 v[80:83], v[234:237], v[186:189], v[80:83]
	v_mfma_f32_16x16x32_bf16 v[76:79], v[226:229], v[198:201], v[76:79]
	v_mfma_f32_16x16x32_bf16 v[72:75], v[234:237], v[198:201], v[72:75]
	v_mfma_f32_16x16x32_bf16 v[68:71], v[226:229], v[206:209], v[68:71]
	v_mfma_f32_16x16x32_bf16 v[64:67], v[234:237], v[206:209], v[64:67]
	v_mfma_f32_16x16x32_bf16 v[92:95], v[230:233], v[182:185], v[92:95]
	ds_read_b128 v[178:181], v137 offset:16384
	v_mfma_f32_16x16x32_bf16 v[88:91], v[238:241], v[182:185], v[88:91]
	v_mfma_f32_16x16x32_bf16 v[84:87], v[230:233], v[194:197], v[84:87]
	ds_read_b128 v[186:189], v137 offset:18432
	v_mfma_f32_16x16x32_bf16 v[80:83], v[238:241], v[194:197], v[80:83]
	v_mfma_f32_16x16x32_bf16 v[76:79], v[230:233], v[202:205], v[76:79]
	ds_read_b128 v[198:201], v137 offset:20480
	v_mfma_f32_16x16x32_bf16 v[72:75], v[238:241], v[202:205], v[72:75]
	v_mfma_f32_16x16x32_bf16 v[68:71], v[230:233], v[222:225], v[68:71]
	ds_read_b128 v[206:209], v137 offset:22528
	v_mfma_f32_16x16x32_bf16 v[64:67], v[238:241], v[222:225], v[64:67]
	s_barrier
	s_setprio 0
	ds_read_b128 v[182:185], v137 offset:17408
	ds_read_b128 v[194:197], v137 offset:19456
	ds_read_b128 v[202:205], v137 offset:21504
	ds_read_b128 v[222:225], v137 offset:23552
	s_add_u32 m0, s3, 0x0
	s_nop 0
	s_add_u32 vcc_lo, s0, s76
	s_addc_u32 vcc_hi, s1, s77
	global_load_lds_dwordx4 v132, vcc
	s_add_u32 m0, s3, 0x2000
	s_nop 0
	global_load_lds_dwordx4 v134, vcc
	s_waitcnt vmcnt(8)
	s_setprio 1
	s_barrier
	s_waitcnt lgkmcnt(0)
	v_mfma_f32_16x16x32_bf16 v[60:63], v[162:165], v[178:181], v[60:63]
	v_mfma_f32_16x16x32_bf16 v[56:59], v[170:173], v[178:181], v[56:59]
	v_mfma_f32_16x16x32_bf16 v[52:55], v[162:165], v[186:189], v[52:55]
	v_mfma_f32_16x16x32_bf16 v[48:51], v[170:173], v[186:189], v[48:51]
	v_mfma_f32_16x16x32_bf16 v[44:47], v[162:165], v[198:201], v[44:47]
	v_mfma_f32_16x16x32_bf16 v[40:43], v[170:173], v[198:201], v[40:43]
	v_mfma_f32_16x16x32_bf16 v[36:39], v[162:165], v[206:209], v[36:39]
	v_mfma_f32_16x16x32_bf16 v[32:35], v[170:173], v[206:209], v[32:35]
	v_mfma_f32_16x16x32_bf16 v[60:63], v[166:169], v[182:185], v[60:63]
	v_mfma_f32_16x16x32_bf16 v[56:59], v[174:177], v[182:185], v[56:59]
	v_mfma_f32_16x16x32_bf16 v[52:55], v[166:169], v[194:197], v[52:55]
	v_mfma_f32_16x16x32_bf16 v[48:51], v[174:177], v[194:197], v[48:51]
	v_mfma_f32_16x16x32_bf16 v[44:47], v[166:169], v[202:205], v[44:47]
	v_mfma_f32_16x16x32_bf16 v[40:43], v[174:177], v[202:205], v[40:43]
	v_mfma_f32_16x16x32_bf16 v[36:39], v[166:169], v[222:225], v[36:39]
	v_mfma_f32_16x16x32_bf16 v[32:35], v[174:177], v[222:225], v[32:35]
	s_barrier
	s_setprio 0
	ds_read_b128 v[162:165], v152 offset:32768
	ds_read_b128 v[166:169], v152 offset:33792
	ds_read_b128 v[170:173], v152 offset:34816
	ds_read_b128 v[174:177], v152 offset:35840
	s_add_u32 m0, s3, s29
	s_nop 0
	s_add_u32 vcc_lo, s0, s70
	s_addc_u32 vcc_hi, s1, s71
	global_load_lds_dwordx4 v128, vcc
	s_add_u32 m0, s3, s29
	s_add_u32 m0, m0, 0x2000
	s_nop 0
	global_load_lds_dwordx4 v130, vcc
	s_waitcnt vmcnt(6)
	s_setprio 1
	s_barrier
; #define WAIT_V(n) asm volatile("s_waitcnt vmcnt(" #n ")" ::: "memory")
; #define WAIT_L(n) asm volatile("s_waitcnt lgkmcnt(" #n ")" ::: "memory")
; #define BAR __builtin_amdgcn_s_barrier()
; #define SCHED __builtin_amdgcn_sched_barrier(0)
; #define STAGE(P, BASE, br, kt) do { const char* _g = (const char*)((BASE) + (size_t)(br) * GK + (kt) * BK); \
;     __builtin_amdgcn_global_load_lds((const unsigned*)(_g + voff0), (unsigned*)((char*)(P) + tx * 16), 16, 0, 0); \
;     __builtin_amdgcn_global_load_lds((const unsigned*)(_g + voff1), (unsigned*)((char*)(P) + tx * 16 + 8192), 16, 0, 0); } while (0)
; #define LDA(dst, b, h) _Pragma("unroll") for (int m = 0; m < 4; ++m) _Pragma("unroll") for (int k = 0; k < 2; ++k) \
;     dst[m][k] = *reinterpret_cast<const bf16x8*>((char*)shm + abase + (((b) * 2 + (h)) * 16384 + (m * 2 + k) * 1024))
; #define LDB(dst, b, h) _Pragma("unroll") for (int n = 0; n < 2; ++n) _Pragma("unroll") for (int k = 0; k < 2; ++k) \
;     dst[n][k] = *reinterpret_cast<const bf16x8*>((char*)shm + bbase + (((b) * 2 + (h)) * 16384 + (n * 2 + k) * 1024))
; template <bool SWAP>
; __device__ __forceinline__ void gemm_main(const u16* __restrict__ A, const u16* __restrict__ Bt, int brow, int bcol,
;                                           u16* shm, f32x4 (&acc)[2][2][4][2]) {
;     ...
;     WAIT_V(6); BAR; MMA(1, 1, At, B1); BAR;
;     LDB(B0, 1, 0); SCHED; LDA(At, 1, 0); STAGE(SA(0, 1), A, brow + HALF, t + 2);
;     WAIT_L(8); BAR; WAIT_L(0); MMA(0, 0, At, B0); BAR; SCHED;
;     LDB(B1, 1, 1); STAGE(SB(1, 0), Bt, bcol, t + 3);
;     BAR; WAIT_L(0); MMA(0, 1, At, B1); BAR;
;     LDA(At, 1, 1); STAGE(SA(1, 0), A, brow, t + 3);
	v_mfma_f32_16x16x32_bf16 v[28:31], v[226:229], v[178:181], v[28:31]
	v_mfma_f32_16x16x32_bf16 v[24:27], v[234:237], v[178:181], v[24:27]
	v_mfma_f32_16x16x32_bf16 v[20:23], v[226:229], v[186:189], v[20:23]
	v_mfma_f32_16x16x32_bf16 v[16:19], v[234:237], v[186:189], v[16:19]
	v_mfma_f32_16x16x32_bf16 v[12:15], v[226:229], v[198:201], v[12:15]
	v_mfma_f32_16x16x32_bf16 v[8:11], v[234:237], v[198:201], v[8:11]
	v_mfma_f32_16x16x32_bf16 v[4:7], v[226:229], v[206:209], v[4:7]
	v_mfma_f32_16x16x32_bf16 v[0:3], v[234:237], v[206:209], v[0:3]
	v_mfma_f32_16x16x32_bf16 v[28:31], v[230:233], v[182:185], v[28:31]
	ds_read_b128 v[178:181], v137 offset:32768
	v_mfma_f32_16x16x32_bf16 v[24:27], v[238:241], v[182:185], v[24:27]
	v_mfma_f32_16x16x32_bf16 v[20:23], v[230:233], v[194:197], v[20:23]
	ds_read_b128 v[186:189], v137 offset:34816
	v_mfma_f32_16x16x32_bf16 v[16:19], v[238:241], v[194:197], v[16:19]
	v_mfma_f32_16x16x32_bf16 v[12:15], v[230:233], v[202:205], v[12:15]
	ds_read_b128 v[198:201], v137 offset:36864
	v_mfma_f32_16x16x32_bf16 v[8:11], v[238:241], v[202:205], v[8:11]
	v_mfma_f32_16x16x32_bf16 v[4:7], v[230:233], v[222:225], v[4:7]
	ds_read_b128 v[206:209], v137 offset:38912
	v_mfma_f32_16x16x32_bf16 v[0:3], v[238:241], v[222:225], v[0:3]
	s_barrier
	s_setprio 0
	ds_read_b128 v[182:185], v137 offset:33792
	ds_read_b128 v[194:197], v137 offset:35840
	ds_read_b128 v[202:205], v137 offset:37888
	ds_read_b128 v[222:225], v137 offset:39936
	s_add_u32 m0, s3, 0x4000
	s_nop 0
	s_add_u32 vcc_lo, s0, s96
	s_addc_u32 vcc_hi, s1, s97
	global_load_lds_dwordx4 v132, vcc
	s_add_u32 m0, s3, 0x6000
	s_nop 0
	global_load_lds_dwordx4 v134, vcc
	s_waitcnt lgkmcnt(8)
	s_setprio 1
	s_barrier
	s_waitcnt lgkmcnt(0)
	v_mfma_f32_16x16x32_bf16 v[124:127], v[162:165], v[178:181], v[124:127]
	v_mfma_f32_16x16x32_bf16 v[120:123], v[170:173], v[178:181], v[120:123]
	v_mfma_f32_16x16x32_bf16 v[116:119], v[162:165], v[186:189], v[116:119]
	v_mfma_f32_16x16x32_bf16 v[112:115], v[170:173], v[186:189], v[112:115]
	v_mfma_f32_16x16x32_bf16 v[108:111], v[162:165], v[198:201], v[108:111]
	v_mfma_f32_16x16x32_bf16 v[104:107], v[170:173], v[198:201], v[104:107]
	v_mfma_f32_16x16x32_bf16 v[100:103], v[162:165], v[206:209], v[100:103]
	v_mfma_f32_16x16x32_bf16 v[96:99], v[170:173], v[206:209], v[96:99]
	v_mfma_f32_16x16x32_bf16 v[124:127], v[166:169], v[182:185], v[124:127]
	v_mfma_f32_16x16x32_bf16 v[120:123], v[174:177], v[182:185], v[120:123]
	v_mfma_f32_16x16x32_bf16 v[116:119], v[166:169], v[194:197], v[116:119]
	v_mfma_f32_16x16x32_bf16 v[112:115], v[174:177], v[194:197], v[112:115]
	v_mfma_f32_16x16x32_bf16 v[108:111], v[166:169], v[202:205], v[108:111]
	v_mfma_f32_16x16x32_bf16 v[104:107], v[174:177], v[202:205], v[104:107]
	v_mfma_f32_16x16x32_bf16 v[100:103], v[166:169], v[222:225], v[100:103]
	v_mfma_f32_16x16x32_bf16 v[96:99], v[174:177], v[222:225], v[96:99]
	s_barrier
	s_setprio 0
	ds_read_b128 v[226:229], v152 offset:49152
	ds_read_b128 v[230:233], v152 offset:50176
	ds_read_b128 v[234:237], v152 offset:51200
	ds_read_b128 v[238:241], v152 offset:52224
	v_add_u32_e32 v250, s30, v153
	v_add_u32_e32 v250, 0x2000, v250
	s_add_u32 m0, s3, s30
	s_nop 0
	s_add_u32 vcc_lo, s0, s34
	s_addc_u32 vcc_hi, s1, s35
	global_load_lds_dwordx4 v128, vcc
	v_lshl_add_u64 v[248:249], v[246:247], 0, s[34:35]
	s_add_u32 m0, s3, s30
	s_add_u32 m0, m0, 0x2000
	s_nop 0
	global_load_lds_dwordx4 v130, vcc
	s_setprio 1
	s_barrier
	s_waitcnt lgkmcnt(0)
	v_mfma_f32_16x16x32_bf16 v[92:95], v[226:229], v[178:181], v[92:95]
	v_mfma_f32_16x16x32_bf16 v[88:91], v[234:237], v[178:181], v[88:91]
	v_mfma_f32_16x16x32_bf16 v[84:87], v[226:229], v[186:189], v[84:87]
	v_mfma_f32_16x16x32_bf16 v[80:83], v[234:237], v[186:189], v[80:83]
	v_mfma_f32_16x16x32_bf16 v[76:79], v[226:229], v[198:201], v[76:79]
	v_mfma_f32_16x16x32_bf16 v[72:75], v[234:237], v[198:201], v[72:75]
	v_mfma_f32_16x16x32_bf16 v[68:71], v[226:229], v[206:209], v[68:71]
	v_mfma_f32_16x16x32_bf16 v[64:67], v[234:237], v[206:209], v[64:67]
	v_mfma_f32_16x16x32_bf16 v[92:95], v[230:233], v[182:185], v[92:95]
	ds_read_b128 v[178:181], v137 offset:49152
	v_mfma_f32_16x16x32_bf16 v[88:91], v[238:241], v[182:185], v[88:91]
	v_mfma_f32_16x16x32_bf16 v[84:87], v[230:233], v[194:197], v[84:87]
	ds_read_b128 v[186:189], v137 offset:51200
	v_mfma_f32_16x16x32_bf16 v[80:83], v[238:241], v[194:197], v[80:83]
	v_mfma_f32_16x16x32_bf16 v[76:79], v[230:233], v[202:205], v[76:79]
	ds_read_b128 v[198:201], v137 offset:53248
	v_mfma_f32_16x16x32_bf16 v[72:75], v[238:241], v[202:205], v[72:75]
	v_mfma_f32_16x16x32_bf16 v[68:71], v[230:233], v[222:225], v[68:71]
	ds_read_b128 v[206:209], v137 offset:55296
	v_mfma_f32_16x16x32_bf16 v[64:67], v[238:241], v[222:225], v[64:67]
	s_barrier
	s_setprio 0
	ds_read_b128 v[182:185], v137 offset:50176
	ds_read_b128 v[194:197], v137 offset:52224
	ds_read_b128 v[202:205], v137 offset:54272
	ds_read_b128 v[222:225], v137 offset:56320
	v_add_u32_e32 v248, 0x8000, v192
	s_add_u32 m0, s3, 0x8000
	s_nop 0
	s_add_u32 vcc_lo, s0, s36
	s_addc_u32 vcc_hi, s1, s37
	global_load_lds_dwordx4 v132, vcc
	s_add_u32 m0, s3, 0xa000
	s_nop 0
	global_load_lds_dwordx4 v134, vcc
	s_waitcnt vmcnt(8)
	s_setprio 1
	s_barrier
; #define WAIT_V(n) asm volatile("s_waitcnt vmcnt(" #n ")" ::: "memory")
; #define WAIT_L(n) asm volatile("s_waitcnt lgkmcnt(" #n ")" ::: "memory")
; #define BAR __builtin_amdgcn_s_barrier()
; #define SCHED __builtin_amdgcn_sched_barrier(0)
; #define STAGE(P, BASE, br, kt) do { const char* _g = (const char*)((BASE) + (size_t)(br) * GK + (kt) * BK); \
;     __builtin_amdgcn_global_load_lds((const unsigned*)(_g + voff0), (unsigned*)((char*)(P) + tx * 16), 16, 0, 0); \
;     __builtin_amdgcn_global_load_lds((const unsigned*)(_g + voff1), (unsigned*)((char*)(P) + tx * 16 + 8192), 16, 0, 0); } while (0)
; #define LDA(dst, b, h) _Pragma("unroll") for (int m = 0; m < 4; ++m) _Pragma("unroll") for (int k = 0; k < 2; ++k) \
;     dst[m][k] = *reinterpret_cast<const bf16x8*>((char*)shm + abase + (((b) * 2 + (h)) * 16384 + (m * 2 + k) * 1024))
; #define LDB(dst, b, h) _Pragma("unroll") for (int n = 0; n < 2; ++n) _Pragma("unroll") for (int k = 0; k < 2; ++k) \
;     dst[n][k] = *reinterpret_cast<const bf16x8*>((char*)shm + bbase + (((b) * 2 + (h)) * 16384 + (n * 2 + k) * 1024))
; template <bool SWAP>
; __device__ __forceinline__ void gemm_main(const u16* __restrict__ A, const u16* __restrict__ Bt, int brow, int bcol,
;                                           u16* shm, f32x4 (&acc)[2][2][4][2]) {
;     ...
;     BAR; WAIT_L(0); MMA(1, 0, At, B0); BAR; SCHED;
;     STAGE(SB(1, 1), Bt, bcol + HALF, t + 3);
;     WAIT_V(6); BAR; MMA(1, 1, At, B1); BAR;
;   }
;   { LDB(B0, 0, 0); LDA(At, 0, 0); STAGE(SA(1, 1), A, brow + HALF, nt - 1);
;     BAR; WAIT_L(0); MMA(0, 0, At, B0); BAR;
	s_waitcnt lgkmcnt(0)
	v_mfma_f32_16x16x32_bf16 v[60:63], v[162:165], v[178:181], v[60:63]
	v_mfma_f32_16x16x32_bf16 v[56:59], v[170:173], v[178:181], v[56:59]
	v_mfma_f32_16x16x32_bf16 v[52:55], v[162:165], v[186:189], v[52:55]
	v_mfma_f32_16x16x32_bf16 v[48:51], v[170:173], v[186:189], v[48:51]
	v_mfma_f32_16x16x32_bf16 v[44:47], v[162:165], v[198:201], v[44:47]
	v_mfma_f32_16x16x32_bf16 v[40:43], v[170:173], v[198:201], v[40:43]
	v_mfma_f32_16x16x32_bf16 v[36:39], v[162:165], v[206:209], v[36:39]
	v_mfma_f32_16x16x32_bf16 v[32:35], v[170:173], v[206:209], v[32:35]
	v_mfma_f32_16x16x32_bf16 v[60:63], v[166:169], v[182:185], v[60:63]
	v_mfma_f32_16x16x32_bf16 v[56:59], v[174:177], v[182:185], v[56:59]
	v_mfma_f32_16x16x32_bf16 v[52:55], v[166:169], v[194:197], v[52:55]
	v_mfma_f32_16x16x32_bf16 v[48:51], v[174:177], v[194:197], v[48:51]
	v_mfma_f32_16x16x32_bf16 v[44:47], v[166:169], v[202:205], v[44:47]
	v_mfma_f32_16x16x32_bf16 v[40:43], v[174:177], v[202:205], v[40:43]
	v_mfma_f32_16x16x32_bf16 v[36:39], v[166:169], v[222:225], v[36:39]
	v_mfma_f32_16x16x32_bf16 v[32:35], v[174:177], v[222:225], v[32:35]
	s_barrier
	s_setprio 0
	ds_read_b128 v[162:165], v152
	ds_read_b128 v[166:169], v152 offset:1024
	ds_read_b128 v[170:173], v152 offset:2048
	ds_read_b128 v[174:177], v152 offset:3072
	s_add_u32 m0, s3, s31
	s_nop 0
	s_add_u32 vcc_lo, s0, s64
	s_addc_u32 vcc_hi, s1, s65
	global_load_lds_dwordx4 v128, vcc
	v_lshl_add_u64 v[254:255], v[246:247], 0, s[64:65]
	s_add_u32 m0, s3, s31
	s_add_u32 m0, m0, 0x2000
	s_nop 0
	global_load_lds_dwordx4 v130, vcc
	s_waitcnt vmcnt(6)
	s_setprio 1
	s_barrier
	v_mfma_f32_16x16x32_bf16 v[28:31], v[226:229], v[178:181], v[28:31]
	v_mfma_f32_16x16x32_bf16 v[24:27], v[234:237], v[178:181], v[24:27]
	v_mfma_f32_16x16x32_bf16 v[20:23], v[226:229], v[186:189], v[20:23]
	v_mfma_f32_16x16x32_bf16 v[16:19], v[234:237], v[186:189], v[16:19]
	v_mfma_f32_16x16x32_bf16 v[12:15], v[226:229], v[198:201], v[12:15]
	v_mfma_f32_16x16x32_bf16 v[8:11], v[234:237], v[198:201], v[8:11]
	v_mfma_f32_16x16x32_bf16 v[4:7], v[226:229], v[206:209], v[4:7]
	v_mfma_f32_16x16x32_bf16 v[0:3], v[234:237], v[206:209], v[0:3]
	v_mfma_f32_16x16x32_bf16 v[28:31], v[230:233], v[182:185], v[28:31]
	ds_read_b128 v[178:181], v137
	v_mfma_f32_16x16x32_bf16 v[24:27], v[238:241], v[182:185], v[24:27]
	v_mfma_f32_16x16x32_bf16 v[20:23], v[230:233], v[194:197], v[20:23]
	ds_read_b128 v[186:189], v137 offset:2048
	v_mfma_f32_16x16x32_bf16 v[16:19], v[238:241], v[194:197], v[16:19]
	v_mfma_f32_16x16x32_bf16 v[12:15], v[230:233], v[202:205], v[12:15]
	ds_read_b128 v[198:201], v137 offset:4096
	v_mfma_f32_16x16x32_bf16 v[8:11], v[238:241], v[202:205], v[8:11]
	v_mfma_f32_16x16x32_bf16 v[4:7], v[230:233], v[222:225], v[4:7]
	ds_read_b128 v[206:209], v137 offset:6144
	v_mfma_f32_16x16x32_bf16 v[0:3], v[238:241], v[222:225], v[0:3]
	s_add_i32 s2, s2, 2
	s_add_u32 s0, s0, 0x100
	s_addc_u32 s1, s1, 0
	s_cmp_lt_u32 s2, 28
	s_barrier
	s_setprio 0
	s_cbranch_scc1 .LBB0_200
	v_lshlrev_b32_e32 v128, 3, v154
	v_lshlrev_b32_e32 v129, 5, v154
	v_and_b32_e32 v128, 0xffff0, v128
	v_and_b32_e32 v129, 32, v129
	s_or_b32 s0, s24, 0x80
	v_add_u32_e32 v129, v129, v156
	v_add_lshl_u32 v128, v155, v128, 12
	s_ashr_i32 s1, s0, 31
	v_lshl_add_u32 v192, v129, 1, v128
	v_lshlrev_b32_e32 v128, 3, v157
	v_lshlrev_b32_e32 v129, 5, v157
	s_lshl_b64 s[0:1], s[0:1], 12
	v_readlane_b32 s2, v253, 35
	v_and_b32_e32 v128, 0xffff0, v128
	v_and_b32_e32 v129, 32, v129
	v_readlane_b32 s3, v253, 36
	s_add_u32 s0, s2, s0
	v_add_u32_e32 v129, v129, v159
	v_add_lshl_u32 v128, v158, v128, 12
	s_addc_u32 s1, s3, s1
	v_lshl_add_u32 v158, v129, 1, v128
	v_mov_b32_e32 v159, v193
	v_lshl_add_u64 v[190:191], s[0:1], 0, v[192:193]
	s_mov_b64 s[4:5], 0xf80
	v_readfirstlane_b32 s2, v160
	v_lshl_add_u64 v[190:191], v[190:191], 0, s[4:5]
	s_mov_b32 m0, s2
	v_lshl_add_u64 v[158:159], s[0:1], 0, v[158:159]
	v_readfirstlane_b32 s0, v161
	ds_read_b128 v[128:131], v152
	ds_read_b128 v[132:135], v152 offset:1024
	ds_read_b128 v[154:157], v152 offset:2048
	ds_read_b128 v[162:165], v152 offset:3072
	ds_read_b128 v[166:169], v137
	ds_read_b128 v[170:173], v137 offset:1024
	ds_read_b128 v[174:177], v137 offset:2048
	ds_read_b128 v[178:181], v137 offset:3072
	ds_read_b128 v[182:185], v137 offset:4096
	ds_read_b128 v[186:189], v137 offset:5120
	ds_read_b128 v[194:197], v137 offset:6144
	ds_read_b128 v[198:201], v137 offset:7168
	global_load_lds_dwordx4 v[190:191], off
	v_lshl_add_u64 v[158:159], v[158:159], 0, s[4:5]
	s_mov_b32 m0, s0
	s_nop 0
	global_load_lds_dwordx4 v[158:159], off
	s_barrier
	s_waitcnt lgkmcnt(0)
	s_setprio 1
	s_waitcnt lgkmcnt(0)
	v_mfma_f32_16x16x32_bf16 v[124:127], v[128:131], v[166:169], v[124:127]
	v_mfma_f32_16x16x32_bf16 v[116:119], v[128:131], v[174:177], v[116:119]
	v_mfma_f32_16x16x32_bf16 v[108:111], v[128:131], v[182:185], v[108:111]
	v_mfma_f32_16x16x32_bf16 v[100:103], v[128:131], v[194:197], v[100:103]
	v_mfma_f32_16x16x32_bf16 v[124:127], v[132:135], v[170:173], v[124:127]
	v_mfma_f32_16x16x32_bf16 v[120:123], v[154:157], v[166:169], v[120:123]
	v_mfma_f32_16x16x32_bf16 v[116:119], v[132:135], v[178:181], v[116:119]
	v_mfma_f32_16x16x32_bf16 v[112:115], v[154:157], v[174:177], v[112:115]
	v_mfma_f32_16x16x32_bf16 v[108:111], v[132:135], v[186:189], v[108:111]
	v_mfma_f32_16x16x32_bf16 v[104:107], v[154:157], v[182:185], v[104:107]
	v_mfma_f32_16x16x32_bf16 v[100:103], v[132:135], v[198:201], v[100:103]
	v_mfma_f32_16x16x32_bf16 v[96:99], v[154:157], v[194:197], v[96:99]
	v_mfma_f32_16x16x32_bf16 v[158:161], v[162:165], v[170:173], v[120:123]
	v_mfma_f32_16x16x32_bf16 v[202:205], v[162:165], v[178:181], v[112:115]
	v_mfma_f32_16x16x32_bf16 v[206:209], v[162:165], v[186:189], v[104:107]
	v_mfma_f32_16x16x32_bf16 v[222:225], v[162:165], v[198:201], v[96:99]
	s_setprio 0
	s_barrier
; #define WAIT_V(n) asm volatile("s_waitcnt vmcnt(" #n ")" ::: "memory")
; #define WAIT_L(n) asm volatile("s_waitcnt lgkmcnt(" #n ")" ::: "memory")
; #define BAR __builtin_amdgcn_s_barrier()
; #define LDA(dst, b, h) _Pragma("unroll") for (int m = 0; m < 4; ++m) _Pragma("unroll") for (int k = 0; k < 2; ++k) \
;     dst[m][k] = *reinterpret_cast<const bf16x8*>((char*)shm + abase + (((b) * 2 + (h)) * 16384 + (m * 2 + k) * 1024))
; #define LDB(dst, b, h) _Pragma("unroll") for (int n = 0; n < 2; ++n) _Pragma("unroll") for (int k = 0; k < 2; ++k) \
;     dst[n][k] = *reinterpret_cast<const bf16x8*>((char*)shm + bbase + (((b) * 2 + (h)) * 16384 + (n * 2 + k) * 1024))
; template <bool SWAP>
; __device__ __forceinline__ void gemm_main(const u16* __restrict__ A, const u16* __restrict__ Bt, int brow, int bcol,
;                                           u16* shm, f32x4 (&acc)[2][2][4][2]) {
;     ...
;     LDB(B1, 0, 1); BAR; WAIT_L(0); MMA(0, 1, At, B1); BAR;
;     LDA(At, 0, 1); WAIT_V(4); BAR; WAIT_L(0); MMA(1, 0, At, B0); MMA(1, 1, At, B1); BAR; }
;   { LDB(B0, 1, 0); LDA(At, 1, 0); WAIT_V(2); BAR; WAIT_L(0); MMA(0, 0, At, B0); BAR;
	s_nop 1
	ds_read_b128 v[96:99], v152 offset:16384
	ds_read_b128 v[104:107], v152 offset:17408
	ds_read_b128 v[112:115], v152 offset:18432
	ds_read_b128 v[120:123], v152 offset:19456
	s_barrier
	s_waitcnt lgkmcnt(0)
	s_setprio 1
	s_waitcnt lgkmcnt(0)
	v_mfma_f32_16x16x32_bf16 v[92:95], v[96:99], v[166:169], v[92:95]
	v_mfma_f32_16x16x32_bf16 v[84:87], v[96:99], v[174:177], v[84:87]
	v_mfma_f32_16x16x32_bf16 v[76:79], v[96:99], v[182:185], v[76:79]
	v_mfma_f32_16x16x32_bf16 v[68:71], v[96:99], v[194:197], v[68:71]
	v_mfma_f32_16x16x32_bf16 v[92:95], v[104:107], v[170:173], v[92:95]
	v_mfma_f32_16x16x32_bf16 v[88:91], v[112:115], v[166:169], v[88:91]
	v_mfma_f32_16x16x32_bf16 v[84:87], v[104:107], v[178:181], v[84:87]
	v_mfma_f32_16x16x32_bf16 v[80:83], v[112:115], v[174:177], v[80:83]
	v_mfma_f32_16x16x32_bf16 v[76:79], v[104:107], v[186:189], v[76:79]
	v_mfma_f32_16x16x32_bf16 v[72:75], v[112:115], v[182:185], v[72:75]
	v_mfma_f32_16x16x32_bf16 v[68:71], v[104:107], v[198:201], v[68:71]
	v_mfma_f32_16x16x32_bf16 v[64:67], v[112:115], v[194:197], v[64:67]
	v_mfma_f32_16x16x32_bf16 v[166:169], v[120:123], v[170:173], v[88:91]
	v_mfma_f32_16x16x32_bf16 v[170:173], v[120:123], v[178:181], v[80:83]
	v_mfma_f32_16x16x32_bf16 v[174:177], v[120:123], v[186:189], v[72:75]
	v_mfma_f32_16x16x32_bf16 v[178:181], v[120:123], v[198:201], v[64:67]
	s_setprio 0
	s_barrier
	s_nop 1
	ds_read_b128 v[64:67], v137 offset:16384
	ds_read_b128 v[72:75], v137 offset:17408
	ds_read_b128 v[80:83], v137 offset:18432
	ds_read_b128 v[88:91], v137 offset:19456
	ds_read_b128 v[182:185], v137 offset:20480
	ds_read_b128 v[186:189], v137 offset:21504
	ds_read_b128 v[194:197], v137 offset:22528
	ds_read_b128 v[198:201], v137 offset:23552
	s_waitcnt vmcnt(4)
	s_barrier
	s_waitcnt lgkmcnt(0)
	s_setprio 1
	s_waitcnt lgkmcnt(0)
	v_mfma_f32_16x16x32_bf16 v[60:63], v[128:131], v[64:67], v[60:63]
	v_mfma_f32_16x16x32_bf16 v[52:55], v[128:131], v[80:83], v[52:55]
	v_mfma_f32_16x16x32_bf16 v[44:47], v[128:131], v[182:185], v[44:47]
	v_mfma_f32_16x16x32_bf16 v[36:39], v[128:131], v[194:197], v[36:39]
	v_mfma_f32_16x16x32_bf16 v[60:63], v[132:135], v[72:75], v[60:63]
	v_mfma_f32_16x16x32_bf16 v[56:59], v[154:157], v[64:67], v[56:59]
	v_mfma_f32_16x16x32_bf16 v[52:55], v[132:135], v[88:91], v[52:55]
	v_mfma_f32_16x16x32_bf16 v[48:51], v[154:157], v[80:83], v[48:51]
	v_mfma_f32_16x16x32_bf16 v[44:47], v[132:135], v[186:189], v[44:47]
	v_mfma_f32_16x16x32_bf16 v[40:43], v[154:157], v[182:185], v[40:43]
	v_mfma_f32_16x16x32_bf16 v[36:39], v[132:135], v[198:201], v[36:39]
	v_mfma_f32_16x16x32_bf16 v[32:35], v[154:157], v[194:197], v[32:35]
	v_mfma_f32_16x16x32_bf16 v[226:229], v[162:165], v[72:75], v[56:59]
	v_mfma_f32_16x16x32_bf16 v[230:233], v[162:165], v[88:91], v[48:51]
	v_mfma_f32_16x16x32_bf16 v[234:237], v[162:165], v[186:189], v[40:43]
	v_mfma_f32_16x16x32_bf16 v[128:131], v[162:165], v[198:201], v[32:35]
	s_setprio 0
	s_setprio 1
	v_mfma_f32_16x16x32_bf16 v[28:31], v[96:99], v[64:67], v[28:31]
	v_mfma_f32_16x16x32_bf16 v[20:23], v[96:99], v[80:83], v[20:23]
	v_mfma_f32_16x16x32_bf16 v[12:15], v[96:99], v[182:185], v[12:15]
	v_mfma_f32_16x16x32_bf16 v[4:7], v[96:99], v[194:197], v[4:7]
	v_mfma_f32_16x16x32_bf16 v[28:31], v[104:107], v[72:75], v[28:31]
	v_mfma_f32_16x16x32_bf16 v[24:27], v[112:115], v[64:67], v[24:27]
	v_mfma_f32_16x16x32_bf16 v[20:23], v[104:107], v[88:91], v[20:23]
	v_mfma_f32_16x16x32_bf16 v[16:19], v[112:115], v[80:83], v[16:19]
	v_mfma_f32_16x16x32_bf16 v[12:15], v[104:107], v[186:189], v[12:15]
	v_mfma_f32_16x16x32_bf16 v[8:11], v[112:115], v[182:185], v[8:11]
	v_mfma_f32_16x16x32_bf16 v[4:7], v[104:107], v[198:201], v[4:7]
	v_mfma_f32_16x16x32_bf16 v[0:3], v[112:115], v[194:197], v[0:3]
	v_mfma_f32_16x16x32_bf16 v[132:135], v[120:123], v[72:75], v[24:27]
	v_mfma_f32_16x16x32_bf16 v[154:157], v[120:123], v[88:91], v[16:19]
	v_mfma_f32_16x16x32_bf16 v[162:165], v[120:123], v[186:189], v[8:11]
	v_mfma_f32_16x16x32_bf16 v[182:185], v[120:123], v[198:201], v[0:3]
	s_setprio 0
	s_barrier
	s_nop 1
	ds_read_b128 v[0:3], v152 offset:32768
	ds_read_b128 v[8:11], v152 offset:33792
	ds_read_b128 v[16:19], v152 offset:34816
	ds_read_b128 v[24:27], v152 offset:35840
	ds_read_b128 v[32:35], v137 offset:32768
	ds_read_b128 v[40:43], v137 offset:33792
	ds_read_b128 v[48:51], v137 offset:34816
	ds_read_b128 v[56:59], v137 offset:35840
	ds_read_b128 v[64:67], v137 offset:36864
	ds_read_b128 v[186:189], v137 offset:37888
	ds_read_b128 v[194:197], v137 offset:38912
	ds_read_b128 v[198:201], v137 offset:39936
	s_waitcnt vmcnt(2)
	s_barrier
; #define WAIT_V(n) asm volatile("s_waitcnt vmcnt(" #n ")" ::: "memory")
; #define WAIT_L(n) asm volatile("s_waitcnt lgkmcnt(" #n ")" ::: "memory")
; #define BAR __builtin_amdgcn_s_barrier()
; #define LDA(dst, b, h) _Pragma("unroll") for (int m = 0; m < 4; ++m) _Pragma("unroll") for (int k = 0; k < 2; ++k) \
;     dst[m][k] = *reinterpret_cast<const bf16x8*>((char*)shm + abase + (((b) * 2 + (h)) * 16384 + (m * 2 + k) * 1024))
; #define LDB(dst, b, h) _Pragma("unroll") for (int n = 0; n < 2; ++n) _Pragma("unroll") for (int k = 0; k < 2; ++k) \
;     dst[n][k] = *reinterpret_cast<const bf16x8*>((char*)shm + bbase + (((b) * 2 + (h)) * 16384 + (n * 2 + k) * 1024))
; template <bool SWAP>
; __device__ __forceinline__ void gemm_main(const u16* __restrict__ A, const u16* __restrict__ Bt, int brow, int bcol,
;                                           u16* shm, f32x4 (&acc)[2][2][4][2]) {
;     ...
;   { LDB(B0, 1, 0); LDA(At, 1, 0); WAIT_V(2); BAR; WAIT_L(0); MMA(0, 0, At, B0); BAR;
;     LDB(B1, 1, 1); WAIT_V(0); BAR; WAIT_L(0); MMA(0, 1, At, B1); BAR;
;     LDA(At, 1, 1); BAR; WAIT_L(0); MMA(1, 0, At, B0); MMA(1, 1, At, B1); BAR; }
;   if (wr == 0) BAR;
	s_waitcnt lgkmcnt(0)
	s_setprio 1
	s_waitcnt lgkmcnt(0)
	v_mfma_f32_16x16x32_bf16 v[72:75], v[0:3], v[32:35], v[124:127]
	v_mfma_f32_16x16x32_bf16 v[120:123], v[8:11], v[40:43], v[72:75]
	v_mfma_f32_16x16x32_bf16 v[72:75], v[16:19], v[32:35], v[158:161]
	v_mfma_f32_16x16x32_bf16 v[124:127], v[24:27], v[40:43], v[72:75]
	v_mfma_f32_16x16x32_bf16 v[72:75], v[0:3], v[48:51], v[116:119]
	v_mfma_f32_16x16x32_bf16 v[112:115], v[8:11], v[56:59], v[72:75]
	v_mfma_f32_16x16x32_bf16 v[72:75], v[16:19], v[48:51], v[202:205]
	v_mfma_f32_16x16x32_bf16 v[116:119], v[24:27], v[56:59], v[72:75]
	v_mfma_f32_16x16x32_bf16 v[72:75], v[0:3], v[64:67], v[108:111]
	v_mfma_f32_16x16x32_bf16 v[104:107], v[8:11], v[186:189], v[72:75]
	v_mfma_f32_16x16x32_bf16 v[72:75], v[16:19], v[64:67], v[206:209]
	v_mfma_f32_16x16x32_bf16 v[108:111], v[24:27], v[186:189], v[72:75]
	v_mfma_f32_16x16x32_bf16 v[72:75], v[0:3], v[194:197], v[100:103]
	v_mfma_f32_16x16x32_bf16 v[96:99], v[8:11], v[198:201], v[72:75]
	v_mfma_f32_16x16x32_bf16 v[72:75], v[16:19], v[194:197], v[222:225]
	v_mfma_f32_16x16x32_bf16 v[100:103], v[24:27], v[198:201], v[72:75]
	s_setprio 0
	s_barrier
	ds_read_b128 v[158:161], v152 offset:49152
	ds_read_b128 v[202:205], v152 offset:50176
	ds_read_b128 v[206:209], v152 offset:51200
	ds_read_b128 v[222:225], v152 offset:52224
	s_waitcnt vmcnt(0)
	s_barrier
	s_waitcnt lgkmcnt(0)
	s_setprio 1
	s_waitcnt lgkmcnt(0)
	v_mfma_f32_16x16x32_bf16 v[72:75], v[158:161], v[32:35], v[92:95]
	v_mfma_f32_16x16x32_bf16 v[32:35], v[206:209], v[32:35], v[166:169]
	v_mfma_f32_16x16x32_bf16 v[92:95], v[222:225], v[40:43], v[32:35]
	v_mfma_f32_16x16x32_bf16 v[32:35], v[158:161], v[48:51], v[84:87]
	v_mfma_f32_16x16x32_bf16 v[80:83], v[202:205], v[56:59], v[32:35]
	v_mfma_f32_16x16x32_bf16 v[32:35], v[206:209], v[48:51], v[170:173]
	v_mfma_f32_16x16x32_bf16 v[84:87], v[222:225], v[56:59], v[32:35]
	v_mfma_f32_16x16x32_bf16 v[32:35], v[158:161], v[64:67], v[76:79]
	v_mfma_f32_16x16x32_bf16 v[88:91], v[202:205], v[40:43], v[72:75]
	v_mfma_f32_16x16x32_bf16 v[72:75], v[202:205], v[186:189], v[32:35]
	v_mfma_f32_16x16x32_bf16 v[32:35], v[206:209], v[64:67], v[174:177]
	v_mfma_f32_16x16x32_bf16 v[76:79], v[222:225], v[186:189], v[32:35]
	v_mfma_f32_16x16x32_bf16 v[32:35], v[158:161], v[194:197], v[68:71]
	v_mfma_f32_16x16x32_bf16 v[64:67], v[202:205], v[198:201], v[32:35]
	v_mfma_f32_16x16x32_bf16 v[32:35], v[206:209], v[194:197], v[178:181]
	v_mfma_f32_16x16x32_bf16 v[68:71], v[222:225], v[198:201], v[32:35]
	s_setprio 0
	s_barrier
	ds_read_b128 v[166:169], v137 offset:49152
	ds_read_b128 v[170:173], v137 offset:50176
	ds_read_b128 v[174:177], v137 offset:51200
	ds_read_b128 v[178:181], v137 offset:52224
	ds_read_b128 v[186:189], v137 offset:53248
	ds_read_b128 v[194:197], v137 offset:54272
	ds_read_b128 v[198:201], v137 offset:55296
	ds_read_b128 v[238:241], v137 offset:56320
	s_barrier
	s_waitcnt lgkmcnt(0)
	s_setprio 1
	s_waitcnt lgkmcnt(0)
	v_mfma_f32_16x16x32_bf16 v[32:35], v[0:3], v[166:169], v[60:63]
	v_mfma_f32_16x16x32_bf16 v[56:59], v[8:11], v[170:173], v[32:35]
	v_mfma_f32_16x16x32_bf16 v[32:35], v[16:19], v[166:169], v[226:229]
	v_mfma_f32_16x16x32_bf16 v[60:63], v[24:27], v[170:173], v[32:35]
	v_mfma_f32_16x16x32_bf16 v[32:35], v[0:3], v[174:177], v[52:55]
	v_mfma_f32_16x16x32_bf16 v[48:51], v[8:11], v[178:181], v[32:35]
	v_mfma_f32_16x16x32_bf16 v[32:35], v[16:19], v[174:177], v[230:233]
	v_mfma_f32_16x16x32_bf16 v[52:55], v[24:27], v[178:181], v[32:35]
	v_mfma_f32_16x16x32_bf16 v[32:35], v[0:3], v[186:189], v[44:47]
	v_mfma_f32_16x16x32_bf16 v[40:43], v[8:11], v[194:197], v[32:35]
	v_mfma_f32_16x16x32_bf16 v[32:35], v[16:19], v[186:189], v[234:237]
	v_mfma_f32_16x16x32_bf16 v[0:3], v[0:3], v[198:201], v[36:39]
	v_mfma_f32_16x16x32_bf16 v[44:47], v[24:27], v[194:197], v[32:35]
	v_mfma_f32_16x16x32_bf16 v[32:35], v[8:11], v[238:241], v[0:3]
	v_mfma_f32_16x16x32_bf16 v[0:3], v[16:19], v[198:201], v[128:131]
	v_mfma_f32_16x16x32_bf16 v[36:39], v[24:27], v[238:241], v[0:3]
	s_setprio 0
	s_setprio 1
	v_mfma_f32_16x16x32_bf16 v[0:3], v[158:161], v[166:169], v[28:31]
	v_mfma_f32_16x16x32_bf16 v[24:27], v[202:205], v[170:173], v[0:3]
	v_mfma_f32_16x16x32_bf16 v[0:3], v[206:209], v[166:169], v[132:135]
	v_mfma_f32_16x16x32_bf16 v[28:31], v[222:225], v[170:173], v[0:3]
	v_mfma_f32_16x16x32_bf16 v[0:3], v[158:161], v[174:177], v[20:23]
	v_mfma_f32_16x16x32_bf16 v[16:19], v[202:205], v[178:181], v[0:3]
	v_mfma_f32_16x16x32_bf16 v[0:3], v[206:209], v[174:177], v[154:157]
	v_mfma_f32_16x16x32_bf16 v[20:23], v[222:225], v[178:181], v[0:3]
	v_mfma_f32_16x16x32_bf16 v[0:3], v[158:161], v[186:189], v[12:15]
	v_mfma_f32_16x16x32_bf16 v[8:11], v[202:205], v[194:197], v[0:3]
	v_mfma_f32_16x16x32_bf16 v[0:3], v[206:209], v[186:189], v[162:165]
	v_mfma_f32_16x16x32_bf16 v[12:15], v[222:225], v[194:197], v[0:3]
	v_mfma_f32_16x16x32_bf16 v[0:3], v[158:161], v[198:201], v[4:7]
	v_mfma_f32_16x16x32_bf16 v[4:7], v[206:209], v[198:201], v[182:185]
	v_mfma_f32_16x16x32_bf16 v[0:3], v[202:205], v[238:241], v[0:3]
	v_mfma_f32_16x16x32_bf16 v[4:7], v[222:225], v[238:241], v[4:7]
	s_setprio 0
	s_movk_i32 s0, 0x100
	v_cmp_gt_u32_e32 vcc, s0, v136
	s_barrier
	s_and_saveexec_b64 s[0:1], vcc
	s_cbranch_execz .LBB0_203
	s_barrier

; #define WAIT_V(n) asm volatile("s_waitcnt vmcnt(" #n ")" ::: "memory")
; #define WAIT_L(n) asm volatile("s_waitcnt lgkmcnt(" #n ")" ::: "memory")
; #define BAR __builtin_amdgcn_s_barrier()
; #define SCHED __builtin_amdgcn_sched_barrier(0)
; #define STAGE(P, BASE, br, kt) do { const char* _g = (const char*)((BASE) + (size_t)(br) * GK + (kt) * BK); \
;     __builtin_amdgcn_global_load_lds((const unsigned*)(_g + voff0), (unsigned*)((char*)(P) + tx * 16), 16, 0, 0); \
;     __builtin_amdgcn_global_load_lds((const unsigned*)(_g + voff1), (unsigned*)((char*)(P) + tx * 16 + 8192), 16, 0, 0); } while (0)
; #define LDA(dst, b, h) _Pragma("unroll") for (int m = 0; m < 4; ++m) _Pragma("unroll") for (int k = 0; k < 2; ++k) \
;     dst[m][k] = *reinterpret_cast<const bf16x8*>((char*)shm + abase + (((b) * 2 + (h)) * 16384 + (m * 2 + k) * 1024))
; #define LDB(dst, b, h) _Pragma("unroll") for (int n = 0; n < 2; ++n) _Pragma("unroll") for (int k = 0; k < 2; ++k) \
;     dst[n][k] = *reinterpret_cast<const bf16x8*>((char*)shm + bbase + (((b) * 2 + (h)) * 16384 + (n * 2 + k) * 1024))
; template <bool SWAP>
; __device__ __forceinline__ void gemm_main(const u16* __restrict__ A, const u16* __restrict__ Bt, int brow, int bcol,
;                                           u16* shm, f32x4 (&acc)[2][2][4][2]) {
;     ...
;     LDB(B0, 0, 0); SCHED; LDA(At, 0, 0); STAGE(SA(1, 1), A, brow + HALF, t + 1);
;     WAIT_L(8); BAR; WAIT_L(0); MMA(0, 0, At, B0); BAR; SCHED;
;     LDB(B1, 0, 1); STAGE(SB(0, 0), Bt, bcol, t + 2);
;     BAR; WAIT_L(0); MMA(0, 1, At, B1); BAR;
;     LDA(At, 0, 1); STAGE(SA(0, 0), A, brow, t + 2);
;     BAR; WAIT_L(0); MMA(1, 0, At, B0); BAR; SCHED;
;     STAGE(SB(0, 1), Bt, bcol + HALF, t + 2);
;     WAIT_V(6); BAR; MMA(1, 1, At, B1); BAR;
;     LDB(B0, 1, 0); SCHED; LDA(At, 1, 0); STAGE(SA(0, 1), A, brow + HALF, t + 2);
.LBB0_436:
	ds_read_b128 v[170:173], v137 offset:1024
	ds_read_b128 v[178:181], v137 offset:3072
	ds_read_b128 v[186:189], v137 offset:5120
	ds_read_b128 v[198:201], v137 offset:7168
	v_add_u32_e32 v192, 0, v139
	v_add_u32_e32 v148, 0xc000, v192
	v_add_u32_e32 v149, 0xe000, v192
	s_add_u32 m0, s2, 0xc000
	v_lshl_add_u64 v[232:233], s[50:51], 0, v[134:135]
	s_add_u32 vcc_lo, s50, s82
	s_addc_u32 vcc_hi, s51, s83
	global_load_lds_dwordx4 v132, vcc
	s_add_u32 m0, s2, 0xe000
	s_nop 0
	global_load_lds_dwordx4 v134, vcc
	s_waitcnt lgkmcnt(8)
	s_setprio 1
	s_barrier
	s_waitcnt lgkmcnt(0)
	v_mfma_f32_16x16x32_bf16 v[124:127], v[150:153], v[166:169], v[124:127]
	v_mfma_f32_16x16x32_bf16 v[120:123], v[158:161], v[166:169], v[120:123]
	v_mfma_f32_16x16x32_bf16 v[116:119], v[150:153], v[174:177], v[116:119]
	v_mfma_f32_16x16x32_bf16 v[112:115], v[158:161], v[174:177], v[112:115]
	v_mfma_f32_16x16x32_bf16 v[108:111], v[150:153], v[182:185], v[108:111]
	v_mfma_f32_16x16x32_bf16 v[104:107], v[158:161], v[182:185], v[104:107]
	v_mfma_f32_16x16x32_bf16 v[100:103], v[150:153], v[194:197], v[100:103]
	v_mfma_f32_16x16x32_bf16 v[96:99], v[158:161], v[194:197], v[96:99]
	v_mfma_f32_16x16x32_bf16 v[124:127], v[154:157], v[170:173], v[124:127]
	v_mfma_f32_16x16x32_bf16 v[120:123], v[162:165], v[170:173], v[120:123]
	v_mfma_f32_16x16x32_bf16 v[116:119], v[154:157], v[178:181], v[116:119]
	v_mfma_f32_16x16x32_bf16 v[112:115], v[162:165], v[178:181], v[112:115]
	v_mfma_f32_16x16x32_bf16 v[108:111], v[154:157], v[186:189], v[108:111]
	v_mfma_f32_16x16x32_bf16 v[104:107], v[162:165], v[186:189], v[104:107]
	v_mfma_f32_16x16x32_bf16 v[100:103], v[154:157], v[198:201], v[100:103]
	v_mfma_f32_16x16x32_bf16 v[96:99], v[162:165], v[198:201], v[96:99]
	s_barrier
	s_setprio 0
	ds_read_b128 v[202:205], v138 offset:16384
	ds_read_b128 v[206:209], v138 offset:17408
	ds_read_b128 v[224:227], v138 offset:18432
	ds_read_b128 v[228:231], v138 offset:19456
	s_add_u32 m0, s2, s28
	s_nop 0
	s_add_u32 vcc_lo, s50, s74
	s_addc_u32 vcc_hi, s51, s75
	global_load_lds_dwordx4 v128, vcc
	v_lshl_add_u64 v[236:237], s[50:51], 0, v[130:131]
	s_add_u32 m0, s2, s28
	s_add_u32 m0, m0, 0x2000
	s_nop 0
	global_load_lds_dwordx4 v130, vcc
	s_setprio 1
	s_barrier
	s_waitcnt lgkmcnt(0)
	v_mfma_f32_16x16x32_bf16 v[92:95], v[202:205], v[166:169], v[92:95]
	v_mfma_f32_16x16x32_bf16 v[88:91], v[224:227], v[166:169], v[88:91]
	v_mfma_f32_16x16x32_bf16 v[84:87], v[202:205], v[174:177], v[84:87]
	v_mfma_f32_16x16x32_bf16 v[80:83], v[224:227], v[174:177], v[80:83]
	v_mfma_f32_16x16x32_bf16 v[76:79], v[202:205], v[182:185], v[76:79]
	v_mfma_f32_16x16x32_bf16 v[72:75], v[224:227], v[182:185], v[72:75]
	v_mfma_f32_16x16x32_bf16 v[68:71], v[202:205], v[194:197], v[68:71]
	v_mfma_f32_16x16x32_bf16 v[64:67], v[224:227], v[194:197], v[64:67]
	v_mfma_f32_16x16x32_bf16 v[92:95], v[206:209], v[170:173], v[92:95]
	ds_read_b128 v[166:169], v137 offset:16384
	v_mfma_f32_16x16x32_bf16 v[88:91], v[228:231], v[170:173], v[88:91]
	v_mfma_f32_16x16x32_bf16 v[84:87], v[206:209], v[178:181], v[84:87]
	ds_read_b128 v[174:177], v137 offset:18432
	v_mfma_f32_16x16x32_bf16 v[80:83], v[228:231], v[178:181], v[80:83]
	v_mfma_f32_16x16x32_bf16 v[76:79], v[206:209], v[186:189], v[76:79]
	ds_read_b128 v[182:185], v137 offset:20480
	v_mfma_f32_16x16x32_bf16 v[72:75], v[228:231], v[186:189], v[72:75]
	v_mfma_f32_16x16x32_bf16 v[68:71], v[206:209], v[198:201], v[68:71]
	ds_read_b128 v[194:197], v137 offset:22528
	v_mfma_f32_16x16x32_bf16 v[64:67], v[228:231], v[198:201], v[64:67]
	s_barrier
	s_setprio 0
	ds_read_b128 v[170:173], v137 offset:17408
	ds_read_b128 v[178:181], v137 offset:19456
	ds_read_b128 v[186:189], v137 offset:21504
	ds_read_b128 v[198:201], v137 offset:23552
	s_add_u32 m0, s2, 0x0
	s_nop 0
	s_add_u32 vcc_lo, s50, s76
	s_addc_u32 vcc_hi, s51, s77
	global_load_lds_dwordx4 v132, vcc
	s_add_u32 m0, s2, 0x2000
	s_nop 0
	global_load_lds_dwordx4 v134, vcc
	s_waitcnt vmcnt(8)
	s_setprio 1
	s_barrier
	s_waitcnt lgkmcnt(0)
	v_mfma_f32_16x16x32_bf16 v[60:63], v[150:153], v[166:169], v[60:63]
	v_mfma_f32_16x16x32_bf16 v[56:59], v[158:161], v[166:169], v[56:59]
	v_mfma_f32_16x16x32_bf16 v[52:55], v[150:153], v[174:177], v[52:55]
	v_mfma_f32_16x16x32_bf16 v[48:51], v[158:161], v[174:177], v[48:51]
	v_mfma_f32_16x16x32_bf16 v[44:47], v[150:153], v[182:185], v[44:47]
	v_mfma_f32_16x16x32_bf16 v[40:43], v[158:161], v[182:185], v[40:43]
	v_mfma_f32_16x16x32_bf16 v[36:39], v[150:153], v[194:197], v[36:39]
	v_mfma_f32_16x16x32_bf16 v[32:35], v[158:161], v[194:197], v[32:35]
	v_mfma_f32_16x16x32_bf16 v[60:63], v[154:157], v[170:173], v[60:63]
	v_mfma_f32_16x16x32_bf16 v[56:59], v[162:165], v[170:173], v[56:59]
	v_mfma_f32_16x16x32_bf16 v[52:55], v[154:157], v[178:181], v[52:55]
	v_mfma_f32_16x16x32_bf16 v[48:51], v[162:165], v[178:181], v[48:51]
	v_mfma_f32_16x16x32_bf16 v[44:47], v[154:157], v[186:189], v[44:47]
	v_mfma_f32_16x16x32_bf16 v[40:43], v[162:165], v[186:189], v[40:43]
	v_mfma_f32_16x16x32_bf16 v[36:39], v[154:157], v[198:201], v[36:39]
	v_mfma_f32_16x16x32_bf16 v[32:35], v[162:165], v[198:201], v[32:35]
	s_barrier
	s_setprio 0
	ds_read_b128 v[150:153], v138 offset:32768
	ds_read_b128 v[154:157], v138 offset:33792
	ds_read_b128 v[158:161], v138 offset:34816
	ds_read_b128 v[162:165], v138 offset:35840
	s_add_u32 m0, s2, s29
	s_nop 0
	s_add_u32 vcc_lo, s50, s70
	s_addc_u32 vcc_hi, s51, s71
	global_load_lds_dwordx4 v128, vcc
	s_add_u32 m0, s2, s29
	s_add_u32 m0, m0, 0x2000
	s_nop 0
	global_load_lds_dwordx4 v130, vcc
	s_waitcnt vmcnt(6)
	s_setprio 1
	s_barrier
; #define WAIT_V(n) asm volatile("s_waitcnt vmcnt(" #n ")" ::: "memory")
; #define WAIT_L(n) asm volatile("s_waitcnt lgkmcnt(" #n ")" ::: "memory")
; #define BAR __builtin_amdgcn_s_barrier()
; #define SCHED __builtin_amdgcn_sched_barrier(0)
; #define STAGE(P, BASE, br, kt) do { const char* _g = (const char*)((BASE) + (size_t)(br) * GK + (kt) * BK); \
;     __builtin_amdgcn_global_load_lds((const unsigned*)(_g + voff0), (unsigned*)((char*)(P) + tx * 16), 16, 0, 0); \
;     __builtin_amdgcn_global_load_lds((const unsigned*)(_g + voff1), (unsigned*)((char*)(P) + tx * 16 + 8192), 16, 0, 0); } while (0)
; #define LDA(dst, b, h) _Pragma("unroll") for (int m = 0; m < 4; ++m) _Pragma("unroll") for (int k = 0; k < 2; ++k) \
;     dst[m][k] = *reinterpret_cast<const bf16x8*>((char*)shm + abase + (((b) * 2 + (h)) * 16384 + (m * 2 + k) * 1024))
; #define LDB(dst, b, h) _Pragma("unroll") for (int n = 0; n < 2; ++n) _Pragma("unroll") for (int k = 0; k < 2; ++k) \
;     dst[n][k] = *reinterpret_cast<const bf16x8*>((char*)shm + bbase + (((b) * 2 + (h)) * 16384 + (n * 2 + k) * 1024))
; template <bool SWAP>
; __device__ __forceinline__ void gemm_main(const u16* __restrict__ A, const u16* __restrict__ Bt, int brow, int bcol,
;                                           u16* shm, f32x4 (&acc)[2][2][4][2]) {
;     ...
;     WAIT_V(6); BAR; MMA(1, 1, At, B1); BAR;
;     LDB(B0, 1, 0); SCHED; LDA(At, 1, 0); STAGE(SA(0, 1), A, brow + HALF, t + 2);
;     WAIT_L(8); BAR; WAIT_L(0); MMA(0, 0, At, B0); BAR; SCHED;
;     LDB(B1, 1, 1); STAGE(SB(1, 0), Bt, bcol, t + 3);
;     BAR; WAIT_L(0); MMA(0, 1, At, B1); BAR;
;     LDA(At, 1, 1); STAGE(SA(1, 0), A, brow, t + 3);
	v_mfma_f32_16x16x32_bf16 v[28:31], v[202:205], v[166:169], v[28:31]
	v_mfma_f32_16x16x32_bf16 v[24:27], v[224:227], v[166:169], v[24:27]
	v_mfma_f32_16x16x32_bf16 v[20:23], v[202:205], v[174:177], v[20:23]
	v_mfma_f32_16x16x32_bf16 v[16:19], v[224:227], v[174:177], v[16:19]
	v_mfma_f32_16x16x32_bf16 v[12:15], v[202:205], v[182:185], v[12:15]
	v_mfma_f32_16x16x32_bf16 v[8:11], v[224:227], v[182:185], v[8:11]
	v_mfma_f32_16x16x32_bf16 v[4:7], v[202:205], v[194:197], v[4:7]
	v_mfma_f32_16x16x32_bf16 v[0:3], v[224:227], v[194:197], v[0:3]
	v_mfma_f32_16x16x32_bf16 v[28:31], v[206:209], v[170:173], v[28:31]
	ds_read_b128 v[166:169], v137 offset:32768
	v_mfma_f32_16x16x32_bf16 v[24:27], v[228:231], v[170:173], v[24:27]
	v_mfma_f32_16x16x32_bf16 v[20:23], v[206:209], v[178:181], v[20:23]
	ds_read_b128 v[174:177], v137 offset:34816
	v_mfma_f32_16x16x32_bf16 v[16:19], v[228:231], v[178:181], v[16:19]
	v_mfma_f32_16x16x32_bf16 v[12:15], v[206:209], v[186:189], v[12:15]
	ds_read_b128 v[182:185], v137 offset:36864
	v_mfma_f32_16x16x32_bf16 v[8:11], v[228:231], v[186:189], v[8:11]
	v_mfma_f32_16x16x32_bf16 v[4:7], v[206:209], v[198:201], v[4:7]
	ds_read_b128 v[194:197], v137 offset:38912
	v_mfma_f32_16x16x32_bf16 v[0:3], v[228:231], v[198:201], v[0:3]
	s_barrier
	s_setprio 0
	ds_read_b128 v[170:173], v137 offset:33792
	ds_read_b128 v[178:181], v137 offset:35840
	ds_read_b128 v[186:189], v137 offset:37888
	ds_read_b128 v[198:201], v137 offset:39936
	s_add_u32 m0, s2, 0x4000
	s_nop 0
	s_add_u32 vcc_lo, s50, s96
	s_addc_u32 vcc_hi, s51, s97
	global_load_lds_dwordx4 v132, vcc
	s_add_u32 m0, s2, 0x6000
	s_nop 0
	global_load_lds_dwordx4 v134, vcc
	s_waitcnt lgkmcnt(8)
	s_setprio 1
	s_barrier
	s_waitcnt lgkmcnt(0)
	v_mfma_f32_16x16x32_bf16 v[124:127], v[150:153], v[166:169], v[124:127]
	v_mfma_f32_16x16x32_bf16 v[120:123], v[158:161], v[166:169], v[120:123]
	v_mfma_f32_16x16x32_bf16 v[116:119], v[150:153], v[174:177], v[116:119]
	v_mfma_f32_16x16x32_bf16 v[112:115], v[158:161], v[174:177], v[112:115]
	v_mfma_f32_16x16x32_bf16 v[108:111], v[150:153], v[182:185], v[108:111]
	v_mfma_f32_16x16x32_bf16 v[104:107], v[158:161], v[182:185], v[104:107]
	v_mfma_f32_16x16x32_bf16 v[100:103], v[150:153], v[194:197], v[100:103]
	v_mfma_f32_16x16x32_bf16 v[96:99], v[158:161], v[194:197], v[96:99]
	v_mfma_f32_16x16x32_bf16 v[124:127], v[154:157], v[170:173], v[124:127]
	v_mfma_f32_16x16x32_bf16 v[120:123], v[162:165], v[170:173], v[120:123]
	v_mfma_f32_16x16x32_bf16 v[116:119], v[154:157], v[178:181], v[116:119]
	v_mfma_f32_16x16x32_bf16 v[112:115], v[162:165], v[178:181], v[112:115]
	v_mfma_f32_16x16x32_bf16 v[108:111], v[154:157], v[186:189], v[108:111]
	v_mfma_f32_16x16x32_bf16 v[104:107], v[162:165], v[186:189], v[104:107]
	v_mfma_f32_16x16x32_bf16 v[100:103], v[154:157], v[198:201], v[100:103]
	v_mfma_f32_16x16x32_bf16 v[96:99], v[162:165], v[198:201], v[96:99]
	s_barrier
	s_setprio 0
	ds_read_b128 v[202:205], v138 offset:49152
	ds_read_b128 v[206:209], v138 offset:50176
	ds_read_b128 v[224:227], v138 offset:51200
	ds_read_b128 v[228:231], v138 offset:52224
	s_add_u32 m0, s2, s30
	s_nop 0
	s_add_u32 vcc_lo, s50, s34
	s_addc_u32 vcc_hi, s51, s35
	global_load_lds_dwordx4 v128, vcc
	v_lshl_add_u64 v[238:239], v[236:237], 0, s[34:35]
	s_add_u32 m0, s2, s30
	s_add_u32 m0, m0, 0x2000
	s_nop 0
	global_load_lds_dwordx4 v130, vcc
	s_setprio 1
	s_barrier
	s_waitcnt lgkmcnt(0)
	v_mfma_f32_16x16x32_bf16 v[92:95], v[202:205], v[166:169], v[92:95]
	v_mfma_f32_16x16x32_bf16 v[88:91], v[224:227], v[166:169], v[88:91]
	v_mfma_f32_16x16x32_bf16 v[84:87], v[202:205], v[174:177], v[84:87]
	v_mfma_f32_16x16x32_bf16 v[80:83], v[224:227], v[174:177], v[80:83]
	v_mfma_f32_16x16x32_bf16 v[76:79], v[202:205], v[182:185], v[76:79]
	v_mfma_f32_16x16x32_bf16 v[72:75], v[224:227], v[182:185], v[72:75]
	v_mfma_f32_16x16x32_bf16 v[68:71], v[202:205], v[194:197], v[68:71]
	v_mfma_f32_16x16x32_bf16 v[64:67], v[224:227], v[194:197], v[64:67]
	v_mfma_f32_16x16x32_bf16 v[92:95], v[206:209], v[170:173], v[92:95]
	ds_read_b128 v[166:169], v137 offset:49152
	v_mfma_f32_16x16x32_bf16 v[88:91], v[228:231], v[170:173], v[88:91]
	v_mfma_f32_16x16x32_bf16 v[84:87], v[206:209], v[178:181], v[84:87]
	ds_read_b128 v[174:177], v137 offset:51200
	v_mfma_f32_16x16x32_bf16 v[80:83], v[228:231], v[178:181], v[80:83]
	v_mfma_f32_16x16x32_bf16 v[76:79], v[206:209], v[186:189], v[76:79]
	ds_read_b128 v[182:185], v137 offset:53248
	v_mfma_f32_16x16x32_bf16 v[72:75], v[228:231], v[186:189], v[72:75]
	v_mfma_f32_16x16x32_bf16 v[68:71], v[206:209], v[198:201], v[68:71]
	ds_read_b128 v[194:197], v137 offset:55296
	v_mfma_f32_16x16x32_bf16 v[64:67], v[228:231], v[198:201], v[64:67]
	s_barrier
	s_setprio 0
	ds_read_b128 v[170:173], v137 offset:50176
	ds_read_b128 v[178:181], v137 offset:52224
	ds_read_b128 v[186:189], v137 offset:54272
	ds_read_b128 v[198:201], v137 offset:56320
	v_add_u32_e32 v223, 0x8000, v192
	s_add_u32 m0, s2, 0x8000
	s_nop 0
	s_add_u32 vcc_lo, s50, s36
	s_addc_u32 vcc_hi, s51, s37
	global_load_lds_dwordx4 v132, vcc
	v_lshl_add_u64 v[190:191], v[232:233], 0, s[36:37]
	s_add_u32 m0, s2, 0xa000
	s_nop 0
	global_load_lds_dwordx4 v134, vcc
	s_waitcnt vmcnt(8)
	s_setprio 1
	s_barrier
; #define WAIT_V(n) asm volatile("s_waitcnt vmcnt(" #n ")" ::: "memory")
; #define WAIT_L(n) asm volatile("s_waitcnt lgkmcnt(" #n ")" ::: "memory")
; #define BAR __builtin_amdgcn_s_barrier()
; #define SCHED __builtin_amdgcn_sched_barrier(0)
; #define STAGE(P, BASE, br, kt) do { const char* _g = (const char*)((BASE) + (size_t)(br) * GK + (kt) * BK); \
;     __builtin_amdgcn_global_load_lds((const unsigned*)(_g + voff0), (unsigned*)((char*)(P) + tx * 16), 16, 0, 0); \
;     __builtin_amdgcn_global_load_lds((const unsigned*)(_g + voff1), (unsigned*)((char*)(P) + tx * 16 + 8192), 16, 0, 0); } while (0)
; #define LDA(dst, b, h) _Pragma("unroll") for (int m = 0; m < 4; ++m) _Pragma("unroll") for (int k = 0; k < 2; ++k) \
;     dst[m][k] = *reinterpret_cast<const bf16x8*>((char*)shm + abase + (((b) * 2 + (h)) * 16384 + (m * 2 + k) * 1024))
; #define LDB(dst, b, h) _Pragma("unroll") for (int n = 0; n < 2; ++n) _Pragma("unroll") for (int k = 0; k < 2; ++k) \
;     dst[n][k] = *reinterpret_cast<const bf16x8*>((char*)shm + bbase + (((b) * 2 + (h)) * 16384 + (n * 2 + k) * 1024))
; template <bool SWAP>
; __device__ __forceinline__ void gemm_main(const u16* __restrict__ A, const u16* __restrict__ Bt, int brow, int bcol,
;                                           u16* shm, f32x4 (&acc)[2][2][4][2]) {
;     ...
;     BAR; WAIT_L(0); MMA(1, 0, At, B0); BAR; SCHED;
;     STAGE(SB(1, 1), Bt, bcol + HALF, t + 3);
;     WAIT_V(6); BAR; MMA(1, 1, At, B1); BAR;
;   }
;   { LDB(B0, 0, 0); LDA(At, 0, 0); STAGE(SA(1, 1), A, brow + HALF, nt - 1);
;     BAR; WAIT_L(0); MMA(0, 0, At, B0); BAR;
	s_waitcnt lgkmcnt(0)
	v_mfma_f32_16x16x32_bf16 v[60:63], v[150:153], v[166:169], v[60:63]
	v_mfma_f32_16x16x32_bf16 v[56:59], v[158:161], v[166:169], v[56:59]
	v_mfma_f32_16x16x32_bf16 v[52:55], v[150:153], v[174:177], v[52:55]
	v_mfma_f32_16x16x32_bf16 v[48:51], v[158:161], v[174:177], v[48:51]
	v_mfma_f32_16x16x32_bf16 v[44:47], v[150:153], v[182:185], v[44:47]
	v_mfma_f32_16x16x32_bf16 v[40:43], v[158:161], v[182:185], v[40:43]
	v_mfma_f32_16x16x32_bf16 v[36:39], v[150:153], v[194:197], v[36:39]
	v_mfma_f32_16x16x32_bf16 v[32:35], v[158:161], v[194:197], v[32:35]
	v_mfma_f32_16x16x32_bf16 v[60:63], v[154:157], v[170:173], v[60:63]
	v_mfma_f32_16x16x32_bf16 v[56:59], v[162:165], v[170:173], v[56:59]
	v_mfma_f32_16x16x32_bf16 v[52:55], v[154:157], v[178:181], v[52:55]
	v_mfma_f32_16x16x32_bf16 v[48:51], v[162:165], v[178:181], v[48:51]
	v_mfma_f32_16x16x32_bf16 v[44:47], v[154:157], v[186:189], v[44:47]
	v_mfma_f32_16x16x32_bf16 v[40:43], v[162:165], v[186:189], v[40:43]
	v_mfma_f32_16x16x32_bf16 v[36:39], v[154:157], v[198:201], v[36:39]
	v_mfma_f32_16x16x32_bf16 v[32:35], v[162:165], v[198:201], v[32:35]
	s_barrier
	s_setprio 0
	ds_read_b128 v[150:153], v138
	ds_read_b128 v[154:157], v138 offset:1024
	ds_read_b128 v[158:161], v138 offset:2048
	ds_read_b128 v[162:165], v138 offset:3072
	s_add_u32 m0, s2, s31
	s_nop 0
	s_add_u32 vcc_lo, s50, s64
	s_addc_u32 vcc_hi, s51, s65
	global_load_lds_dwordx4 v128, vcc
	v_lshl_add_u64 v[254:255], v[236:237], 0, s[64:65]
	s_add_u32 m0, s2, s31
	s_add_u32 m0, m0, 0x2000
	s_nop 0
	global_load_lds_dwordx4 v130, vcc
	s_waitcnt vmcnt(6)
	s_setprio 1
	s_barrier
	v_mfma_f32_16x16x32_bf16 v[28:31], v[202:205], v[166:169], v[28:31]
	v_mfma_f32_16x16x32_bf16 v[24:27], v[224:227], v[166:169], v[24:27]
	v_mfma_f32_16x16x32_bf16 v[20:23], v[202:205], v[174:177], v[20:23]
	v_mfma_f32_16x16x32_bf16 v[16:19], v[224:227], v[174:177], v[16:19]
	v_mfma_f32_16x16x32_bf16 v[12:15], v[202:205], v[182:185], v[12:15]
	v_mfma_f32_16x16x32_bf16 v[8:11], v[224:227], v[182:185], v[8:11]
	v_mfma_f32_16x16x32_bf16 v[4:7], v[202:205], v[194:197], v[4:7]
	v_mfma_f32_16x16x32_bf16 v[0:3], v[224:227], v[194:197], v[0:3]
	v_mfma_f32_16x16x32_bf16 v[28:31], v[206:209], v[170:173], v[28:31]
	ds_read_b128 v[166:169], v137
	v_mfma_f32_16x16x32_bf16 v[24:27], v[228:231], v[170:173], v[24:27]
	v_mfma_f32_16x16x32_bf16 v[20:23], v[206:209], v[178:181], v[20:23]
	ds_read_b128 v[174:177], v137 offset:2048
	v_mfma_f32_16x16x32_bf16 v[16:19], v[228:231], v[178:181], v[16:19]
	v_mfma_f32_16x16x32_bf16 v[12:15], v[206:209], v[186:189], v[12:15]
	ds_read_b128 v[182:185], v137 offset:4096
	v_mfma_f32_16x16x32_bf16 v[8:11], v[228:231], v[186:189], v[8:11]
	v_mfma_f32_16x16x32_bf16 v[4:7], v[206:209], v[198:201], v[4:7]
	ds_read_b128 v[194:197], v137 offset:6144
	v_mfma_f32_16x16x32_bf16 v[0:3], v[228:231], v[198:201], v[0:3]
	s_add_i32 s1, s1, 2
	v_lshl_add_u64 v[128:129], v[128:129], 0, s[74:75]
	v_lshl_add_u64 v[130:131], v[130:131], 0, s[74:75]
	v_lshl_add_u64 v[132:133], v[132:133], 0, s[74:75]
	s_cmp_lt_u32 s1, 28
	v_lshl_add_u64 v[134:135], v[134:135], 0, s[74:75]
	s_barrier
	s_setprio 0
	s_cbranch_scc1 .LBB0_436
	v_lshlrev_b32_e32 v128, 3, v142
	v_lshlrev_b32_e32 v129, 5, v142
	v_and_b32_e32 v128, 0xffff0, v128
	v_and_b32_e32 v129, 32, v129
	s_or_b32 s2, s0, 0x80
	v_add_u32_e32 v129, v129, v144
	v_add_lshl_u32 v128, v143, v128, 12
	s_ashr_i32 s3, s2, 31
	v_lshl_add_u32 v192, v129, 1, v128
	v_lshlrev_b32_e32 v128, 3, v145
	v_lshlrev_b32_e32 v129, 5, v145
	s_lshl_b64 s[2:3], s[2:3], 12
	v_and_b32_e32 v128, 0xffff0, v128
	v_and_b32_e32 v129, 32, v129
	s_add_u32 s2, s16, s2
	v_add_u32_e32 v129, v129, v147
	v_add_lshl_u32 v128, v146, v128, 12
	s_addc_u32 s3, s17, s3
	v_lshl_add_u32 v146, v129, 1, v128
	v_mov_b32_e32 v147, v193
	v_lshl_add_u64 v[186:187], s[2:3], 0, v[192:193]
	s_mov_b64 s[8:9], 0xf80
	v_readfirstlane_b32 s1, v148
	v_lshl_add_u64 v[186:187], v[186:187], 0, s[8:9]
	s_mov_b32 m0, s1
	v_lshl_add_u64 v[146:147], s[2:3], 0, v[146:147]
	v_readfirstlane_b32 s1, v149
	ds_read_b128 v[128:131], v138
	ds_read_b128 v[132:135], v138 offset:1024
	ds_read_b128 v[142:145], v138 offset:2048
	ds_read_b128 v[150:153], v138 offset:3072
	ds_read_b128 v[154:157], v137
	ds_read_b128 v[158:161], v137 offset:1024
	ds_read_b128 v[162:165], v137 offset:2048
	ds_read_b128 v[166:169], v137 offset:3072
	ds_read_b128 v[170:173], v137 offset:4096
	ds_read_b128 v[174:177], v137 offset:5120
	ds_read_b128 v[178:181], v137 offset:6144
	ds_read_b128 v[182:185], v137 offset:7168
	global_load_lds_dwordx4 v[186:187], off
	v_lshl_add_u64 v[146:147], v[146:147], 0, s[8:9]
	s_mov_b32 m0, s1
	s_nop 0
	global_load_lds_dwordx4 v[146:147], off
	s_barrier
	s_waitcnt lgkmcnt(0)
	s_setprio 1
	s_waitcnt lgkmcnt(0)
	v_mfma_f32_16x16x32_bf16 v[124:127], v[128:131], v[154:157], v[124:127]
	v_mfma_f32_16x16x32_bf16 v[112:115], v[142:145], v[162:165], v[112:115]
	v_mfma_f32_16x16x32_bf16 v[104:107], v[142:145], v[170:173], v[104:107]
	v_mfma_f32_16x16x32_bf16 v[96:99], v[142:145], v[178:181], v[96:99]
	v_mfma_f32_16x16x32_bf16 v[124:127], v[132:135], v[158:161], v[124:127]
	v_mfma_f32_16x16x32_bf16 v[120:123], v[142:145], v[154:157], v[120:123]
	v_mfma_f32_16x16x32_bf16 v[116:119], v[128:131], v[162:165], v[116:119]
	v_mfma_f32_16x16x32_bf16 v[112:115], v[150:153], v[166:169], v[112:115]
	v_mfma_f32_16x16x32_bf16 v[108:111], v[128:131], v[170:173], v[108:111]
	v_mfma_f32_16x16x32_bf16 v[104:107], v[150:153], v[174:177], v[104:107]
	v_mfma_f32_16x16x32_bf16 v[100:103], v[128:131], v[178:181], v[100:103]
	v_mfma_f32_16x16x32_bf16 v[96:99], v[150:153], v[182:185], v[96:99]
	v_mfma_f32_16x16x32_bf16 v[146:149], v[150:153], v[158:161], v[120:123]
	v_mfma_f32_16x16x32_bf16 v[186:189], v[132:135], v[166:169], v[116:119]
	v_mfma_f32_16x16x32_bf16 v[194:197], v[132:135], v[174:177], v[108:111]
	v_mfma_f32_16x16x32_bf16 v[198:201], v[132:135], v[182:185], v[100:103]
	s_setprio 0
	s_barrier
; #define WAIT_V(n) asm volatile("s_waitcnt vmcnt(" #n ")" ::: "memory")
; #define WAIT_L(n) asm volatile("s_waitcnt lgkmcnt(" #n ")" ::: "memory")
; #define BAR __builtin_amdgcn_s_barrier()
; #define LDA(dst, b, h) _Pragma("unroll") for (int m = 0; m < 4; ++m) _Pragma("unroll") for (int k = 0; k < 2; ++k) \
;     dst[m][k] = *reinterpret_cast<const bf16x8*>((char*)shm + abase + (((b) * 2 + (h)) * 16384 + (m * 2 + k) * 1024))
; #define LDB(dst, b, h) _Pragma("unroll") for (int n = 0; n < 2; ++n) _Pragma("unroll") for (int k = 0; k < 2; ++k) \
;     dst[n][k] = *reinterpret_cast<const bf16x8*>((char*)shm + bbase + (((b) * 2 + (h)) * 16384 + (n * 2 + k) * 1024))
; template <bool SWAP>
; __device__ __forceinline__ void gemm_main(const u16* __restrict__ A, const u16* __restrict__ Bt, int brow, int bcol,
;                                           u16* shm, f32x4 (&acc)[2][2][4][2]) {
;     ...
;     LDB(B1, 0, 1); BAR; WAIT_L(0); MMA(0, 1, At, B1); BAR;
;     LDA(At, 0, 1); WAIT_V(4); BAR; WAIT_L(0); MMA(1, 0, At, B0); MMA(1, 1, At, B1); BAR; }
;   { LDB(B0, 1, 0); LDA(At, 1, 0); WAIT_V(2); BAR; WAIT_L(0); MMA(0, 0, At, B0); BAR;
	s_nop 0
	ds_read_b128 v[100:103], v138 offset:16384
	ds_read_b128 v[108:111], v138 offset:17408
	ds_read_b128 v[116:119], v138 offset:18432
	ds_read_b128 v[120:123], v138 offset:19456
	s_barrier
	s_waitcnt lgkmcnt(0)
	s_setprio 1
	s_waitcnt lgkmcnt(0)
	v_mfma_f32_16x16x32_bf16 v[88:91], v[116:119], v[154:157], v[88:91]
	v_mfma_f32_16x16x32_bf16 v[80:83], v[116:119], v[162:165], v[80:83]
	v_mfma_f32_16x16x32_bf16 v[72:75], v[116:119], v[170:173], v[72:75]
	v_mfma_f32_16x16x32_bf16 v[64:67], v[116:119], v[178:181], v[64:67]
	v_mfma_f32_16x16x32_bf16 v[92:95], v[100:103], v[154:157], v[92:95]
	v_mfma_f32_16x16x32_bf16 v[88:91], v[120:123], v[158:161], v[88:91]
	v_mfma_f32_16x16x32_bf16 v[84:87], v[100:103], v[162:165], v[84:87]
	v_mfma_f32_16x16x32_bf16 v[80:83], v[120:123], v[166:169], v[80:83]
	v_mfma_f32_16x16x32_bf16 v[76:79], v[100:103], v[170:173], v[76:79]
	v_mfma_f32_16x16x32_bf16 v[72:75], v[120:123], v[174:177], v[72:75]
	v_mfma_f32_16x16x32_bf16 v[68:71], v[100:103], v[178:181], v[68:71]
	v_mfma_f32_16x16x32_bf16 v[64:67], v[120:123], v[182:185], v[64:67]
	v_mfma_f32_16x16x32_bf16 v[202:205], v[108:111], v[158:161], v[92:95]
	v_mfma_f32_16x16x32_bf16 v[154:157], v[108:111], v[166:169], v[84:87]
	v_mfma_f32_16x16x32_bf16 v[158:161], v[108:111], v[174:177], v[76:79]
	v_mfma_f32_16x16x32_bf16 v[162:165], v[108:111], v[182:185], v[68:71]
	s_setprio 0
	s_barrier
	s_nop 0
	ds_read_b128 v[68:71], v137 offset:16384
	ds_read_b128 v[76:79], v137 offset:17408
	ds_read_b128 v[84:87], v137 offset:18432
	ds_read_b128 v[92:95], v137 offset:19456
	ds_read_b128 v[166:169], v137 offset:20480
	ds_read_b128 v[170:173], v137 offset:21504
	ds_read_b128 v[174:177], v137 offset:22528
	ds_read_b128 v[178:181], v137 offset:23552
	s_waitcnt vmcnt(4)
	s_barrier
	s_waitcnt lgkmcnt(0)
	s_setprio 1
	s_waitcnt lgkmcnt(0)
	v_mfma_f32_16x16x32_bf16 v[60:63], v[128:131], v[68:71], v[60:63]
	v_mfma_f32_16x16x32_bf16 v[56:59], v[142:145], v[68:71], v[56:59]
	v_mfma_f32_16x16x32_bf16 v[48:51], v[142:145], v[84:87], v[48:51]
	v_mfma_f32_16x16x32_bf16 v[40:43], v[142:145], v[166:169], v[40:43]
	v_mfma_f32_16x16x32_bf16 v[32:35], v[142:145], v[174:177], v[32:35]
	v_mfma_f32_16x16x32_bf16 v[60:63], v[132:135], v[76:79], v[60:63]
	v_mfma_f32_16x16x32_bf16 v[56:59], v[150:153], v[76:79], v[56:59]
	v_mfma_f32_16x16x32_bf16 v[52:55], v[128:131], v[84:87], v[52:55]
	v_mfma_f32_16x16x32_bf16 v[48:51], v[150:153], v[92:95], v[48:51]
	v_mfma_f32_16x16x32_bf16 v[44:47], v[128:131], v[166:169], v[44:47]
	v_mfma_f32_16x16x32_bf16 v[40:43], v[150:153], v[170:173], v[40:43]
	v_mfma_f32_16x16x32_bf16 v[36:39], v[128:131], v[174:177], v[36:39]
	v_mfma_f32_16x16x32_bf16 v[32:35], v[150:153], v[178:181], v[32:35]
	v_mfma_f32_16x16x32_bf16 v[182:185], v[132:135], v[92:95], v[52:55]
	v_mfma_f32_16x16x32_bf16 v[206:209], v[132:135], v[170:173], v[44:47]
	v_mfma_f32_16x16x32_bf16 v[128:131], v[132:135], v[178:181], v[36:39]
	s_setprio 0
	s_setprio 1
	v_mfma_f32_16x16x32_bf16 v[24:27], v[116:119], v[68:71], v[24:27]
	v_mfma_f32_16x16x32_bf16 v[16:19], v[116:119], v[84:87], v[16:19]
	v_mfma_f32_16x16x32_bf16 v[8:11], v[116:119], v[166:169], v[8:11]
	v_mfma_f32_16x16x32_bf16 v[0:3], v[116:119], v[174:177], v[0:3]
	v_mfma_f32_16x16x32_bf16 v[28:31], v[100:103], v[68:71], v[28:31]
	v_mfma_f32_16x16x32_bf16 v[24:27], v[120:123], v[76:79], v[24:27]
	v_mfma_f32_16x16x32_bf16 v[20:23], v[100:103], v[84:87], v[20:23]
	v_mfma_f32_16x16x32_bf16 v[16:19], v[120:123], v[92:95], v[16:19]
	v_mfma_f32_16x16x32_bf16 v[12:15], v[100:103], v[166:169], v[12:15]
	v_mfma_f32_16x16x32_bf16 v[8:11], v[120:123], v[170:173], v[8:11]
	v_mfma_f32_16x16x32_bf16 v[4:7], v[100:103], v[174:177], v[4:7]
	v_mfma_f32_16x16x32_bf16 v[0:3], v[120:123], v[178:181], v[0:3]
	v_mfma_f32_16x16x32_bf16 v[132:135], v[108:111], v[76:79], v[28:31]
	v_mfma_f32_16x16x32_bf16 v[142:145], v[108:111], v[92:95], v[20:23]
	v_mfma_f32_16x16x32_bf16 v[150:153], v[108:111], v[170:173], v[12:15]
	v_mfma_f32_16x16x32_bf16 v[166:169], v[108:111], v[178:181], v[4:7]
	s_setprio 0
	s_barrier
	s_nop 0
	ds_read_b128 v[4:7], v138 offset:32768
	ds_read_b128 v[12:15], v138 offset:33792
	ds_read_b128 v[170:173], v138 offset:34816
	ds_read_b128 v[174:177], v138 offset:35840
	ds_read_b128 v[20:23], v137 offset:32768
	ds_read_b128 v[28:31], v137 offset:33792
	ds_read_b128 v[36:39], v137 offset:34816
	ds_read_b128 v[44:47], v137 offset:35840
	ds_read_b128 v[52:55], v137 offset:36864
	ds_read_b128 v[178:181], v137 offset:37888
	ds_read_b128 v[224:227], v137 offset:38912
	ds_read_b128 v[228:231], v137 offset:39936
	s_waitcnt vmcnt(2)
	s_barrier
; #define WAIT_V(n) asm volatile("s_waitcnt vmcnt(" #n ")" ::: "memory")
; #define WAIT_L(n) asm volatile("s_waitcnt lgkmcnt(" #n ")" ::: "memory")
; #define BAR __builtin_amdgcn_s_barrier()
; #define LDA(dst, b, h) _Pragma("unroll") for (int m = 0; m < 4; ++m) _Pragma("unroll") for (int k = 0; k < 2; ++k) \
;     dst[m][k] = *reinterpret_cast<const bf16x8*>((char*)shm + abase + (((b) * 2 + (h)) * 16384 + (m * 2 + k) * 1024))
; #define LDB(dst, b, h) _Pragma("unroll") for (int n = 0; n < 2; ++n) _Pragma("unroll") for (int k = 0; k < 2; ++k) \
;     dst[n][k] = *reinterpret_cast<const bf16x8*>((char*)shm + bbase + (((b) * 2 + (h)) * 16384 + (n * 2 + k) * 1024))
; template <bool SWAP>
; __device__ __forceinline__ void gemm_main(const u16* __restrict__ A, const u16* __restrict__ Bt, int brow, int bcol,
;                                           u16* shm, f32x4 (&acc)[2][2][4][2]) {
;     ...
;   { LDB(B0, 1, 0); LDA(At, 1, 0); WAIT_V(2); BAR; WAIT_L(0); MMA(0, 0, At, B0); BAR;
;     LDB(B1, 1, 1); WAIT_V(0); BAR; WAIT_L(0); MMA(0, 1, At, B1); BAR;
;     LDA(At, 1, 1); BAR; WAIT_L(0); MMA(1, 0, At, B0); MMA(1, 1, At, B1); BAR; }
;   if (wr == 0) BAR;
	s_waitcnt lgkmcnt(0)
	s_setprio 1
	s_waitcnt lgkmcnt(0)
	v_mfma_f32_16x16x32_bf16 v[68:71], v[4:7], v[20:23], v[124:127]
	v_mfma_f32_16x16x32_bf16 v[120:123], v[12:15], v[28:31], v[68:71]
	v_mfma_f32_16x16x32_bf16 v[68:71], v[170:173], v[20:23], v[146:149]
	v_mfma_f32_16x16x32_bf16 v[116:119], v[174:177], v[28:31], v[68:71]
	v_mfma_f32_16x16x32_bf16 v[68:71], v[4:7], v[36:39], v[186:189]
	v_mfma_f32_16x16x32_bf16 v[108:111], v[12:15], v[44:47], v[68:71]
	v_mfma_f32_16x16x32_bf16 v[68:71], v[170:173], v[36:39], v[112:115]
	v_mfma_f32_16x16x32_bf16 v[100:103], v[174:177], v[44:47], v[68:71]
	v_mfma_f32_16x16x32_bf16 v[68:71], v[4:7], v[52:55], v[194:197]
	v_mfma_f32_16x16x32_bf16 v[92:95], v[12:15], v[178:181], v[68:71]
	v_mfma_f32_16x16x32_bf16 v[68:71], v[170:173], v[52:55], v[104:107]
	v_mfma_f32_16x16x32_bf16 v[84:87], v[174:177], v[178:181], v[68:71]
	v_mfma_f32_16x16x32_bf16 v[68:71], v[4:7], v[224:227], v[198:201]
	v_mfma_f32_16x16x32_bf16 v[76:79], v[12:15], v[228:231], v[68:71]
	v_mfma_f32_16x16x32_bf16 v[68:71], v[170:173], v[224:227], v[96:99]
	v_mfma_f32_16x16x32_bf16 v[68:71], v[174:177], v[228:231], v[68:71]
	s_setprio 0
	s_barrier
	ds_read_b128 v[146:149], v138 offset:49152
	ds_read_b128 v[186:189], v138 offset:50176
	ds_read_b128 v[194:197], v138 offset:51200
	ds_read_b128 v[198:201], v138 offset:52224
	s_waitcnt vmcnt(0)
	s_barrier
	s_waitcnt lgkmcnt(0)
	s_setprio 1
	s_waitcnt lgkmcnt(0)
	v_mfma_f32_16x16x32_bf16 v[96:99], v[146:149], v[20:23], v[202:205]
	v_mfma_f32_16x16x32_bf16 v[20:23], v[194:197], v[20:23], v[88:91]
	v_mfma_f32_16x16x32_bf16 v[112:115], v[198:201], v[28:31], v[20:23]
	v_mfma_f32_16x16x32_bf16 v[20:23], v[146:149], v[36:39], v[154:157]
	v_mfma_f32_16x16x32_bf16 v[104:107], v[186:189], v[44:47], v[20:23]
	v_mfma_f32_16x16x32_bf16 v[20:23], v[194:197], v[36:39], v[80:83]
	v_mfma_f32_16x16x32_bf16 v[124:127], v[186:189], v[28:31], v[96:99]
	v_mfma_f32_16x16x32_bf16 v[96:99], v[198:201], v[44:47], v[20:23]
	v_mfma_f32_16x16x32_bf16 v[20:23], v[146:149], v[52:55], v[158:161]
	v_mfma_f32_16x16x32_bf16 v[88:91], v[186:189], v[178:181], v[20:23]
	v_mfma_f32_16x16x32_bf16 v[20:23], v[194:197], v[52:55], v[72:75]
	v_mfma_f32_16x16x32_bf16 v[80:83], v[198:201], v[178:181], v[20:23]
	v_mfma_f32_16x16x32_bf16 v[20:23], v[146:149], v[224:227], v[162:165]
	v_mfma_f32_16x16x32_bf16 v[72:75], v[186:189], v[228:231], v[20:23]
	v_mfma_f32_16x16x32_bf16 v[20:23], v[194:197], v[224:227], v[64:67]
	v_mfma_f32_16x16x32_bf16 v[64:67], v[198:201], v[228:231], v[20:23]
	s_setprio 0
	s_barrier
	ds_read_b128 v[154:157], v137 offset:49152
	ds_read_b128 v[158:161], v137 offset:50176
	ds_read_b128 v[162:165], v137 offset:51200
	ds_read_b128 v[178:181], v137 offset:52224
	ds_read_b128 v[202:205], v137 offset:53248
	ds_read_b128 v[224:227], v137 offset:54272
	ds_read_b128 v[228:231], v137 offset:55296
	ds_read_b128 v[232:235], v137 offset:56320
	s_barrier
	s_waitcnt lgkmcnt(0)
	s_setprio 1
	s_waitcnt lgkmcnt(0)
	v_mfma_f32_16x16x32_bf16 v[20:23], v[4:7], v[154:157], v[60:63]
	v_mfma_f32_16x16x32_bf16 v[60:63], v[12:15], v[158:161], v[20:23]
	v_mfma_f32_16x16x32_bf16 v[20:23], v[170:173], v[154:157], v[56:59]
	v_mfma_f32_16x16x32_bf16 v[52:55], v[174:177], v[158:161], v[20:23]
	v_mfma_f32_16x16x32_bf16 v[20:23], v[4:7], v[162:165], v[182:185]
	v_mfma_f32_16x16x32_bf16 v[44:47], v[12:15], v[178:181], v[20:23]
	v_mfma_f32_16x16x32_bf16 v[20:23], v[170:173], v[162:165], v[48:51]
	v_mfma_f32_16x16x32_bf16 v[36:39], v[174:177], v[178:181], v[20:23]
	v_mfma_f32_16x16x32_bf16 v[20:23], v[4:7], v[202:205], v[206:209]
	v_mfma_f32_16x16x32_bf16 v[4:7], v[4:7], v[228:231], v[128:131]
	v_mfma_f32_16x16x32_bf16 v[28:31], v[12:15], v[224:227], v[20:23]
	v_mfma_f32_16x16x32_bf16 v[20:23], v[170:173], v[202:205], v[40:43]
	v_mfma_f32_16x16x32_bf16 v[12:15], v[12:15], v[232:235], v[4:7]
	v_mfma_f32_16x16x32_bf16 v[4:7], v[170:173], v[228:231], v[32:35]
	v_mfma_f32_16x16x32_bf16 v[20:23], v[174:177], v[224:227], v[20:23]
	v_mfma_f32_16x16x32_bf16 v[4:7], v[174:177], v[232:235], v[4:7]
	s_setprio 0
	s_setprio 1
	v_mfma_f32_16x16x32_bf16 v[32:35], v[146:149], v[154:157], v[132:135]
	v_mfma_f32_16x16x32_bf16 v[24:27], v[194:197], v[154:157], v[24:27]
	v_mfma_f32_16x16x32_bf16 v[16:19], v[194:197], v[162:165], v[16:19]
	v_mfma_f32_16x16x32_bf16 v[56:59], v[186:189], v[158:161], v[32:35]
	v_mfma_f32_16x16x32_bf16 v[48:51], v[198:201], v[158:161], v[24:27]
	v_mfma_f32_16x16x32_bf16 v[24:27], v[146:149], v[162:165], v[142:145]
	v_mfma_f32_16x16x32_bf16 v[32:35], v[198:201], v[178:181], v[16:19]
	v_mfma_f32_16x16x32_bf16 v[16:19], v[146:149], v[202:205], v[150:153]
	v_mfma_f32_16x16x32_bf16 v[8:11], v[194:197], v[202:205], v[8:11]
	v_mfma_f32_16x16x32_bf16 v[40:43], v[186:189], v[178:181], v[24:27]
	v_mfma_f32_16x16x32_bf16 v[24:27], v[186:189], v[224:227], v[16:19]
	v_mfma_f32_16x16x32_bf16 v[16:19], v[198:201], v[224:227], v[8:11]
	v_mfma_f32_16x16x32_bf16 v[8:11], v[146:149], v[228:231], v[166:169]
	v_mfma_f32_16x16x32_bf16 v[0:3], v[194:197], v[228:231], v[0:3]
	v_mfma_f32_16x16x32_bf16 v[8:11], v[186:189], v[232:235], v[8:11]
	v_mfma_f32_16x16x32_bf16 v[0:3], v[198:201], v[232:235], v[0:3]
	s_setprio 0
	s_movk_i32 s1, 0x100
	v_cmp_gt_u32_e32 vcc, s1, v136
	s_barrier
	s_and_saveexec_b64 s[8:9], vcc
	s_cbranch_execz .LBB0_439
	s_barrier

; #define WAIT_V(n) asm volatile("s_waitcnt vmcnt(" #n ")" ::: "memory")
; #define WAIT_L(n) asm volatile("s_waitcnt lgkmcnt(" #n ")" ::: "memory")
; #define BAR __builtin_amdgcn_s_barrier()
; #define SCHED __builtin_amdgcn_sched_barrier(0)
; #define STAGE(P, BASE, br, kt) do { const char* _g = (const char*)((BASE) + (size_t)(br) * GK + (kt) * BK); \
;     __builtin_amdgcn_global_load_lds((const unsigned*)(_g + voff0), (unsigned*)((char*)(P) + tx * 16), 16, 0, 0); \
;     __builtin_amdgcn_global_load_lds((const unsigned*)(_g + voff1), (unsigned*)((char*)(P) + tx * 16 + 8192), 16, 0, 0); } while (0)
; #define LDA(dst, b, h) _Pragma("unroll") for (int m = 0; m < 4; ++m) _Pragma("unroll") for (int k = 0; k < 2; ++k) \
;     dst[m][k] = *reinterpret_cast<const bf16x8*>((char*)shm + abase + (((b) * 2 + (h)) * 16384 + (m * 2 + k) * 1024))
; #define LDB(dst, b, h) _Pragma("unroll") for (int n = 0; n < 2; ++n) _Pragma("unroll") for (int k = 0; k < 2; ++k) \
;     dst[n][k] = *reinterpret_cast<const bf16x8*>((char*)shm + bbase + (((b) * 2 + (h)) * 16384 + (n * 2 + k) * 1024))
; template <bool SWAP>
; __device__ __forceinline__ void gemm_main(const u16* __restrict__ A, const u16* __restrict__ Bt, int brow, int bcol,
;                                           u16* shm, f32x4 (&acc)[2][2][4][2]) {
;     ...
;     LDB(B0, 0, 0); SCHED; LDA(At, 0, 0); STAGE(SA(1, 1), A, brow + HALF, t + 1);
;     WAIT_L(8); BAR; WAIT_L(0); MMA(0, 0, At, B0); BAR; SCHED;
;     LDB(B1, 0, 1); STAGE(SB(0, 0), Bt, bcol, t + 2);
;     BAR; WAIT_L(0); MMA(0, 1, At, B1); BAR;
;     LDA(At, 0, 1); STAGE(SA(0, 0), A, brow, t + 2);
;     BAR; WAIT_L(0); MMA(1, 0, At, B0); BAR; SCHED;
;     STAGE(SB(0, 1), Bt, bcol + HALF, t + 2);
;     WAIT_V(6); BAR; MMA(1, 1, At, B1); BAR;
;     LDB(B0, 1, 0); SCHED; LDA(At, 1, 0); STAGE(SA(0, 1), A, brow + HALF, t + 2);
.LBB0_576:
	ds_read_b128 v[168:171], v137 offset:1024
	ds_read_b128 v[176:179], v137 offset:3072
	ds_read_b128 v[184:187], v137 offset:5120
	ds_read_b128 v[194:197], v137 offset:7168
	v_add_u32_e32 v192, 0, v140
	v_add_u32_e32 v146, 0xc000, v192
	v_add_u32_e32 v147, 0xe000, v192
	s_add_u32 m0, s3, 0xc000
	v_lshl_add_u64 v[232:233], s[4:5], 0, v[134:135]
	s_add_u32 vcc_lo, s4, s10
	s_addc_u32 vcc_hi, s5, s11
	global_load_lds_dwordx4 v132, vcc
	s_add_u32 m0, s3, 0xe000
	s_nop 0
	global_load_lds_dwordx4 v134, vcc
	s_waitcnt lgkmcnt(8)
	s_setprio 1
	s_barrier
	s_waitcnt lgkmcnt(0)
	v_mfma_f32_16x16x32_bf16 v[124:127], v[148:151], v[164:167], v[124:127]
	v_mfma_f32_16x16x32_bf16 v[120:123], v[156:159], v[164:167], v[120:123]
	v_mfma_f32_16x16x32_bf16 v[116:119], v[148:151], v[172:175], v[116:119]
	v_mfma_f32_16x16x32_bf16 v[112:115], v[156:159], v[172:175], v[112:115]
	v_mfma_f32_16x16x32_bf16 v[108:111], v[148:151], v[180:183], v[108:111]
	v_mfma_f32_16x16x32_bf16 v[104:107], v[156:159], v[180:183], v[104:107]
	v_mfma_f32_16x16x32_bf16 v[100:103], v[148:151], v[188:191], v[100:103]
	v_mfma_f32_16x16x32_bf16 v[96:99], v[156:159], v[188:191], v[96:99]
	v_mfma_f32_16x16x32_bf16 v[124:127], v[152:155], v[168:171], v[124:127]
	v_mfma_f32_16x16x32_bf16 v[120:123], v[160:163], v[168:171], v[120:123]
	v_mfma_f32_16x16x32_bf16 v[116:119], v[152:155], v[176:179], v[116:119]
	v_mfma_f32_16x16x32_bf16 v[112:115], v[160:163], v[176:179], v[112:115]
	v_mfma_f32_16x16x32_bf16 v[108:111], v[152:155], v[184:187], v[108:111]
	v_mfma_f32_16x16x32_bf16 v[104:107], v[160:163], v[184:187], v[104:107]
	v_mfma_f32_16x16x32_bf16 v[100:103], v[152:155], v[194:197], v[100:103]
	v_mfma_f32_16x16x32_bf16 v[96:99], v[160:163], v[194:197], v[96:99]
	s_barrier
	s_setprio 0
	ds_read_b128 v[198:201], v138 offset:16384
	ds_read_b128 v[202:205], v138 offset:17408
	ds_read_b128 v[206:209], v138 offset:18432
	ds_read_b128 v[226:229], v138 offset:19456
	v_lshl_add_u64 v[234:235], s[4:5], 0, v[128:129]
	s_add_u32 m0, s3, s28
	s_nop 0
	s_add_u32 vcc_lo, s4, s12
	s_addc_u32 vcc_hi, s5, s13
	global_load_lds_dwordx4 v128, vcc
	v_lshl_add_u64 v[236:237], s[4:5], 0, v[130:131]
	s_add_u32 m0, s3, s28
	s_add_u32 m0, m0, 0x2000
	s_nop 0
	global_load_lds_dwordx4 v130, vcc
	s_setprio 1
	s_barrier
	s_waitcnt lgkmcnt(0)
	v_mfma_f32_16x16x32_bf16 v[92:95], v[198:201], v[164:167], v[92:95]
	v_mfma_f32_16x16x32_bf16 v[88:91], v[206:209], v[164:167], v[88:91]
	v_mfma_f32_16x16x32_bf16 v[84:87], v[198:201], v[172:175], v[84:87]
	v_mfma_f32_16x16x32_bf16 v[80:83], v[206:209], v[172:175], v[80:83]
	v_mfma_f32_16x16x32_bf16 v[76:79], v[198:201], v[180:183], v[76:79]
	v_mfma_f32_16x16x32_bf16 v[72:75], v[206:209], v[180:183], v[72:75]
	v_mfma_f32_16x16x32_bf16 v[68:71], v[198:201], v[188:191], v[68:71]
	v_mfma_f32_16x16x32_bf16 v[64:67], v[206:209], v[188:191], v[64:67]
	v_mfma_f32_16x16x32_bf16 v[92:95], v[202:205], v[168:171], v[92:95]
	ds_read_b128 v[164:167], v137 offset:16384
	v_mfma_f32_16x16x32_bf16 v[88:91], v[226:229], v[168:171], v[88:91]
	v_mfma_f32_16x16x32_bf16 v[84:87], v[202:205], v[176:179], v[84:87]
	ds_read_b128 v[172:175], v137 offset:18432
	v_mfma_f32_16x16x32_bf16 v[80:83], v[226:229], v[176:179], v[80:83]
	v_mfma_f32_16x16x32_bf16 v[76:79], v[202:205], v[184:187], v[76:79]
	ds_read_b128 v[180:183], v137 offset:20480
	v_mfma_f32_16x16x32_bf16 v[72:75], v[226:229], v[184:187], v[72:75]
	v_mfma_f32_16x16x32_bf16 v[68:71], v[202:205], v[194:197], v[68:71]
	ds_read_b128 v[188:191], v137 offset:22528
	v_mfma_f32_16x16x32_bf16 v[64:67], v[226:229], v[194:197], v[64:67]
	s_barrier
	s_setprio 0
	ds_read_b128 v[168:171], v137 offset:17408
	ds_read_b128 v[176:179], v137 offset:19456
	ds_read_b128 v[184:187], v137 offset:21504
	ds_read_b128 v[194:197], v137 offset:23552
	s_add_u32 m0, s3, 0x0
	s_nop 0
	s_add_u32 vcc_lo, s4, s14
	s_addc_u32 vcc_hi, s5, s15
	global_load_lds_dwordx4 v132, vcc
	s_add_u32 m0, s3, 0x2000
	s_nop 0
	global_load_lds_dwordx4 v134, vcc
	s_waitcnt vmcnt(8)
	s_setprio 1
	s_barrier
	s_waitcnt lgkmcnt(0)
	v_mfma_f32_16x16x32_bf16 v[60:63], v[148:151], v[164:167], v[60:63]
	v_mfma_f32_16x16x32_bf16 v[56:59], v[156:159], v[164:167], v[56:59]
	v_mfma_f32_16x16x32_bf16 v[52:55], v[148:151], v[172:175], v[52:55]
	v_mfma_f32_16x16x32_bf16 v[48:51], v[156:159], v[172:175], v[48:51]
	v_mfma_f32_16x16x32_bf16 v[44:47], v[148:151], v[180:183], v[44:47]
	v_mfma_f32_16x16x32_bf16 v[40:43], v[156:159], v[180:183], v[40:43]
	v_mfma_f32_16x16x32_bf16 v[36:39], v[148:151], v[188:191], v[36:39]
	v_mfma_f32_16x16x32_bf16 v[32:35], v[156:159], v[188:191], v[32:35]
	v_mfma_f32_16x16x32_bf16 v[60:63], v[152:155], v[168:171], v[60:63]
	v_mfma_f32_16x16x32_bf16 v[56:59], v[160:163], v[168:171], v[56:59]
	v_mfma_f32_16x16x32_bf16 v[52:55], v[152:155], v[176:179], v[52:55]
	v_mfma_f32_16x16x32_bf16 v[48:51], v[160:163], v[176:179], v[48:51]
	v_mfma_f32_16x16x32_bf16 v[44:47], v[152:155], v[184:187], v[44:47]
	v_mfma_f32_16x16x32_bf16 v[40:43], v[160:163], v[184:187], v[40:43]
	v_mfma_f32_16x16x32_bf16 v[36:39], v[152:155], v[194:197], v[36:39]
	v_mfma_f32_16x16x32_bf16 v[32:35], v[160:163], v[194:197], v[32:35]
	s_barrier
	s_setprio 0
	ds_read_b128 v[148:151], v138 offset:32768
	ds_read_b128 v[152:155], v138 offset:33792
	ds_read_b128 v[156:159], v138 offset:34816
	ds_read_b128 v[160:163], v138 offset:35840
	s_add_u32 m0, s3, s29
	s_nop 0
	s_add_u32 vcc_lo, s4, s80
	s_addc_u32 vcc_hi, s5, s81
	global_load_lds_dwordx4 v128, vcc
	s_add_u32 m0, s3, s29
	s_add_u32 m0, m0, 0x2000
	s_nop 0
	global_load_lds_dwordx4 v130, vcc
	s_waitcnt vmcnt(6)
	s_setprio 1
	s_barrier
; #define WAIT_V(n) asm volatile("s_waitcnt vmcnt(" #n ")" ::: "memory")
; #define WAIT_L(n) asm volatile("s_waitcnt lgkmcnt(" #n ")" ::: "memory")
; #define BAR __builtin_amdgcn_s_barrier()
; #define SCHED __builtin_amdgcn_sched_barrier(0)
; #define STAGE(P, BASE, br, kt) do { const char* _g = (const char*)((BASE) + (size_t)(br) * GK + (kt) * BK); \
;     __builtin_amdgcn_global_load_lds((const unsigned*)(_g + voff0), (unsigned*)((char*)(P) + tx * 16), 16, 0, 0); \
;     __builtin_amdgcn_global_load_lds((const unsigned*)(_g + voff1), (unsigned*)((char*)(P) + tx * 16 + 8192), 16, 0, 0); } while (0)
; #define LDA(dst, b, h) _Pragma("unroll") for (int m = 0; m < 4; ++m) _Pragma("unroll") for (int k = 0; k < 2; ++k) \
;     dst[m][k] = *reinterpret_cast<const bf16x8*>((char*)shm + abase + (((b) * 2 + (h)) * 16384 + (m * 2 + k) * 1024))
; #define LDB(dst, b, h) _Pragma("unroll") for (int n = 0; n < 2; ++n) _Pragma("unroll") for (int k = 0; k < 2; ++k) \
;     dst[n][k] = *reinterpret_cast<const bf16x8*>((char*)shm + bbase + (((b) * 2 + (h)) * 16384 + (n * 2 + k) * 1024))
; template <bool SWAP>
; __device__ __forceinline__ void gemm_main(const u16* __restrict__ A, const u16* __restrict__ Bt, int brow, int bcol,
;                                           u16* shm, f32x4 (&acc)[2][2][4][2]) {
;     ...
;     WAIT_V(6); BAR; MMA(1, 1, At, B1); BAR;
;     LDB(B0, 1, 0); SCHED; LDA(At, 1, 0); STAGE(SA(0, 1), A, brow + HALF, t + 2);
;     WAIT_L(8); BAR; WAIT_L(0); MMA(0, 0, At, B0); BAR; SCHED;
;     LDB(B1, 1, 1); STAGE(SB(1, 0), Bt, bcol, t + 3);
;     BAR; WAIT_L(0); MMA(0, 1, At, B1); BAR;
;     LDA(At, 1, 1); STAGE(SA(1, 0), A, brow, t + 3);
	v_mfma_f32_16x16x32_bf16 v[28:31], v[198:201], v[164:167], v[28:31]
	v_mfma_f32_16x16x32_bf16 v[24:27], v[206:209], v[164:167], v[24:27]
	v_mfma_f32_16x16x32_bf16 v[20:23], v[198:201], v[172:175], v[20:23]
	v_mfma_f32_16x16x32_bf16 v[16:19], v[206:209], v[172:175], v[16:19]
	v_mfma_f32_16x16x32_bf16 v[12:15], v[198:201], v[180:183], v[12:15]
	v_mfma_f32_16x16x32_bf16 v[8:11], v[206:209], v[180:183], v[8:11]
	v_mfma_f32_16x16x32_bf16 v[4:7], v[198:201], v[188:191], v[4:7]
	v_mfma_f32_16x16x32_bf16 v[0:3], v[206:209], v[188:191], v[0:3]
	v_mfma_f32_16x16x32_bf16 v[28:31], v[202:205], v[168:171], v[28:31]
	ds_read_b128 v[164:167], v137 offset:32768
	v_mfma_f32_16x16x32_bf16 v[24:27], v[226:229], v[168:171], v[24:27]
	v_mfma_f32_16x16x32_bf16 v[20:23], v[202:205], v[176:179], v[20:23]
	ds_read_b128 v[172:175], v137 offset:34816
	v_mfma_f32_16x16x32_bf16 v[16:19], v[226:229], v[176:179], v[16:19]
	v_mfma_f32_16x16x32_bf16 v[12:15], v[202:205], v[184:187], v[12:15]
	ds_read_b128 v[180:183], v137 offset:36864
	v_mfma_f32_16x16x32_bf16 v[8:11], v[226:229], v[184:187], v[8:11]
	v_mfma_f32_16x16x32_bf16 v[4:7], v[202:205], v[194:197], v[4:7]
	ds_read_b128 v[188:191], v137 offset:38912
	v_mfma_f32_16x16x32_bf16 v[0:3], v[226:229], v[194:197], v[0:3]
	s_barrier
	s_setprio 0
	ds_read_b128 v[168:171], v137 offset:33792
	ds_read_b128 v[176:179], v137 offset:35840
	ds_read_b128 v[184:187], v137 offset:37888
	ds_read_b128 v[194:197], v137 offset:39936
	s_add_u32 m0, s3, 0x4000
	s_nop 0
	s_add_u32 vcc_lo, s4, s66
	s_addc_u32 vcc_hi, s5, s67
	global_load_lds_dwordx4 v132, vcc
	s_add_u32 m0, s3, 0x6000
	s_nop 0
	global_load_lds_dwordx4 v134, vcc
	s_waitcnt lgkmcnt(8)
	s_setprio 1
	s_barrier
	s_waitcnt lgkmcnt(0)
	v_mfma_f32_16x16x32_bf16 v[124:127], v[148:151], v[164:167], v[124:127]
	v_mfma_f32_16x16x32_bf16 v[120:123], v[156:159], v[164:167], v[120:123]
	v_mfma_f32_16x16x32_bf16 v[116:119], v[148:151], v[172:175], v[116:119]
	v_mfma_f32_16x16x32_bf16 v[112:115], v[156:159], v[172:175], v[112:115]
	v_mfma_f32_16x16x32_bf16 v[108:111], v[148:151], v[180:183], v[108:111]
	v_mfma_f32_16x16x32_bf16 v[104:107], v[156:159], v[180:183], v[104:107]
	v_mfma_f32_16x16x32_bf16 v[100:103], v[148:151], v[188:191], v[100:103]
	v_mfma_f32_16x16x32_bf16 v[96:99], v[156:159], v[188:191], v[96:99]
	v_mfma_f32_16x16x32_bf16 v[124:127], v[152:155], v[168:171], v[124:127]
	v_mfma_f32_16x16x32_bf16 v[120:123], v[160:163], v[168:171], v[120:123]
	v_mfma_f32_16x16x32_bf16 v[116:119], v[152:155], v[176:179], v[116:119]
	v_mfma_f32_16x16x32_bf16 v[112:115], v[160:163], v[176:179], v[112:115]
	v_mfma_f32_16x16x32_bf16 v[108:111], v[152:155], v[184:187], v[108:111]
	v_mfma_f32_16x16x32_bf16 v[104:107], v[160:163], v[184:187], v[104:107]
	v_mfma_f32_16x16x32_bf16 v[100:103], v[152:155], v[194:197], v[100:103]
	v_mfma_f32_16x16x32_bf16 v[96:99], v[160:163], v[194:197], v[96:99]
	s_barrier
	s_setprio 0
	ds_read_b128 v[198:201], v138 offset:49152
	ds_read_b128 v[202:205], v138 offset:50176
	ds_read_b128 v[206:209], v138 offset:51200
	ds_read_b128 v[226:229], v138 offset:52224
	s_add_u32 m0, s3, s30
	s_nop 0
	s_add_u32 vcc_lo, s4, s86
	s_addc_u32 vcc_hi, s5, s87
	global_load_lds_dwordx4 v128, vcc
	v_lshl_add_u64 v[238:239], v[236:237], 0, s[86:87]
	s_add_u32 m0, s3, s30
	s_add_u32 m0, m0, 0x2000
	s_nop 0
	global_load_lds_dwordx4 v130, vcc
	s_setprio 1
	s_barrier
	s_waitcnt lgkmcnt(0)
	v_mfma_f32_16x16x32_bf16 v[92:95], v[198:201], v[164:167], v[92:95]
	v_mfma_f32_16x16x32_bf16 v[88:91], v[206:209], v[164:167], v[88:91]
	v_mfma_f32_16x16x32_bf16 v[84:87], v[198:201], v[172:175], v[84:87]
	v_mfma_f32_16x16x32_bf16 v[80:83], v[206:209], v[172:175], v[80:83]
	v_mfma_f32_16x16x32_bf16 v[76:79], v[198:201], v[180:183], v[76:79]
	v_mfma_f32_16x16x32_bf16 v[72:75], v[206:209], v[180:183], v[72:75]
	v_mfma_f32_16x16x32_bf16 v[68:71], v[198:201], v[188:191], v[68:71]
	v_mfma_f32_16x16x32_bf16 v[64:67], v[206:209], v[188:191], v[64:67]
	v_mfma_f32_16x16x32_bf16 v[92:95], v[202:205], v[168:171], v[92:95]
	ds_read_b128 v[164:167], v137 offset:49152
	v_mfma_f32_16x16x32_bf16 v[88:91], v[226:229], v[168:171], v[88:91]
	v_mfma_f32_16x16x32_bf16 v[84:87], v[202:205], v[176:179], v[84:87]
	ds_read_b128 v[172:175], v137 offset:51200
	v_mfma_f32_16x16x32_bf16 v[80:83], v[226:229], v[176:179], v[80:83]
	v_mfma_f32_16x16x32_bf16 v[76:79], v[202:205], v[184:187], v[76:79]
	ds_read_b128 v[180:183], v137 offset:53248
	v_mfma_f32_16x16x32_bf16 v[72:75], v[226:229], v[184:187], v[72:75]
	v_mfma_f32_16x16x32_bf16 v[68:71], v[202:205], v[194:197], v[68:71]
	ds_read_b128 v[188:191], v137 offset:55296
	v_mfma_f32_16x16x32_bf16 v[64:67], v[226:229], v[194:197], v[64:67]
	s_barrier
	s_setprio 0
	ds_read_b128 v[168:171], v137 offset:50176
	ds_read_b128 v[176:179], v137 offset:52224
	ds_read_b128 v[184:187], v137 offset:54272
	ds_read_b128 v[194:197], v137 offset:56320
	v_add_u32_e32 v225, 0x8000, v192
	s_add_u32 m0, s3, 0x8000
	s_nop 0
	s_add_u32 vcc_lo, s4, s26
	s_addc_u32 vcc_hi, s5, s27
	global_load_lds_dwordx4 v132, vcc
	v_lshl_add_u64 v[230:231], v[232:233], 0, s[26:27]
	s_add_u32 m0, s3, 0xa000
	s_nop 0
	global_load_lds_dwordx4 v134, vcc
	s_waitcnt vmcnt(8)
	s_setprio 1
	s_barrier
; #define WAIT_V(n) asm volatile("s_waitcnt vmcnt(" #n ")" ::: "memory")
; #define WAIT_L(n) asm volatile("s_waitcnt lgkmcnt(" #n ")" ::: "memory")
; #define BAR __builtin_amdgcn_s_barrier()
; #define SCHED __builtin_amdgcn_sched_barrier(0)
; #define STAGE(P, BASE, br, kt) do { const char* _g = (const char*)((BASE) + (size_t)(br) * GK + (kt) * BK); \
;     __builtin_amdgcn_global_load_lds((const unsigned*)(_g + voff0), (unsigned*)((char*)(P) + tx * 16), 16, 0, 0); \
;     __builtin_amdgcn_global_load_lds((const unsigned*)(_g + voff1), (unsigned*)((char*)(P) + tx * 16 + 8192), 16, 0, 0); } while (0)
; #define LDA(dst, b, h) _Pragma("unroll") for (int m = 0; m < 4; ++m) _Pragma("unroll") for (int k = 0; k < 2; ++k) \
;     dst[m][k] = *reinterpret_cast<const bf16x8*>((char*)shm + abase + (((b) * 2 + (h)) * 16384 + (m * 2 + k) * 1024))
; #define LDB(dst, b, h) _Pragma("unroll") for (int n = 0; n < 2; ++n) _Pragma("unroll") for (int k = 0; k < 2; ++k) \
;     dst[n][k] = *reinterpret_cast<const bf16x8*>((char*)shm + bbase + (((b) * 2 + (h)) * 16384 + (n * 2 + k) * 1024))
; template <bool SWAP>
; __device__ __forceinline__ void gemm_main(const u16* __restrict__ A, const u16* __restrict__ Bt, int brow, int bcol,
;                                           u16* shm, f32x4 (&acc)[2][2][4][2]) {
;     ...
;     BAR; WAIT_L(0); MMA(1, 0, At, B0); BAR; SCHED;
;     STAGE(SB(1, 1), Bt, bcol + HALF, t + 3);
;     WAIT_V(6); BAR; MMA(1, 1, At, B1); BAR;
;   }
;   { LDB(B0, 0, 0); LDA(At, 0, 0); STAGE(SA(1, 1), A, brow + HALF, nt - 1);
;     BAR; WAIT_L(0); MMA(0, 0, At, B0); BAR;
	s_waitcnt lgkmcnt(0)
	v_mfma_f32_16x16x32_bf16 v[60:63], v[148:151], v[164:167], v[60:63]
	v_mfma_f32_16x16x32_bf16 v[56:59], v[156:159], v[164:167], v[56:59]
	v_mfma_f32_16x16x32_bf16 v[52:55], v[148:151], v[172:175], v[52:55]
	v_mfma_f32_16x16x32_bf16 v[48:51], v[156:159], v[172:175], v[48:51]
	v_mfma_f32_16x16x32_bf16 v[44:47], v[148:151], v[180:183], v[44:47]
	v_mfma_f32_16x16x32_bf16 v[40:43], v[156:159], v[180:183], v[40:43]
	v_mfma_f32_16x16x32_bf16 v[36:39], v[148:151], v[188:191], v[36:39]
	v_mfma_f32_16x16x32_bf16 v[32:35], v[156:159], v[188:191], v[32:35]
	v_mfma_f32_16x16x32_bf16 v[60:63], v[152:155], v[168:171], v[60:63]
	v_mfma_f32_16x16x32_bf16 v[56:59], v[160:163], v[168:171], v[56:59]
	v_mfma_f32_16x16x32_bf16 v[52:55], v[152:155], v[176:179], v[52:55]
	v_mfma_f32_16x16x32_bf16 v[48:51], v[160:163], v[176:179], v[48:51]
	v_mfma_f32_16x16x32_bf16 v[44:47], v[152:155], v[184:187], v[44:47]
	v_mfma_f32_16x16x32_bf16 v[40:43], v[160:163], v[184:187], v[40:43]
	v_mfma_f32_16x16x32_bf16 v[36:39], v[152:155], v[194:197], v[36:39]
	v_mfma_f32_16x16x32_bf16 v[32:35], v[160:163], v[194:197], v[32:35]
	s_barrier
	s_setprio 0
	ds_read_b128 v[148:151], v138
	ds_read_b128 v[152:155], v138 offset:1024
	ds_read_b128 v[156:159], v138 offset:2048
	ds_read_b128 v[160:163], v138 offset:3072
	s_add_u32 m0, s3, s31
	s_nop 0
	s_add_u32 vcc_lo, s4, s56
	s_addc_u32 vcc_hi, s5, s57
	global_load_lds_dwordx4 v128, vcc
	v_lshl_add_u64 v[254:255], v[236:237], 0, s[56:57]
	s_add_u32 m0, s3, s31
	s_add_u32 m0, m0, 0x2000
	s_nop 0
	global_load_lds_dwordx4 v130, vcc
	s_waitcnt vmcnt(6)
	s_setprio 1
	s_barrier
	v_mfma_f32_16x16x32_bf16 v[28:31], v[198:201], v[164:167], v[28:31]
	v_mfma_f32_16x16x32_bf16 v[24:27], v[206:209], v[164:167], v[24:27]
	v_mfma_f32_16x16x32_bf16 v[20:23], v[198:201], v[172:175], v[20:23]
	v_mfma_f32_16x16x32_bf16 v[16:19], v[206:209], v[172:175], v[16:19]
	v_mfma_f32_16x16x32_bf16 v[12:15], v[198:201], v[180:183], v[12:15]
	v_mfma_f32_16x16x32_bf16 v[8:11], v[206:209], v[180:183], v[8:11]
	v_mfma_f32_16x16x32_bf16 v[4:7], v[198:201], v[188:191], v[4:7]
	v_mfma_f32_16x16x32_bf16 v[0:3], v[206:209], v[188:191], v[0:3]
	v_mfma_f32_16x16x32_bf16 v[28:31], v[202:205], v[168:171], v[28:31]
	ds_read_b128 v[164:167], v137
	v_mfma_f32_16x16x32_bf16 v[24:27], v[226:229], v[168:171], v[24:27]
	v_mfma_f32_16x16x32_bf16 v[20:23], v[202:205], v[176:179], v[20:23]
	ds_read_b128 v[172:175], v137 offset:2048
	v_mfma_f32_16x16x32_bf16 v[16:19], v[226:229], v[176:179], v[16:19]
	v_mfma_f32_16x16x32_bf16 v[12:15], v[202:205], v[184:187], v[12:15]
	ds_read_b128 v[180:183], v137 offset:4096
	v_mfma_f32_16x16x32_bf16 v[8:11], v[226:229], v[184:187], v[8:11]
	v_mfma_f32_16x16x32_bf16 v[4:7], v[202:205], v[194:197], v[4:7]
	ds_read_b128 v[188:191], v137 offset:6144
	v_mfma_f32_16x16x32_bf16 v[0:3], v[226:229], v[194:197], v[0:3]
	s_add_i32 s2, s2, 2
	s_add_u32 s4, s4, 0x100
	s_addc_u32 s5, s5, 0
	s_cmp_lt_u32 s2, 28
	s_barrier
	s_setprio 0
	s_cbranch_scc1 .LBB0_576
	v_lshlrev_b32_e32 v128, 3, v139
	v_lshlrev_b32_e32 v129, 5, v139
	v_and_b32_e32 v128, 0xffff0, v128
	v_and_b32_e32 v129, 32, v129
	v_add_u32_e32 v129, v129, v142
	v_add_lshl_u32 v128, v141, v128, 12
	v_lshl_add_u32 v192, v129, 1, v128
	v_lshlrev_b32_e32 v128, 3, v143
	v_lshlrev_b32_e32 v129, 5, v143
	v_and_b32_e32 v128, 0xffff0, v128
	v_and_b32_e32 v129, 32, v129
	v_add_u32_e32 v129, v129, v145
	v_add_lshl_u32 v128, v144, v128, 12
	v_lshl_add_u32 v144, v129, 1, v128
	v_mov_b32_e32 v145, v193
	v_lshl_add_u64 v[184:185], s[0:1], 0, v[192:193]
	s_mov_b64 s[4:5], 0xf80
	v_readfirstlane_b32 s2, v146
	v_lshl_add_u64 v[184:185], v[184:185], 0, s[4:5]
	s_mov_b32 m0, s2
	v_lshl_add_u64 v[144:145], s[0:1], 0, v[144:145]
	v_readfirstlane_b32 s0, v147
	ds_read_b128 v[128:131], v138
	ds_read_b128 v[132:135], v138 offset:1024
	ds_read_b128 v[140:143], v138 offset:2048
	ds_read_b128 v[148:151], v138 offset:3072
	ds_read_b128 v[152:155], v137
	ds_read_b128 v[156:159], v137 offset:1024
	ds_read_b128 v[160:163], v137 offset:2048
	ds_read_b128 v[164:167], v137 offset:3072
	ds_read_b128 v[168:171], v137 offset:4096
	ds_read_b128 v[172:175], v137 offset:5120
	ds_read_b128 v[176:179], v137 offset:6144
	ds_read_b128 v[180:183], v137 offset:7168
	global_load_lds_dwordx4 v[184:185], off
	v_lshl_add_u64 v[144:145], v[144:145], 0, s[4:5]
	s_mov_b32 m0, s0
	s_nop 0
	global_load_lds_dwordx4 v[144:145], off
	s_barrier
	s_waitcnt lgkmcnt(0)
	s_setprio 1
	s_waitcnt lgkmcnt(0)
	v_mfma_f32_16x16x32_bf16 v[124:127], v[128:131], v[152:155], v[124:127]
	v_mfma_f32_16x16x32_bf16 v[120:123], v[140:143], v[152:155], v[120:123]
	v_mfma_f32_16x16x32_bf16 v[116:119], v[128:131], v[160:163], v[116:119]
	v_mfma_f32_16x16x32_bf16 v[112:115], v[140:143], v[160:163], v[112:115]
	v_mfma_f32_16x16x32_bf16 v[108:111], v[128:131], v[168:171], v[108:111]
	v_mfma_f32_16x16x32_bf16 v[104:107], v[140:143], v[168:171], v[104:107]
	v_mfma_f32_16x16x32_bf16 v[100:103], v[128:131], v[176:179], v[100:103]
	v_mfma_f32_16x16x32_bf16 v[96:99], v[140:143], v[176:179], v[96:99]
	v_mfma_f32_16x16x32_bf16 v[124:127], v[132:135], v[156:159], v[124:127]
	v_mfma_f32_16x16x32_bf16 v[120:123], v[148:151], v[156:159], v[120:123]
	v_mfma_f32_16x16x32_bf16 v[116:119], v[132:135], v[164:167], v[116:119]
	v_mfma_f32_16x16x32_bf16 v[112:115], v[148:151], v[164:167], v[112:115]
	v_mfma_f32_16x16x32_bf16 v[108:111], v[132:135], v[172:175], v[108:111]
	v_mfma_f32_16x16x32_bf16 v[104:107], v[148:151], v[172:175], v[104:107]
	v_mfma_f32_16x16x32_bf16 v[100:103], v[132:135], v[180:183], v[100:103]
	v_mfma_f32_16x16x32_bf16 v[96:99], v[148:151], v[180:183], v[96:99]
	s_setprio 0
	s_barrier
; #define WAIT_V(n) asm volatile("s_waitcnt vmcnt(" #n ")" ::: "memory")
; #define WAIT_L(n) asm volatile("s_waitcnt lgkmcnt(" #n ")" ::: "memory")
; #define BAR __builtin_amdgcn_s_barrier()
; #define LDA(dst, b, h) _Pragma("unroll") for (int m = 0; m < 4; ++m) _Pragma("unroll") for (int k = 0; k < 2; ++k) \
;     dst[m][k] = *reinterpret_cast<const bf16x8*>((char*)shm + abase + (((b) * 2 + (h)) * 16384 + (m * 2 + k) * 1024))
; #define LDB(dst, b, h) _Pragma("unroll") for (int n = 0; n < 2; ++n) _Pragma("unroll") for (int k = 0; k < 2; ++k) \
;     dst[n][k] = *reinterpret_cast<const bf16x8*>((char*)shm + bbase + (((b) * 2 + (h)) * 16384 + (n * 2 + k) * 1024))
; template <bool SWAP>
; __device__ __forceinline__ void gemm_main(const u16* __restrict__ A, const u16* __restrict__ Bt, int brow, int bcol,
;                                           u16* shm, f32x4 (&acc)[2][2][4][2]) {
;     ...
;     LDB(B1, 0, 1); BAR; WAIT_L(0); MMA(0, 1, At, B1); BAR;
;     LDA(At, 0, 1); WAIT_V(4); BAR; WAIT_L(0); MMA(1, 0, At, B0); MMA(1, 1, At, B1); BAR; }
;   { LDB(B0, 1, 0); LDA(At, 1, 0); WAIT_V(2); BAR; WAIT_L(0); MMA(0, 0, At, B0); BAR;
	ds_read_b128 v[144:147], v138 offset:16384
	ds_read_b128 v[184:187], v138 offset:17408
	ds_read_b128 v[188:191], v138 offset:18432
	ds_read_b128 v[194:197], v138 offset:19456
	s_barrier
	s_waitcnt lgkmcnt(0)
	s_setprio 1
	s_waitcnt lgkmcnt(0)
	v_mfma_f32_16x16x32_bf16 v[92:95], v[144:147], v[152:155], v[92:95]
	v_mfma_f32_16x16x32_bf16 v[88:91], v[188:191], v[152:155], v[88:91]
	v_mfma_f32_16x16x32_bf16 v[84:87], v[144:147], v[160:163], v[84:87]
	v_mfma_f32_16x16x32_bf16 v[80:83], v[188:191], v[160:163], v[80:83]
	v_mfma_f32_16x16x32_bf16 v[76:79], v[144:147], v[168:171], v[76:79]
	v_mfma_f32_16x16x32_bf16 v[72:75], v[188:191], v[168:171], v[72:75]
	v_mfma_f32_16x16x32_bf16 v[68:71], v[144:147], v[176:179], v[68:71]
	v_mfma_f32_16x16x32_bf16 v[64:67], v[188:191], v[176:179], v[64:67]
	v_mfma_f32_16x16x32_bf16 v[92:95], v[184:187], v[156:159], v[92:95]
	v_mfma_f32_16x16x32_bf16 v[88:91], v[194:197], v[156:159], v[88:91]
	v_mfma_f32_16x16x32_bf16 v[84:87], v[184:187], v[164:167], v[84:87]
	v_mfma_f32_16x16x32_bf16 v[80:83], v[194:197], v[164:167], v[80:83]
	v_mfma_f32_16x16x32_bf16 v[76:79], v[184:187], v[172:175], v[76:79]
	v_mfma_f32_16x16x32_bf16 v[72:75], v[194:197], v[172:175], v[72:75]
	v_mfma_f32_16x16x32_bf16 v[68:71], v[184:187], v[180:183], v[68:71]
	v_mfma_f32_16x16x32_bf16 v[64:67], v[194:197], v[180:183], v[64:67]
	s_setprio 0
	s_barrier
	ds_read_b128 v[152:155], v137 offset:16384
	ds_read_b128 v[156:159], v137 offset:17408
	ds_read_b128 v[160:163], v137 offset:18432
	ds_read_b128 v[164:167], v137 offset:19456
	ds_read_b128 v[168:171], v137 offset:20480
	ds_read_b128 v[172:175], v137 offset:21504
	ds_read_b128 v[176:179], v137 offset:22528
	ds_read_b128 v[180:183], v137 offset:23552
	s_waitcnt vmcnt(4)
	s_barrier
	s_waitcnt lgkmcnt(0)
	s_setprio 1
	s_waitcnt lgkmcnt(0)
	v_mfma_f32_16x16x32_bf16 v[60:63], v[128:131], v[152:155], v[60:63]
	v_mfma_f32_16x16x32_bf16 v[56:59], v[140:143], v[152:155], v[56:59]
	v_mfma_f32_16x16x32_bf16 v[52:55], v[128:131], v[160:163], v[52:55]
	v_mfma_f32_16x16x32_bf16 v[48:51], v[140:143], v[160:163], v[48:51]
	v_mfma_f32_16x16x32_bf16 v[44:47], v[128:131], v[168:171], v[44:47]
	v_mfma_f32_16x16x32_bf16 v[40:43], v[140:143], v[168:171], v[40:43]
	v_mfma_f32_16x16x32_bf16 v[36:39], v[128:131], v[176:179], v[36:39]
	v_mfma_f32_16x16x32_bf16 v[32:35], v[140:143], v[176:179], v[32:35]
	v_mfma_f32_16x16x32_bf16 v[60:63], v[132:135], v[156:159], v[60:63]
	v_mfma_f32_16x16x32_bf16 v[56:59], v[148:151], v[156:159], v[56:59]
	v_mfma_f32_16x16x32_bf16 v[52:55], v[132:135], v[164:167], v[52:55]
	v_mfma_f32_16x16x32_bf16 v[48:51], v[148:151], v[164:167], v[48:51]
	v_mfma_f32_16x16x32_bf16 v[44:47], v[132:135], v[172:175], v[44:47]
	v_mfma_f32_16x16x32_bf16 v[40:43], v[148:151], v[172:175], v[40:43]
	v_mfma_f32_16x16x32_bf16 v[36:39], v[132:135], v[180:183], v[36:39]
	v_mfma_f32_16x16x32_bf16 v[32:35], v[148:151], v[180:183], v[32:35]
	s_setprio 0
	s_setprio 1
	v_mfma_f32_16x16x32_bf16 v[28:31], v[144:147], v[152:155], v[28:31]
	v_mfma_f32_16x16x32_bf16 v[24:27], v[188:191], v[152:155], v[24:27]
	v_mfma_f32_16x16x32_bf16 v[20:23], v[144:147], v[160:163], v[20:23]
	v_mfma_f32_16x16x32_bf16 v[16:19], v[188:191], v[160:163], v[16:19]
	v_mfma_f32_16x16x32_bf16 v[12:15], v[144:147], v[168:171], v[12:15]
	v_mfma_f32_16x16x32_bf16 v[8:11], v[188:191], v[168:171], v[8:11]
	v_mfma_f32_16x16x32_bf16 v[4:7], v[144:147], v[176:179], v[4:7]
	v_mfma_f32_16x16x32_bf16 v[0:3], v[188:191], v[176:179], v[0:3]
	v_mfma_f32_16x16x32_bf16 v[28:31], v[184:187], v[156:159], v[28:31]
	v_mfma_f32_16x16x32_bf16 v[24:27], v[194:197], v[156:159], v[24:27]
	v_mfma_f32_16x16x32_bf16 v[20:23], v[184:187], v[164:167], v[20:23]
	v_mfma_f32_16x16x32_bf16 v[16:19], v[194:197], v[164:167], v[16:19]
	v_mfma_f32_16x16x32_bf16 v[12:15], v[184:187], v[172:175], v[12:15]
	v_mfma_f32_16x16x32_bf16 v[8:11], v[194:197], v[172:175], v[8:11]
	v_mfma_f32_16x16x32_bf16 v[4:7], v[184:187], v[180:183], v[4:7]
	v_mfma_f32_16x16x32_bf16 v[0:3], v[194:197], v[180:183], v[0:3]
	s_setprio 0
	s_barrier
	ds_read_b128 v[128:131], v138 offset:32768
	ds_read_b128 v[132:135], v138 offset:33792
	ds_read_b128 v[140:143], v138 offset:34816
	ds_read_b128 v[144:147], v138 offset:35840
	ds_read_b128 v[148:151], v137 offset:32768
	ds_read_b128 v[152:155], v137 offset:33792
	ds_read_b128 v[156:159], v137 offset:34816
	ds_read_b128 v[160:163], v137 offset:35840
	ds_read_b128 v[164:167], v137 offset:36864
	ds_read_b128 v[168:171], v137 offset:37888
	ds_read_b128 v[172:175], v137 offset:38912
	ds_read_b128 v[176:179], v137 offset:39936
	s_waitcnt vmcnt(2)
	s_barrier
; #define WAIT_V(n) asm volatile("s_waitcnt vmcnt(" #n ")" ::: "memory")
; #define WAIT_L(n) asm volatile("s_waitcnt lgkmcnt(" #n ")" ::: "memory")
; #define BAR __builtin_amdgcn_s_barrier()
; #define LDA(dst, b, h) _Pragma("unroll") for (int m = 0; m < 4; ++m) _Pragma("unroll") for (int k = 0; k < 2; ++k) \
;     dst[m][k] = *reinterpret_cast<const bf16x8*>((char*)shm + abase + (((b) * 2 + (h)) * 16384 + (m * 2 + k) * 1024))
; #define LDB(dst, b, h) _Pragma("unroll") for (int n = 0; n < 2; ++n) _Pragma("unroll") for (int k = 0; k < 2; ++k) \
;     dst[n][k] = *reinterpret_cast<const bf16x8*>((char*)shm + bbase + (((b) * 2 + (h)) * 16384 + (n * 2 + k) * 1024))
; template <bool SWAP>
; __device__ __forceinline__ void gemm_main(const u16* __restrict__ A, const u16* __restrict__ Bt, int brow, int bcol,
;                                           u16* shm, f32x4 (&acc)[2][2][4][2]) {
;     ...
;   { LDB(B0, 1, 0); LDA(At, 1, 0); WAIT_V(2); BAR; WAIT_L(0); MMA(0, 0, At, B0); BAR;
;     LDB(B1, 1, 1); WAIT_V(0); BAR; WAIT_L(0); MMA(0, 1, At, B1); BAR;
;     LDA(At, 1, 1); BAR; WAIT_L(0); MMA(1, 0, At, B0); MMA(1, 1, At, B1); BAR; }
;   if (wr == 0) BAR;
	s_waitcnt lgkmcnt(0)
	s_setprio 1
	s_waitcnt lgkmcnt(0)
	v_mfma_f32_16x16x32_bf16 v[124:127], v[128:131], v[148:151], v[124:127]
	v_mfma_f32_16x16x32_bf16 v[120:123], v[140:143], v[148:151], v[120:123]
	v_mfma_f32_16x16x32_bf16 v[116:119], v[128:131], v[156:159], v[116:119]
	v_mfma_f32_16x16x32_bf16 v[112:115], v[140:143], v[156:159], v[112:115]
	v_mfma_f32_16x16x32_bf16 v[108:111], v[128:131], v[164:167], v[108:111]
	v_mfma_f32_16x16x32_bf16 v[104:107], v[140:143], v[164:167], v[104:107]
	v_mfma_f32_16x16x32_bf16 v[100:103], v[128:131], v[172:175], v[100:103]
	v_mfma_f32_16x16x32_bf16 v[96:99], v[140:143], v[172:175], v[96:99]
	v_mfma_f32_16x16x32_bf16 v[124:127], v[132:135], v[152:155], v[124:127]
	v_mfma_f32_16x16x32_bf16 v[120:123], v[144:147], v[152:155], v[120:123]
	v_mfma_f32_16x16x32_bf16 v[116:119], v[132:135], v[160:163], v[116:119]
	v_mfma_f32_16x16x32_bf16 v[112:115], v[144:147], v[160:163], v[112:115]
	v_mfma_f32_16x16x32_bf16 v[108:111], v[132:135], v[168:171], v[108:111]
	v_mfma_f32_16x16x32_bf16 v[104:107], v[144:147], v[168:171], v[104:107]
	v_mfma_f32_16x16x32_bf16 v[100:103], v[132:135], v[176:179], v[100:103]
	v_mfma_f32_16x16x32_bf16 v[96:99], v[144:147], v[176:179], v[96:99]
	s_setprio 0
	s_barrier
	ds_read_b128 v[180:183], v138 offset:49152
	ds_read_b128 v[184:187], v138 offset:50176
	ds_read_b128 v[188:191], v138 offset:51200
	ds_read_b128 v[194:197], v138 offset:52224
	s_waitcnt vmcnt(0)
	s_barrier
	s_waitcnt lgkmcnt(0)
	s_setprio 1
	s_waitcnt lgkmcnt(0)
	v_mfma_f32_16x16x32_bf16 v[92:95], v[180:183], v[148:151], v[92:95]
	v_mfma_f32_16x16x32_bf16 v[88:91], v[188:191], v[148:151], v[88:91]
	v_mfma_f32_16x16x32_bf16 v[84:87], v[180:183], v[156:159], v[84:87]
	v_mfma_f32_16x16x32_bf16 v[80:83], v[188:191], v[156:159], v[80:83]
	v_mfma_f32_16x16x32_bf16 v[76:79], v[180:183], v[164:167], v[76:79]
	v_mfma_f32_16x16x32_bf16 v[72:75], v[188:191], v[164:167], v[72:75]
	v_mfma_f32_16x16x32_bf16 v[68:71], v[180:183], v[172:175], v[68:71]
	v_mfma_f32_16x16x32_bf16 v[64:67], v[188:191], v[172:175], v[64:67]
	v_mfma_f32_16x16x32_bf16 v[92:95], v[184:187], v[152:155], v[92:95]
	v_mfma_f32_16x16x32_bf16 v[88:91], v[194:197], v[152:155], v[88:91]
	v_mfma_f32_16x16x32_bf16 v[84:87], v[184:187], v[160:163], v[84:87]
	v_mfma_f32_16x16x32_bf16 v[80:83], v[194:197], v[160:163], v[80:83]
	v_mfma_f32_16x16x32_bf16 v[76:79], v[184:187], v[168:171], v[76:79]
	v_mfma_f32_16x16x32_bf16 v[72:75], v[194:197], v[168:171], v[72:75]
	v_mfma_f32_16x16x32_bf16 v[68:71], v[184:187], v[176:179], v[68:71]
	v_mfma_f32_16x16x32_bf16 v[64:67], v[194:197], v[176:179], v[64:67]
	s_setprio 0
	s_barrier
	ds_read_b128 v[148:151], v137 offset:49152
	ds_read_b128 v[152:155], v137 offset:50176
	ds_read_b128 v[156:159], v137 offset:51200
	ds_read_b128 v[160:163], v137 offset:52224
	ds_read_b128 v[164:167], v137 offset:53248
	ds_read_b128 v[168:171], v137 offset:54272
	ds_read_b128 v[172:175], v137 offset:55296
	ds_read_b128 v[176:179], v137 offset:56320
	s_barrier
	s_waitcnt lgkmcnt(0)
	s_setprio 1
	s_waitcnt lgkmcnt(0)
	v_mfma_f32_16x16x32_bf16 v[60:63], v[128:131], v[148:151], v[60:63]
	v_mfma_f32_16x16x32_bf16 v[56:59], v[140:143], v[148:151], v[56:59]
	v_mfma_f32_16x16x32_bf16 v[52:55], v[128:131], v[156:159], v[52:55]
	v_mfma_f32_16x16x32_bf16 v[48:51], v[140:143], v[156:159], v[48:51]
	v_mfma_f32_16x16x32_bf16 v[44:47], v[128:131], v[164:167], v[44:47]
	v_mfma_f32_16x16x32_bf16 v[40:43], v[140:143], v[164:167], v[40:43]
	v_mfma_f32_16x16x32_bf16 v[36:39], v[128:131], v[172:175], v[36:39]
	v_mfma_f32_16x16x32_bf16 v[32:35], v[140:143], v[172:175], v[32:35]
	v_mfma_f32_16x16x32_bf16 v[60:63], v[132:135], v[152:155], v[60:63]
	v_mfma_f32_16x16x32_bf16 v[56:59], v[144:147], v[152:155], v[56:59]
	v_mfma_f32_16x16x32_bf16 v[52:55], v[132:135], v[160:163], v[52:55]
	v_mfma_f32_16x16x32_bf16 v[48:51], v[144:147], v[160:163], v[48:51]
	v_mfma_f32_16x16x32_bf16 v[44:47], v[132:135], v[168:171], v[44:47]
	v_mfma_f32_16x16x32_bf16 v[40:43], v[144:147], v[168:171], v[40:43]
	v_mfma_f32_16x16x32_bf16 v[36:39], v[132:135], v[176:179], v[36:39]
	v_mfma_f32_16x16x32_bf16 v[32:35], v[144:147], v[176:179], v[32:35]
	s_setprio 0
	s_setprio 1
	v_mfma_f32_16x16x32_bf16 v[28:31], v[180:183], v[148:151], v[28:31]
	v_mfma_f32_16x16x32_bf16 v[24:27], v[188:191], v[148:151], v[24:27]
	v_mfma_f32_16x16x32_bf16 v[20:23], v[180:183], v[156:159], v[20:23]
	v_mfma_f32_16x16x32_bf16 v[16:19], v[188:191], v[156:159], v[16:19]
	v_mfma_f32_16x16x32_bf16 v[12:15], v[180:183], v[164:167], v[12:15]
	v_mfma_f32_16x16x32_bf16 v[8:11], v[188:191], v[164:167], v[8:11]
	v_mfma_f32_16x16x32_bf16 v[4:7], v[180:183], v[172:175], v[4:7]
	v_mfma_f32_16x16x32_bf16 v[0:3], v[188:191], v[172:175], v[0:3]
	v_mfma_f32_16x16x32_bf16 v[28:31], v[184:187], v[152:155], v[28:31]
	v_mfma_f32_16x16x32_bf16 v[24:27], v[194:197], v[152:155], v[24:27]
	v_mfma_f32_16x16x32_bf16 v[20:23], v[184:187], v[160:163], v[20:23]
	v_mfma_f32_16x16x32_bf16 v[16:19], v[194:197], v[160:163], v[16:19]
	v_mfma_f32_16x16x32_bf16 v[12:15], v[184:187], v[168:171], v[12:15]
	v_mfma_f32_16x16x32_bf16 v[8:11], v[194:197], v[168:171], v[8:11]
	v_mfma_f32_16x16x32_bf16 v[4:7], v[184:187], v[176:179], v[4:7]
	v_mfma_f32_16x16x32_bf16 v[0:3], v[194:197], v[176:179], v[0:3]
	s_setprio 0
	s_movk_i32 s0, 0x100
	v_cmp_gt_u32_e32 vcc, s0, v136
	s_barrier
	s_and_saveexec_b64 s[0:1], vcc
	s_cbranch_execz .LBB0_579
	s_barrier

; #define WAIT_V(n) asm volatile("s_waitcnt vmcnt(" #n ")" ::: "memory")
; #define WAIT_L(n) asm volatile("s_waitcnt lgkmcnt(" #n ")" ::: "memory")
; #define BAR __builtin_amdgcn_s_barrier()
; #define SCHED __builtin_amdgcn_sched_barrier(0)
; #define STAGE(P, BASE, br, kt) do { const char* _g = (const char*)((BASE) + (size_t)(br) * GK + (kt) * BK); \
;     __builtin_amdgcn_global_load_lds((const unsigned*)(_g + voff0), (unsigned*)((char*)(P) + tx * 16), 16, 0, 0); \
;     __builtin_amdgcn_global_load_lds((const unsigned*)(_g + voff1), (unsigned*)((char*)(P) + tx * 16 + 8192), 16, 0, 0); } while (0)
; #define LDA(dst, b, h) _Pragma("unroll") for (int m = 0; m < 4; ++m) _Pragma("unroll") for (int k = 0; k < 2; ++k) \
;     dst[m][k] = *reinterpret_cast<const bf16x8*>((char*)shm + abase + (((b) * 2 + (h)) * 16384 + (m * 2 + k) * 1024))
; #define LDB(dst, b, h) _Pragma("unroll") for (int n = 0; n < 2; ++n) _Pragma("unroll") for (int k = 0; k < 2; ++k) \
;     dst[n][k] = *reinterpret_cast<const bf16x8*>((char*)shm + bbase + (((b) * 2 + (h)) * 16384 + (n * 2 + k) * 1024))
; template <bool SWAP>
; __device__ __forceinline__ void gemm_main(const u16* __restrict__ A, const u16* __restrict__ Bt, int brow, int bcol,
;                                           u16* shm, f32x4 (&acc)[2][2][4][2]) {
;     ...
;     LDB(B0, 0, 0); SCHED; LDA(At, 0, 0); STAGE(SA(1, 1), A, brow + HALF, t + 1);
;     WAIT_L(8); BAR; WAIT_L(0); MMA(0, 0, At, B0); BAR; SCHED;
;     LDB(B1, 0, 1); STAGE(SB(0, 0), Bt, bcol, t + 2);
;     BAR; WAIT_L(0); MMA(0, 1, At, B1); BAR;
;     LDA(At, 0, 1); STAGE(SA(0, 0), A, brow, t + 2);
;     BAR; WAIT_L(0); MMA(1, 0, At, B0); BAR; SCHED;
;     STAGE(SB(0, 1), Bt, bcol + HALF, t + 2);
;     WAIT_V(6); BAR; MMA(1, 1, At, B1); BAR;
;     LDB(B0, 1, 0); SCHED; LDA(At, 1, 0); STAGE(SA(0, 1), A, brow + HALF, t + 2);
.LBB0_627:
	ds_read_b128 v[170:173], v139 offset:1024
	ds_read_b128 v[178:181], v139 offset:3072
	ds_read_b128 v[186:189], v139 offset:5120
	ds_read_b128 v[198:201], v139 offset:7168
	v_add_u32_e32 v192, 0, v142
	v_add_u32_e32 v148, 0xc000, v192
	v_add_u32_e32 v149, 0xe000, v192
	s_add_u32 m0, s9, 0xc000
	v_lshl_add_u64 v[232:233], s[4:5], 0, v[134:135]
	s_add_u32 vcc_lo, s4, s68
	s_addc_u32 vcc_hi, s5, s69
	global_load_lds_dwordx4 v132, vcc
	s_add_u32 m0, s9, 0xe000
	s_nop 0
	global_load_lds_dwordx4 v134, vcc
	s_waitcnt lgkmcnt(8)
	s_setprio 1
	s_barrier
	s_waitcnt lgkmcnt(0)
	v_mfma_f32_16x16x32_bf16 v[124:127], v[150:153], v[166:169], v[124:127]
	v_mfma_f32_16x16x32_bf16 v[120:123], v[158:161], v[166:169], v[120:123]
	v_mfma_f32_16x16x32_bf16 v[116:119], v[150:153], v[174:177], v[116:119]
	v_mfma_f32_16x16x32_bf16 v[112:115], v[158:161], v[174:177], v[112:115]
	v_mfma_f32_16x16x32_bf16 v[108:111], v[150:153], v[182:185], v[108:111]
	v_mfma_f32_16x16x32_bf16 v[104:107], v[158:161], v[182:185], v[104:107]
	v_mfma_f32_16x16x32_bf16 v[100:103], v[150:153], v[194:197], v[100:103]
	v_mfma_f32_16x16x32_bf16 v[96:99], v[158:161], v[194:197], v[96:99]
	v_mfma_f32_16x16x32_bf16 v[124:127], v[154:157], v[170:173], v[124:127]
	v_mfma_f32_16x16x32_bf16 v[120:123], v[162:165], v[170:173], v[120:123]
	v_mfma_f32_16x16x32_bf16 v[116:119], v[154:157], v[178:181], v[116:119]
	v_mfma_f32_16x16x32_bf16 v[112:115], v[162:165], v[178:181], v[112:115]
	v_mfma_f32_16x16x32_bf16 v[108:111], v[154:157], v[186:189], v[108:111]
	v_mfma_f32_16x16x32_bf16 v[104:107], v[162:165], v[186:189], v[104:107]
	v_mfma_f32_16x16x32_bf16 v[100:103], v[154:157], v[198:201], v[100:103]
	v_mfma_f32_16x16x32_bf16 v[96:99], v[162:165], v[198:201], v[96:99]
	s_barrier
	s_setprio 0
	ds_read_b128 v[202:205], v140 offset:16384
	ds_read_b128 v[206:209], v140 offset:17408
	ds_read_b128 v[224:227], v140 offset:18432
	ds_read_b128 v[228:231], v140 offset:19456
	v_lshl_add_u64 v[234:235], s[4:5], 0, v[128:129]
	s_add_u32 m0, s9, s28
	s_nop 0
	s_add_u32 vcc_lo, s4, s94
	s_addc_u32 vcc_hi, s5, s95
	global_load_lds_dwordx4 v128, vcc
	v_lshl_add_u64 v[236:237], s[4:5], 0, v[130:131]
	s_add_u32 m0, s9, s28
	s_add_u32 m0, m0, 0x2000
	s_nop 0
	global_load_lds_dwordx4 v130, vcc
	s_setprio 1
	s_barrier
	s_waitcnt lgkmcnt(0)
	v_mfma_f32_16x16x32_bf16 v[92:95], v[202:205], v[166:169], v[92:95]
	v_mfma_f32_16x16x32_bf16 v[88:91], v[224:227], v[166:169], v[88:91]
	v_mfma_f32_16x16x32_bf16 v[84:87], v[202:205], v[174:177], v[84:87]
	v_mfma_f32_16x16x32_bf16 v[80:83], v[224:227], v[174:177], v[80:83]
	v_mfma_f32_16x16x32_bf16 v[76:79], v[202:205], v[182:185], v[76:79]
	v_mfma_f32_16x16x32_bf16 v[72:75], v[224:227], v[182:185], v[72:75]
	v_mfma_f32_16x16x32_bf16 v[68:71], v[202:205], v[194:197], v[68:71]
	v_mfma_f32_16x16x32_bf16 v[64:67], v[224:227], v[194:197], v[64:67]
	v_mfma_f32_16x16x32_bf16 v[92:95], v[206:209], v[170:173], v[92:95]
	ds_read_b128 v[166:169], v139 offset:16384
	v_mfma_f32_16x16x32_bf16 v[88:91], v[228:231], v[170:173], v[88:91]
	v_mfma_f32_16x16x32_bf16 v[84:87], v[206:209], v[178:181], v[84:87]
	ds_read_b128 v[174:177], v139 offset:18432
	v_mfma_f32_16x16x32_bf16 v[80:83], v[228:231], v[178:181], v[80:83]
	v_mfma_f32_16x16x32_bf16 v[76:79], v[206:209], v[186:189], v[76:79]
	ds_read_b128 v[182:185], v139 offset:20480
	v_mfma_f32_16x16x32_bf16 v[72:75], v[228:231], v[186:189], v[72:75]
	v_mfma_f32_16x16x32_bf16 v[68:71], v[206:209], v[198:201], v[68:71]
	ds_read_b128 v[194:197], v139 offset:22528
	v_mfma_f32_16x16x32_bf16 v[64:67], v[228:231], v[198:201], v[64:67]
	s_barrier
	s_setprio 0
	ds_read_b128 v[170:173], v139 offset:17408
	ds_read_b128 v[178:181], v139 offset:19456
	ds_read_b128 v[186:189], v139 offset:21504
	ds_read_b128 v[198:201], v139 offset:23552
	s_add_u32 m0, s9, 0x0
	s_nop 0
	s_add_u32 vcc_lo, s4, s62
	s_addc_u32 vcc_hi, s5, s63
	global_load_lds_dwordx4 v132, vcc
	s_add_u32 m0, s9, 0x2000
	s_nop 0
	global_load_lds_dwordx4 v134, vcc
	s_waitcnt vmcnt(8)
	s_setprio 1
	s_barrier
	s_waitcnt lgkmcnt(0)
	v_mfma_f32_16x16x32_bf16 v[60:63], v[150:153], v[166:169], v[60:63]
	v_mfma_f32_16x16x32_bf16 v[56:59], v[158:161], v[166:169], v[56:59]
	v_mfma_f32_16x16x32_bf16 v[52:55], v[150:153], v[174:177], v[52:55]
	v_mfma_f32_16x16x32_bf16 v[48:51], v[158:161], v[174:177], v[48:51]
	v_mfma_f32_16x16x32_bf16 v[44:47], v[150:153], v[182:185], v[44:47]
	v_mfma_f32_16x16x32_bf16 v[40:43], v[158:161], v[182:185], v[40:43]
	v_mfma_f32_16x16x32_bf16 v[36:39], v[150:153], v[194:197], v[36:39]
	v_mfma_f32_16x16x32_bf16 v[32:35], v[158:161], v[194:197], v[32:35]
	v_mfma_f32_16x16x32_bf16 v[60:63], v[154:157], v[170:173], v[60:63]
	v_mfma_f32_16x16x32_bf16 v[56:59], v[162:165], v[170:173], v[56:59]
	v_mfma_f32_16x16x32_bf16 v[52:55], v[154:157], v[178:181], v[52:55]
	v_mfma_f32_16x16x32_bf16 v[48:51], v[162:165], v[178:181], v[48:51]
	v_mfma_f32_16x16x32_bf16 v[44:47], v[154:157], v[186:189], v[44:47]
	v_mfma_f32_16x16x32_bf16 v[40:43], v[162:165], v[186:189], v[40:43]
	v_mfma_f32_16x16x32_bf16 v[36:39], v[154:157], v[198:201], v[36:39]
	v_mfma_f32_16x16x32_bf16 v[32:35], v[162:165], v[198:201], v[32:35]
	s_barrier
	s_setprio 0
	ds_read_b128 v[150:153], v140 offset:32768
	ds_read_b128 v[154:157], v140 offset:33792
	ds_read_b128 v[158:161], v140 offset:34816
	ds_read_b128 v[162:165], v140 offset:35840
	s_add_u32 m0, s9, s29
	s_nop 0
	s_add_u32 vcc_lo, s4, s78
	s_addc_u32 vcc_hi, s5, s79
	global_load_lds_dwordx4 v128, vcc
	s_add_u32 m0, s9, s29
	s_add_u32 m0, m0, 0x2000
	s_nop 0
	global_load_lds_dwordx4 v130, vcc
	s_waitcnt vmcnt(6)
	s_setprio 1
	s_barrier
; #define WAIT_V(n) asm volatile("s_waitcnt vmcnt(" #n ")" ::: "memory")
; #define WAIT_L(n) asm volatile("s_waitcnt lgkmcnt(" #n ")" ::: "memory")
; #define BAR __builtin_amdgcn_s_barrier()
; #define SCHED __builtin_amdgcn_sched_barrier(0)
; #define STAGE(P, BASE, br, kt) do { const char* _g = (const char*)((BASE) + (size_t)(br) * GK + (kt) * BK); \
;     __builtin_amdgcn_global_load_lds((const unsigned*)(_g + voff0), (unsigned*)((char*)(P) + tx * 16), 16, 0, 0); \
;     __builtin_amdgcn_global_load_lds((const unsigned*)(_g + voff1), (unsigned*)((char*)(P) + tx * 16 + 8192), 16, 0, 0); } while (0)
; #define LDA(dst, b, h) _Pragma("unroll") for (int m = 0; m < 4; ++m) _Pragma("unroll") for (int k = 0; k < 2; ++k) \
;     dst[m][k] = *reinterpret_cast<const bf16x8*>((char*)shm + abase + (((b) * 2 + (h)) * 16384 + (m * 2 + k) * 1024))
; #define LDB(dst, b, h) _Pragma("unroll") for (int n = 0; n < 2; ++n) _Pragma("unroll") for (int k = 0; k < 2; ++k) \
;     dst[n][k] = *reinterpret_cast<const bf16x8*>((char*)shm + bbase + (((b) * 2 + (h)) * 16384 + (n * 2 + k) * 1024))
; template <bool SWAP>
; __device__ __forceinline__ void gemm_main(const u16* __restrict__ A, const u16* __restrict__ Bt, int brow, int bcol,
;                                           u16* shm, f32x4 (&acc)[2][2][4][2]) {
;     ...
;     WAIT_V(6); BAR; MMA(1, 1, At, B1); BAR;
;     LDB(B0, 1, 0); SCHED; LDA(At, 1, 0); STAGE(SA(0, 1), A, brow + HALF, t + 2);
;     WAIT_L(8); BAR; WAIT_L(0); MMA(0, 0, At, B0); BAR; SCHED;
;     LDB(B1, 1, 1); STAGE(SB(1, 0), Bt, bcol, t + 3);
;     BAR; WAIT_L(0); MMA(0, 1, At, B1); BAR;
;     LDA(At, 1, 1); STAGE(SA(1, 0), A, brow, t + 3);
	v_mfma_f32_16x16x32_bf16 v[28:31], v[202:205], v[166:169], v[28:31]
	v_mfma_f32_16x16x32_bf16 v[24:27], v[224:227], v[166:169], v[24:27]
	v_mfma_f32_16x16x32_bf16 v[20:23], v[202:205], v[174:177], v[20:23]
	v_mfma_f32_16x16x32_bf16 v[16:19], v[224:227], v[174:177], v[16:19]
	v_mfma_f32_16x16x32_bf16 v[12:15], v[202:205], v[182:185], v[12:15]
	v_mfma_f32_16x16x32_bf16 v[8:11], v[224:227], v[182:185], v[8:11]
	v_mfma_f32_16x16x32_bf16 v[4:7], v[202:205], v[194:197], v[4:7]
	v_mfma_f32_16x16x32_bf16 v[0:3], v[224:227], v[194:197], v[0:3]
	v_mfma_f32_16x16x32_bf16 v[28:31], v[206:209], v[170:173], v[28:31]
	ds_read_b128 v[166:169], v139 offset:32768
	v_mfma_f32_16x16x32_bf16 v[24:27], v[228:231], v[170:173], v[24:27]
	v_mfma_f32_16x16x32_bf16 v[20:23], v[206:209], v[178:181], v[20:23]
	ds_read_b128 v[174:177], v139 offset:34816
	v_mfma_f32_16x16x32_bf16 v[16:19], v[228:231], v[178:181], v[16:19]
	v_mfma_f32_16x16x32_bf16 v[12:15], v[206:209], v[186:189], v[12:15]
	ds_read_b128 v[182:185], v139 offset:36864
	v_mfma_f32_16x16x32_bf16 v[8:11], v[228:231], v[186:189], v[8:11]
	v_mfma_f32_16x16x32_bf16 v[4:7], v[206:209], v[198:201], v[4:7]
	ds_read_b128 v[194:197], v139 offset:38912
	v_mfma_f32_16x16x32_bf16 v[0:3], v[228:231], v[198:201], v[0:3]
	s_barrier
	s_setprio 0
	ds_read_b128 v[170:173], v139 offset:33792
	ds_read_b128 v[178:181], v139 offset:35840
	ds_read_b128 v[186:189], v139 offset:37888
	ds_read_b128 v[198:201], v139 offset:39936
	s_add_u32 m0, s9, 0x4000
	s_nop 0
	s_add_u32 vcc_lo, s4, s88
	s_addc_u32 vcc_hi, s5, s89
	global_load_lds_dwordx4 v132, vcc
	s_add_u32 m0, s9, 0x6000
	s_nop 0
	global_load_lds_dwordx4 v134, vcc
	s_waitcnt lgkmcnt(8)
	s_setprio 1
	s_barrier
	s_waitcnt lgkmcnt(0)
	v_mfma_f32_16x16x32_bf16 v[124:127], v[150:153], v[166:169], v[124:127]
	v_mfma_f32_16x16x32_bf16 v[120:123], v[158:161], v[166:169], v[120:123]
	v_mfma_f32_16x16x32_bf16 v[116:119], v[150:153], v[174:177], v[116:119]
	v_mfma_f32_16x16x32_bf16 v[112:115], v[158:161], v[174:177], v[112:115]
	v_mfma_f32_16x16x32_bf16 v[108:111], v[150:153], v[182:185], v[108:111]
	v_mfma_f32_16x16x32_bf16 v[104:107], v[158:161], v[182:185], v[104:107]
	v_mfma_f32_16x16x32_bf16 v[100:103], v[150:153], v[194:197], v[100:103]
	v_mfma_f32_16x16x32_bf16 v[96:99], v[158:161], v[194:197], v[96:99]
	v_mfma_f32_16x16x32_bf16 v[124:127], v[154:157], v[170:173], v[124:127]
	v_mfma_f32_16x16x32_bf16 v[120:123], v[162:165], v[170:173], v[120:123]
	v_mfma_f32_16x16x32_bf16 v[116:119], v[154:157], v[178:181], v[116:119]
	v_mfma_f32_16x16x32_bf16 v[112:115], v[162:165], v[178:181], v[112:115]
	v_mfma_f32_16x16x32_bf16 v[108:111], v[154:157], v[186:189], v[108:111]
	v_mfma_f32_16x16x32_bf16 v[104:107], v[162:165], v[186:189], v[104:107]
	v_mfma_f32_16x16x32_bf16 v[100:103], v[154:157], v[198:201], v[100:103]
	v_mfma_f32_16x16x32_bf16 v[96:99], v[162:165], v[198:201], v[96:99]
	s_barrier
	s_setprio 0
	ds_read_b128 v[202:205], v140 offset:49152
	ds_read_b128 v[206:209], v140 offset:50176
	ds_read_b128 v[224:227], v140 offset:51200
	ds_read_b128 v[228:231], v140 offset:52224
	s_add_u32 m0, s9, s30
	s_nop 0
	s_add_u32 vcc_lo, s4, s52
	s_addc_u32 vcc_hi, s5, s53
	global_load_lds_dwordx4 v128, vcc
	v_lshl_add_u64 v[238:239], v[236:237], 0, s[52:53]
	s_add_u32 m0, s9, s30
	s_add_u32 m0, m0, 0x2000
	s_nop 0
	global_load_lds_dwordx4 v130, vcc
	s_setprio 1
	s_barrier
	s_waitcnt lgkmcnt(0)
	v_mfma_f32_16x16x32_bf16 v[92:95], v[202:205], v[166:169], v[92:95]
	v_mfma_f32_16x16x32_bf16 v[88:91], v[224:227], v[166:169], v[88:91]
	v_mfma_f32_16x16x32_bf16 v[84:87], v[202:205], v[174:177], v[84:87]
	v_mfma_f32_16x16x32_bf16 v[80:83], v[224:227], v[174:177], v[80:83]
	v_mfma_f32_16x16x32_bf16 v[76:79], v[202:205], v[182:185], v[76:79]
	v_mfma_f32_16x16x32_bf16 v[72:75], v[224:227], v[182:185], v[72:75]
	v_mfma_f32_16x16x32_bf16 v[68:71], v[202:205], v[194:197], v[68:71]
	v_mfma_f32_16x16x32_bf16 v[64:67], v[224:227], v[194:197], v[64:67]
	v_mfma_f32_16x16x32_bf16 v[92:95], v[206:209], v[170:173], v[92:95]
	ds_read_b128 v[166:169], v139 offset:49152
	v_mfma_f32_16x16x32_bf16 v[88:91], v[228:231], v[170:173], v[88:91]
	v_mfma_f32_16x16x32_bf16 v[84:87], v[206:209], v[178:181], v[84:87]
	ds_read_b128 v[174:177], v139 offset:51200
	v_mfma_f32_16x16x32_bf16 v[80:83], v[228:231], v[178:181], v[80:83]
	v_mfma_f32_16x16x32_bf16 v[76:79], v[206:209], v[186:189], v[76:79]
	ds_read_b128 v[182:185], v139 offset:53248
	v_mfma_f32_16x16x32_bf16 v[72:75], v[228:231], v[186:189], v[72:75]
	v_mfma_f32_16x16x32_bf16 v[68:71], v[206:209], v[198:201], v[68:71]
	ds_read_b128 v[194:197], v139 offset:55296
	v_mfma_f32_16x16x32_bf16 v[64:67], v[228:231], v[198:201], v[64:67]
	s_barrier
	s_setprio 0
	ds_read_b128 v[170:173], v139 offset:50176
	ds_read_b128 v[178:181], v139 offset:52224
	ds_read_b128 v[186:189], v139 offset:54272
	ds_read_b128 v[198:201], v139 offset:56320
	v_add_u32_e32 v223, 0x8000, v192
	s_add_u32 m0, s9, 0x8000
	s_nop 0
	s_add_u32 vcc_lo, s4, s44
	s_addc_u32 vcc_hi, s5, s45
	global_load_lds_dwordx4 v132, vcc
	v_lshl_add_u64 v[190:191], v[232:233], 0, s[44:45]
	s_add_u32 m0, s9, 0xa000
	s_nop 0
	global_load_lds_dwordx4 v134, vcc
	s_waitcnt vmcnt(8)
	s_setprio 1
	s_barrier
; #define WAIT_V(n) asm volatile("s_waitcnt vmcnt(" #n ")" ::: "memory")
; #define WAIT_L(n) asm volatile("s_waitcnt lgkmcnt(" #n ")" ::: "memory")
; #define BAR __builtin_amdgcn_s_barrier()
; #define SCHED __builtin_amdgcn_sched_barrier(0)
; #define STAGE(P, BASE, br, kt) do { const char* _g = (const char*)((BASE) + (size_t)(br) * GK + (kt) * BK); \
;     __builtin_amdgcn_global_load_lds((const unsigned*)(_g + voff0), (unsigned*)((char*)(P) + tx * 16), 16, 0, 0); \
;     __builtin_amdgcn_global_load_lds((const unsigned*)(_g + voff1), (unsigned*)((char*)(P) + tx * 16 + 8192), 16, 0, 0); } while (0)
; #define LDA(dst, b, h) _Pragma("unroll") for (int m = 0; m < 4; ++m) _Pragma("unroll") for (int k = 0; k < 2; ++k) \
;     dst[m][k] = *reinterpret_cast<const bf16x8*>((char*)shm + abase + (((b) * 2 + (h)) * 16384 + (m * 2 + k) * 1024))
; #define LDB(dst, b, h) _Pragma("unroll") for (int n = 0; n < 2; ++n) _Pragma("unroll") for (int k = 0; k < 2; ++k) \
;     dst[n][k] = *reinterpret_cast<const bf16x8*>((char*)shm + bbase + (((b) * 2 + (h)) * 16384 + (n * 2 + k) * 1024))
; template <bool SWAP>
; __device__ __forceinline__ void gemm_main(const u16* __restrict__ A, const u16* __restrict__ Bt, int brow, int bcol,
;                                           u16* shm, f32x4 (&acc)[2][2][4][2]) {
;     ...
;     BAR; WAIT_L(0); MMA(1, 0, At, B0); BAR; SCHED;
;     STAGE(SB(1, 1), Bt, bcol + HALF, t + 3);
;     WAIT_V(6); BAR; MMA(1, 1, At, B1); BAR;
;   }
;   { LDB(B0, 0, 0); LDA(At, 0, 0); STAGE(SA(1, 1), A, brow + HALF, nt - 1);
;     BAR; WAIT_L(0); MMA(0, 0, At, B0); BAR;
	s_waitcnt lgkmcnt(0)
	v_mfma_f32_16x16x32_bf16 v[60:63], v[150:153], v[166:169], v[60:63]
	v_mfma_f32_16x16x32_bf16 v[56:59], v[158:161], v[166:169], v[56:59]
	v_mfma_f32_16x16x32_bf16 v[52:55], v[150:153], v[174:177], v[52:55]
	v_mfma_f32_16x16x32_bf16 v[48:51], v[158:161], v[174:177], v[48:51]
	v_mfma_f32_16x16x32_bf16 v[44:47], v[150:153], v[182:185], v[44:47]
	v_mfma_f32_16x16x32_bf16 v[40:43], v[158:161], v[182:185], v[40:43]
	v_mfma_f32_16x16x32_bf16 v[36:39], v[150:153], v[194:197], v[36:39]
	v_mfma_f32_16x16x32_bf16 v[32:35], v[158:161], v[194:197], v[32:35]
	v_mfma_f32_16x16x32_bf16 v[60:63], v[154:157], v[170:173], v[60:63]
	v_mfma_f32_16x16x32_bf16 v[56:59], v[162:165], v[170:173], v[56:59]
	v_mfma_f32_16x16x32_bf16 v[52:55], v[154:157], v[178:181], v[52:55]
	v_mfma_f32_16x16x32_bf16 v[48:51], v[162:165], v[178:181], v[48:51]
	v_mfma_f32_16x16x32_bf16 v[44:47], v[154:157], v[186:189], v[44:47]
	v_mfma_f32_16x16x32_bf16 v[40:43], v[162:165], v[186:189], v[40:43]
	v_mfma_f32_16x16x32_bf16 v[36:39], v[154:157], v[198:201], v[36:39]
	v_mfma_f32_16x16x32_bf16 v[32:35], v[162:165], v[198:201], v[32:35]
	s_barrier
	s_setprio 0
	ds_read_b128 v[150:153], v140
	ds_read_b128 v[154:157], v140 offset:1024
	ds_read_b128 v[158:161], v140 offset:2048
	ds_read_b128 v[162:165], v140 offset:3072
	s_add_u32 m0, s9, s31
	s_nop 0
	s_add_u32 vcc_lo, s4, s38
	s_addc_u32 vcc_hi, s5, s39
	global_load_lds_dwordx4 v128, vcc
	v_lshl_add_u64 v[254:255], v[236:237], 0, s[38:39]
	s_add_u32 m0, s9, s31
	s_add_u32 m0, m0, 0x2000
	s_nop 0
	global_load_lds_dwordx4 v130, vcc
	s_waitcnt vmcnt(6)
	s_setprio 1
	s_barrier
	v_mfma_f32_16x16x32_bf16 v[28:31], v[202:205], v[166:169], v[28:31]
	v_mfma_f32_16x16x32_bf16 v[24:27], v[224:227], v[166:169], v[24:27]
	v_mfma_f32_16x16x32_bf16 v[20:23], v[202:205], v[174:177], v[20:23]
	v_mfma_f32_16x16x32_bf16 v[16:19], v[224:227], v[174:177], v[16:19]
	v_mfma_f32_16x16x32_bf16 v[12:15], v[202:205], v[182:185], v[12:15]
	v_mfma_f32_16x16x32_bf16 v[8:11], v[224:227], v[182:185], v[8:11]
	v_mfma_f32_16x16x32_bf16 v[4:7], v[202:205], v[194:197], v[4:7]
	v_mfma_f32_16x16x32_bf16 v[0:3], v[224:227], v[194:197], v[0:3]
	v_mfma_f32_16x16x32_bf16 v[28:31], v[206:209], v[170:173], v[28:31]
	ds_read_b128 v[166:169], v139
	v_mfma_f32_16x16x32_bf16 v[24:27], v[228:231], v[170:173], v[24:27]
	v_mfma_f32_16x16x32_bf16 v[20:23], v[206:209], v[178:181], v[20:23]
	ds_read_b128 v[174:177], v139 offset:2048
	v_mfma_f32_16x16x32_bf16 v[16:19], v[228:231], v[178:181], v[16:19]
	v_mfma_f32_16x16x32_bf16 v[12:15], v[206:209], v[186:189], v[12:15]
	ds_read_b128 v[182:185], v139 offset:4096
	v_mfma_f32_16x16x32_bf16 v[8:11], v[228:231], v[186:189], v[8:11]
	v_mfma_f32_16x16x32_bf16 v[4:7], v[206:209], v[198:201], v[4:7]
	ds_read_b128 v[194:197], v139 offset:6144
	v_mfma_f32_16x16x32_bf16 v[0:3], v[228:231], v[198:201], v[0:3]
	s_add_i32 s8, s8, 2
	s_add_u32 s4, s4, 0x100
	s_addc_u32 s5, s5, 0
	s_cmp_lt_u32 s8, 28
	s_barrier
	s_setprio 0
	s_cbranch_scc1 .LBB0_627
	s_and_b32 s4, s7, 0xffffe0
	s_and_b32 s5, s6, 31
	s_or_b32 s4, s4, s5
	s_lshl_b32 s10, s4, 8
	v_lshlrev_b32_e32 v128, 3, v141
	v_lshlrev_b32_e32 v129, 5, v141
	v_and_b32_e32 v128, 0xffff0, v128
	v_and_b32_e32 v129, 32, v129
	s_or_b32 s4, s10, 0x80
	v_add_u32_e32 v129, v129, v144
	v_add_lshl_u32 v128, v143, v128, 12
	s_ashr_i32 s5, s4, 31
	v_lshl_add_u32 v192, v129, 1, v128
	v_lshlrev_b32_e32 v128, 3, v145
	v_lshlrev_b32_e32 v129, 5, v145
	s_lshl_b64 s[4:5], s[4:5], 12
	v_and_b32_e32 v128, 0xffff0, v128
	v_and_b32_e32 v129, 32, v129
	s_add_u32 s4, s84, s4
	v_add_u32_e32 v129, v129, v147
	v_add_lshl_u32 v128, v146, v128, 12
	s_addc_u32 s5, s85, s5
	v_lshl_add_u32 v146, v129, 1, v128
	v_mov_b32_e32 v147, v193
	v_lshl_add_u64 v[186:187], s[4:5], 0, v[192:193]
	s_mov_b64 s[8:9], 0xf80
	v_readfirstlane_b32 s7, v148
	v_lshl_add_u64 v[186:187], v[186:187], 0, s[8:9]
	s_mov_b32 m0, s7
	v_lshl_add_u64 v[146:147], s[4:5], 0, v[146:147]
	v_readfirstlane_b32 s4, v149
	ds_read_b128 v[128:131], v140
	ds_read_b128 v[132:135], v140 offset:1024
	ds_read_b128 v[142:145], v140 offset:2048
	ds_read_b128 v[150:153], v140 offset:3072
	ds_read_b128 v[154:157], v139
	ds_read_b128 v[158:161], v139 offset:1024
	ds_read_b128 v[162:165], v139 offset:2048
	ds_read_b128 v[166:169], v139 offset:3072
	ds_read_b128 v[170:173], v139 offset:4096
	ds_read_b128 v[174:177], v139 offset:5120
	ds_read_b128 v[178:181], v139 offset:6144
	ds_read_b128 v[182:185], v139 offset:7168
	global_load_lds_dwordx4 v[186:187], off
	v_lshl_add_u64 v[146:147], v[146:147], 0, s[8:9]
	s_mov_b32 m0, s4
	s_nop 0
	global_load_lds_dwordx4 v[146:147], off
	s_barrier
	s_waitcnt lgkmcnt(0)
	s_setprio 1
	s_waitcnt lgkmcnt(0)
	v_mfma_f32_16x16x32_bf16 v[124:127], v[128:131], v[154:157], v[124:127]
	v_mfma_f32_16x16x32_bf16 v[116:119], v[128:131], v[162:165], v[116:119]
	v_mfma_f32_16x16x32_bf16 v[108:111], v[128:131], v[170:173], v[108:111]
	v_mfma_f32_16x16x32_bf16 v[100:103], v[128:131], v[178:181], v[100:103]
	v_mfma_f32_16x16x32_bf16 v[124:127], v[132:135], v[158:161], v[124:127]
	v_mfma_f32_16x16x32_bf16 v[120:123], v[142:145], v[154:157], v[120:123]
	v_mfma_f32_16x16x32_bf16 v[116:119], v[132:135], v[166:169], v[116:119]
	v_mfma_f32_16x16x32_bf16 v[112:115], v[142:145], v[162:165], v[112:115]
	v_mfma_f32_16x16x32_bf16 v[108:111], v[132:135], v[174:177], v[108:111]
	v_mfma_f32_16x16x32_bf16 v[104:107], v[142:145], v[170:173], v[104:107]
	v_mfma_f32_16x16x32_bf16 v[100:103], v[132:135], v[182:185], v[100:103]
	v_mfma_f32_16x16x32_bf16 v[96:99], v[142:145], v[178:181], v[96:99]
	v_mfma_f32_16x16x32_bf16 v[146:149], v[150:153], v[158:161], v[120:123]
	v_mfma_f32_16x16x32_bf16 v[186:189], v[150:153], v[166:169], v[112:115]
	v_mfma_f32_16x16x32_bf16 v[194:197], v[150:153], v[174:177], v[104:107]
	v_mfma_f32_16x16x32_bf16 v[198:201], v[150:153], v[182:185], v[96:99]
	s_setprio 0
	s_barrier
; #define WAIT_V(n) asm volatile("s_waitcnt vmcnt(" #n ")" ::: "memory")
; #define WAIT_L(n) asm volatile("s_waitcnt lgkmcnt(" #n ")" ::: "memory")
; #define BAR __builtin_amdgcn_s_barrier()
; #define LDA(dst, b, h) _Pragma("unroll") for (int m = 0; m < 4; ++m) _Pragma("unroll") for (int k = 0; k < 2; ++k) \
;     dst[m][k] = *reinterpret_cast<const bf16x8*>((char*)shm + abase + (((b) * 2 + (h)) * 16384 + (m * 2 + k) * 1024))
; #define LDB(dst, b, h) _Pragma("unroll") for (int n = 0; n < 2; ++n) _Pragma("unroll") for (int k = 0; k < 2; ++k) \
;     dst[n][k] = *reinterpret_cast<const bf16x8*>((char*)shm + bbase + (((b) * 2 + (h)) * 16384 + (n * 2 + k) * 1024))
; template <bool SWAP>
; __device__ __forceinline__ void gemm_main(const u16* __restrict__ A, const u16* __restrict__ Bt, int brow, int bcol,
;                                           u16* shm, f32x4 (&acc)[2][2][4][2]) {
;     ...
;     LDB(B1, 0, 1); BAR; WAIT_L(0); MMA(0, 1, At, B1); BAR;
;     LDA(At, 0, 1); WAIT_V(4); BAR; WAIT_L(0); MMA(1, 0, At, B0); MMA(1, 1, At, B1); BAR; }
;   { LDB(B0, 1, 0); LDA(At, 1, 0); WAIT_V(2); BAR; WAIT_L(0); MMA(0, 0, At, B0); BAR;
	s_nop 1
	ds_read_b128 v[96:99], v140 offset:16384
	ds_read_b128 v[104:107], v140 offset:17408
	ds_read_b128 v[112:115], v140 offset:18432
	ds_read_b128 v[120:123], v140 offset:19456
	s_barrier
	s_waitcnt lgkmcnt(0)
	s_setprio 1
	s_waitcnt lgkmcnt(0)
	v_mfma_f32_16x16x32_bf16 v[92:95], v[96:99], v[154:157], v[92:95]
	v_mfma_f32_16x16x32_bf16 v[84:87], v[96:99], v[162:165], v[84:87]
	v_mfma_f32_16x16x32_bf16 v[76:79], v[96:99], v[170:173], v[76:79]
	v_mfma_f32_16x16x32_bf16 v[68:71], v[96:99], v[178:181], v[68:71]
	v_mfma_f32_16x16x32_bf16 v[92:95], v[104:107], v[158:161], v[92:95]
	v_mfma_f32_16x16x32_bf16 v[88:91], v[112:115], v[154:157], v[88:91]
	v_mfma_f32_16x16x32_bf16 v[84:87], v[104:107], v[166:169], v[84:87]
	v_mfma_f32_16x16x32_bf16 v[80:83], v[112:115], v[162:165], v[80:83]
	v_mfma_f32_16x16x32_bf16 v[76:79], v[104:107], v[174:177], v[76:79]
	v_mfma_f32_16x16x32_bf16 v[72:75], v[112:115], v[170:173], v[72:75]
	v_mfma_f32_16x16x32_bf16 v[68:71], v[104:107], v[182:185], v[68:71]
	v_mfma_f32_16x16x32_bf16 v[64:67], v[112:115], v[178:181], v[64:67]
	v_mfma_f32_16x16x32_bf16 v[154:157], v[120:123], v[158:161], v[88:91]
	v_mfma_f32_16x16x32_bf16 v[158:161], v[120:123], v[166:169], v[80:83]
	v_mfma_f32_16x16x32_bf16 v[162:165], v[120:123], v[174:177], v[72:75]
	v_mfma_f32_16x16x32_bf16 v[166:169], v[120:123], v[182:185], v[64:67]
	s_setprio 0
	s_barrier
	s_nop 1
	ds_read_b128 v[64:67], v139 offset:16384
	ds_read_b128 v[72:75], v139 offset:17408
	ds_read_b128 v[80:83], v139 offset:18432
	ds_read_b128 v[88:91], v139 offset:19456
	ds_read_b128 v[170:173], v139 offset:20480
	ds_read_b128 v[174:177], v139 offset:21504
	ds_read_b128 v[178:181], v139 offset:22528
	ds_read_b128 v[182:185], v139 offset:23552
	s_waitcnt vmcnt(4)
	s_barrier
	s_waitcnt lgkmcnt(0)
	s_setprio 1
	s_waitcnt lgkmcnt(0)
	v_mfma_f32_16x16x32_bf16 v[60:63], v[128:131], v[64:67], v[60:63]
	v_mfma_f32_16x16x32_bf16 v[52:55], v[128:131], v[80:83], v[52:55]
	v_mfma_f32_16x16x32_bf16 v[44:47], v[128:131], v[170:173], v[44:47]
	v_mfma_f32_16x16x32_bf16 v[36:39], v[128:131], v[178:181], v[36:39]
	v_mfma_f32_16x16x32_bf16 v[60:63], v[132:135], v[72:75], v[60:63]
	v_mfma_f32_16x16x32_bf16 v[56:59], v[142:145], v[64:67], v[56:59]
	v_mfma_f32_16x16x32_bf16 v[52:55], v[132:135], v[88:91], v[52:55]
	v_mfma_f32_16x16x32_bf16 v[48:51], v[142:145], v[80:83], v[48:51]
	v_mfma_f32_16x16x32_bf16 v[44:47], v[132:135], v[174:177], v[44:47]
	v_mfma_f32_16x16x32_bf16 v[40:43], v[142:145], v[170:173], v[40:43]
	v_mfma_f32_16x16x32_bf16 v[36:39], v[132:135], v[182:185], v[36:39]
	v_mfma_f32_16x16x32_bf16 v[32:35], v[142:145], v[178:181], v[32:35]
	v_mfma_f32_16x16x32_bf16 v[202:205], v[150:153], v[72:75], v[56:59]
	v_mfma_f32_16x16x32_bf16 v[206:209], v[150:153], v[88:91], v[48:51]
	v_mfma_f32_16x16x32_bf16 v[224:227], v[150:153], v[174:177], v[40:43]
	v_mfma_f32_16x16x32_bf16 v[128:131], v[150:153], v[182:185], v[32:35]
	s_setprio 0
	s_setprio 1
	v_mfma_f32_16x16x32_bf16 v[28:31], v[96:99], v[64:67], v[28:31]
	v_mfma_f32_16x16x32_bf16 v[20:23], v[96:99], v[80:83], v[20:23]
	v_mfma_f32_16x16x32_bf16 v[12:15], v[96:99], v[170:173], v[12:15]
	v_mfma_f32_16x16x32_bf16 v[4:7], v[96:99], v[178:181], v[4:7]
	v_mfma_f32_16x16x32_bf16 v[28:31], v[104:107], v[72:75], v[28:31]
	v_mfma_f32_16x16x32_bf16 v[24:27], v[112:115], v[64:67], v[24:27]
	v_mfma_f32_16x16x32_bf16 v[20:23], v[104:107], v[88:91], v[20:23]
	v_mfma_f32_16x16x32_bf16 v[16:19], v[112:115], v[80:83], v[16:19]
	v_mfma_f32_16x16x32_bf16 v[12:15], v[104:107], v[174:177], v[12:15]
	v_mfma_f32_16x16x32_bf16 v[8:11], v[112:115], v[170:173], v[8:11]
	v_mfma_f32_16x16x32_bf16 v[4:7], v[104:107], v[182:185], v[4:7]
	v_mfma_f32_16x16x32_bf16 v[0:3], v[112:115], v[178:181], v[0:3]
	v_mfma_f32_16x16x32_bf16 v[132:135], v[120:123], v[72:75], v[24:27]
	v_mfma_f32_16x16x32_bf16 v[142:145], v[120:123], v[88:91], v[16:19]
	v_mfma_f32_16x16x32_bf16 v[150:153], v[120:123], v[174:177], v[8:11]
	v_mfma_f32_16x16x32_bf16 v[170:173], v[120:123], v[182:185], v[0:3]
	s_setprio 0
	s_barrier
	s_nop 1
	ds_read_b128 v[0:3], v140 offset:32768
	ds_read_b128 v[8:11], v140 offset:33792
	ds_read_b128 v[16:19], v140 offset:34816
	ds_read_b128 v[24:27], v140 offset:35840
	ds_read_b128 v[32:35], v139 offset:32768
	ds_read_b128 v[40:43], v139 offset:33792
	ds_read_b128 v[48:51], v139 offset:34816
	ds_read_b128 v[56:59], v139 offset:35840
	ds_read_b128 v[64:67], v139 offset:36864
	ds_read_b128 v[174:177], v139 offset:37888
	ds_read_b128 v[178:181], v139 offset:38912
	ds_read_b128 v[182:185], v139 offset:39936
	s_waitcnt vmcnt(2)
	s_barrier
; #define WAIT_V(n) asm volatile("s_waitcnt vmcnt(" #n ")" ::: "memory")
; #define WAIT_L(n) asm volatile("s_waitcnt lgkmcnt(" #n ")" ::: "memory")
; #define BAR __builtin_amdgcn_s_barrier()
; #define LDA(dst, b, h) _Pragma("unroll") for (int m = 0; m < 4; ++m) _Pragma("unroll") for (int k = 0; k < 2; ++k) \
;     dst[m][k] = *reinterpret_cast<const bf16x8*>((char*)shm + abase + (((b) * 2 + (h)) * 16384 + (m * 2 + k) * 1024))
; #define LDB(dst, b, h) _Pragma("unroll") for (int n = 0; n < 2; ++n) _Pragma("unroll") for (int k = 0; k < 2; ++k) \
;     dst[n][k] = *reinterpret_cast<const bf16x8*>((char*)shm + bbase + (((b) * 2 + (h)) * 16384 + (n * 2 + k) * 1024))
; template <bool SWAP>
; __device__ __forceinline__ void gemm_main(const u16* __restrict__ A, const u16* __restrict__ Bt, int brow, int bcol,
;                                           u16* shm, f32x4 (&acc)[2][2][4][2]) {
;     ...
;   { LDB(B0, 1, 0); LDA(At, 1, 0); WAIT_V(2); BAR; WAIT_L(0); MMA(0, 0, At, B0); BAR;
;     LDB(B1, 1, 1); WAIT_V(0); BAR; WAIT_L(0); MMA(0, 1, At, B1); BAR;
;     LDA(At, 1, 1); BAR; WAIT_L(0); MMA(1, 0, At, B0); MMA(1, 1, At, B1); BAR; }
;   if (wr == 0) BAR;
	s_waitcnt lgkmcnt(0)
	s_setprio 1
	s_waitcnt lgkmcnt(0)
	v_mfma_f32_16x16x32_bf16 v[72:75], v[0:3], v[32:35], v[124:127]
	v_mfma_f32_16x16x32_bf16 v[120:123], v[8:11], v[40:43], v[72:75]
	v_mfma_f32_16x16x32_bf16 v[72:75], v[16:19], v[32:35], v[146:149]
	v_mfma_f32_16x16x32_bf16 v[124:127], v[24:27], v[40:43], v[72:75]
	v_mfma_f32_16x16x32_bf16 v[72:75], v[0:3], v[48:51], v[116:119]
	v_mfma_f32_16x16x32_bf16 v[112:115], v[8:11], v[56:59], v[72:75]
	v_mfma_f32_16x16x32_bf16 v[72:75], v[16:19], v[48:51], v[186:189]
	v_mfma_f32_16x16x32_bf16 v[116:119], v[24:27], v[56:59], v[72:75]
	v_mfma_f32_16x16x32_bf16 v[72:75], v[0:3], v[64:67], v[108:111]
	v_mfma_f32_16x16x32_bf16 v[104:107], v[8:11], v[174:177], v[72:75]
	v_mfma_f32_16x16x32_bf16 v[72:75], v[16:19], v[64:67], v[194:197]
	v_mfma_f32_16x16x32_bf16 v[108:111], v[24:27], v[174:177], v[72:75]
	v_mfma_f32_16x16x32_bf16 v[72:75], v[0:3], v[178:181], v[100:103]
	v_mfma_f32_16x16x32_bf16 v[96:99], v[8:11], v[182:185], v[72:75]
	v_mfma_f32_16x16x32_bf16 v[72:75], v[16:19], v[178:181], v[198:201]
	v_mfma_f32_16x16x32_bf16 v[100:103], v[24:27], v[182:185], v[72:75]
	s_setprio 0
	s_barrier
	ds_read_b128 v[146:149], v140 offset:49152
	ds_read_b128 v[186:189], v140 offset:50176
	ds_read_b128 v[194:197], v140 offset:51200
	ds_read_b128 v[198:201], v140 offset:52224
	s_waitcnt vmcnt(0)
	s_barrier
	s_waitcnt lgkmcnt(0)
	s_setprio 1
	s_waitcnt lgkmcnt(0)
	v_mfma_f32_16x16x32_bf16 v[72:75], v[146:149], v[32:35], v[92:95]
	v_mfma_f32_16x16x32_bf16 v[32:35], v[194:197], v[32:35], v[154:157]
	v_mfma_f32_16x16x32_bf16 v[92:95], v[198:201], v[40:43], v[32:35]
	v_mfma_f32_16x16x32_bf16 v[32:35], v[146:149], v[48:51], v[84:87]
	v_mfma_f32_16x16x32_bf16 v[80:83], v[186:189], v[56:59], v[32:35]
	v_mfma_f32_16x16x32_bf16 v[32:35], v[194:197], v[48:51], v[158:161]
	v_mfma_f32_16x16x32_bf16 v[84:87], v[198:201], v[56:59], v[32:35]
	v_mfma_f32_16x16x32_bf16 v[32:35], v[146:149], v[64:67], v[76:79]
	v_mfma_f32_16x16x32_bf16 v[88:91], v[186:189], v[40:43], v[72:75]
	v_mfma_f32_16x16x32_bf16 v[72:75], v[186:189], v[174:177], v[32:35]
	v_mfma_f32_16x16x32_bf16 v[32:35], v[194:197], v[64:67], v[162:165]
	v_mfma_f32_16x16x32_bf16 v[76:79], v[198:201], v[174:177], v[32:35]
	v_mfma_f32_16x16x32_bf16 v[32:35], v[146:149], v[178:181], v[68:71]
	v_mfma_f32_16x16x32_bf16 v[64:67], v[186:189], v[182:185], v[32:35]
	v_mfma_f32_16x16x32_bf16 v[32:35], v[194:197], v[178:181], v[166:169]
	v_mfma_f32_16x16x32_bf16 v[68:71], v[198:201], v[182:185], v[32:35]
	s_setprio 0
	s_barrier
	ds_read_b128 v[154:157], v139 offset:49152
	ds_read_b128 v[158:161], v139 offset:50176
	ds_read_b128 v[162:165], v139 offset:51200
	ds_read_b128 v[166:169], v139 offset:52224
	ds_read_b128 v[174:177], v139 offset:53248
	ds_read_b128 v[178:181], v139 offset:54272
	ds_read_b128 v[182:185], v139 offset:55296
	ds_read_b128 v[228:231], v139 offset:56320
	s_barrier
	s_waitcnt lgkmcnt(0)
	s_setprio 1
	s_waitcnt lgkmcnt(0)
	v_mfma_f32_16x16x32_bf16 v[32:35], v[0:3], v[154:157], v[60:63]
	v_mfma_f32_16x16x32_bf16 v[56:59], v[8:11], v[158:161], v[32:35]
	v_mfma_f32_16x16x32_bf16 v[32:35], v[16:19], v[154:157], v[202:205]
	v_mfma_f32_16x16x32_bf16 v[60:63], v[24:27], v[158:161], v[32:35]
	v_mfma_f32_16x16x32_bf16 v[32:35], v[0:3], v[162:165], v[52:55]
	v_mfma_f32_16x16x32_bf16 v[48:51], v[8:11], v[166:169], v[32:35]
	v_mfma_f32_16x16x32_bf16 v[32:35], v[16:19], v[162:165], v[206:209]
	v_mfma_f32_16x16x32_bf16 v[52:55], v[24:27], v[166:169], v[32:35]
	v_mfma_f32_16x16x32_bf16 v[32:35], v[0:3], v[174:177], v[44:47]
	v_mfma_f32_16x16x32_bf16 v[40:43], v[8:11], v[178:181], v[32:35]
	v_mfma_f32_16x16x32_bf16 v[32:35], v[16:19], v[174:177], v[224:227]
	v_mfma_f32_16x16x32_bf16 v[0:3], v[0:3], v[182:185], v[36:39]
	v_mfma_f32_16x16x32_bf16 v[44:47], v[24:27], v[178:181], v[32:35]
	v_mfma_f32_16x16x32_bf16 v[32:35], v[8:11], v[228:231], v[0:3]
	v_mfma_f32_16x16x32_bf16 v[0:3], v[16:19], v[182:185], v[128:131]
	v_mfma_f32_16x16x32_bf16 v[36:39], v[24:27], v[228:231], v[0:3]
	s_setprio 0
	s_setprio 1
	v_mfma_f32_16x16x32_bf16 v[0:3], v[146:149], v[154:157], v[28:31]
	v_mfma_f32_16x16x32_bf16 v[24:27], v[186:189], v[158:161], v[0:3]
	v_mfma_f32_16x16x32_bf16 v[0:3], v[194:197], v[154:157], v[132:135]
	v_mfma_f32_16x16x32_bf16 v[28:31], v[198:201], v[158:161], v[0:3]
	v_mfma_f32_16x16x32_bf16 v[0:3], v[146:149], v[162:165], v[20:23]
	v_mfma_f32_16x16x32_bf16 v[16:19], v[186:189], v[166:169], v[0:3]
	v_mfma_f32_16x16x32_bf16 v[0:3], v[194:197], v[162:165], v[142:145]
	v_mfma_f32_16x16x32_bf16 v[20:23], v[198:201], v[166:169], v[0:3]
	v_mfma_f32_16x16x32_bf16 v[0:3], v[146:149], v[174:177], v[12:15]
	v_mfma_f32_16x16x32_bf16 v[8:11], v[186:189], v[178:181], v[0:3]
	v_mfma_f32_16x16x32_bf16 v[0:3], v[194:197], v[174:177], v[150:153]
	v_mfma_f32_16x16x32_bf16 v[12:15], v[198:201], v[178:181], v[0:3]
	v_mfma_f32_16x16x32_bf16 v[0:3], v[146:149], v[182:185], v[4:7]
	v_mfma_f32_16x16x32_bf16 v[4:7], v[194:197], v[182:185], v[170:173]
	v_mfma_f32_16x16x32_bf16 v[0:3], v[186:189], v[228:231], v[0:3]
	v_mfma_f32_16x16x32_bf16 v[4:7], v[198:201], v[228:231], v[4:7]
	s_setprio 0
	s_movk_i32 s4, 0x100
	v_cmp_gt_u32_e32 vcc, s4, v138
	s_barrier
	s_and_saveexec_b64 s[4:5], vcc
	s_cbranch_execz .LBB0_630
	s_barrier
